# GEMM mainloops: one static s_setprio 1 for the wave half that runs one barrier behind, per-segment setprio flips removed, priority reset at the phase-loop edge
# speedup vs baseline: 1.0117x; 1.0044x over previous
; __device__ __forceinline__ CPar params_ptr() { CPar q = (CPar)__builtin_amdgcn_kernarg_segment_ptr(); asm volatile("" : "+s"(q)); return q; }
; __global__ __launch_bounds__(512, 2) void mega(Params pk) {
;     ...
;     for (int ph = ph_lo; ph < ph_hi; ++ph) {
;         if (ph == ph_lo + 1) grid.sync();
;         else if (ph > ph_lo + 1) xcd_barrier(xb);
;         CPar p = params_ptr();
;         unsigned char* ws = p->ws;
;         bf16_t *HB = (bf16_t*)(ws + WS_HB), *Z = (bf16_t*)(ws + WS_Z), *XBC = (bf16_t*)(ws + WS_XBC), *U = (bf16_t*)(ws + WS_U), *Q = (bf16_t*)(ws + WS_Q), *G = (bf16_t*)(ws + WS_G);
;         float *DT = (float*)(ws + WS_DT), *XM = (float*)(ws + WS_XMETA);
;         const int l = ph >> 3, sub = ph & 7;
.LBB0_8:
	s_setprio 0
	v_readlane_b32 s12, v255, 44
	v_readlane_b32 s14, v255, 46
	v_readlane_b32 s15, v255, 47
	s_add_i32 s14, s14, 1
	s_cmp_ge_i32 s14, s15
	v_readlane_b32 s13, v255, 45
	s_cbranch_scc1 .LBB0_1072

; __device__ __forceinline__ int lbid() { int t = blockIdx.x; asm volatile("" : "+s"(t)); return t; }
; __device__ __forceinline__ int lgdim() { int t = gridDim.x; asm volatile("" : "+s"(t)); return t; }
; #define PG8_STAGE(bufoff, gbase, voff) do { _Pragma("unroll") for (int _i = 0; _i < 2; ++_i) \
;         __builtin_amdgcn_global_load_lds((const unsigned*)((const char*)(gbase) + (voff)[_i]), (LAS unsigned*)(lds + (bufoff) + ldsw + _i * 8192), 16, 0, 0); } while (0)
; #define PG8_WAIT_V(n) asm volatile("s_waitcnt vmcnt(" #n ")" ::: "memory")
; #define PG8_BAR __builtin_amdgcn_s_barrier()
; template <class Epi>
; __device__ __forceinline__ void gemm_phase(LAS unsigned char* lds, const Gemm g, const StaticOrder& S, const Epi& E) {
;     ...
;     const char* cA = (const char*)g.A + (size_t)cur.pm * tstepA; const char* cB = (const char*)g.Bt + (size_t)cur.pn * tstepB;
;     PG8_STAGE(PG8_SB(0, 0), cB, voffB); PG8_STAGE(PG8_SA(0, 0), cA, voffA); PG8_STAGE(PG8_SB(0, 1), cB + hstepB, voffB); PG8_STAGE(PG8_SA(0, 1), cA + hstepA, voffA);
;     if (wr == 1) PG8_BAR;
;     PG8_WAIT_V(4); PG8_BAR;
;     PG8_STAGE(PG8_SB(1, 0), cB + kstep, voffB); PG8_STAGE(PG8_SA(1, 0), cA + kstep, voffA); PG8_STAGE(PG8_SB(1, 1), cB + hstepB + kstep, voffB);
;     PG8_WAIT_V(6); PG8_BAR;
; __global__ __launch_bounds__(512, 2) void mega(Params pk) {
;     ...
;             S.init(NROWS, 1024, lgdim(), lbid());
;             EpiRes E{p->out, XM, nullptr, nullptr, nullptr, nullptr, nullptr};
;             pg8::gemm_phase(lds, pg8::Gemm{(const bf16_t*)(ws + WS_ACT), (const bf16_t*)(ws + W_DOWN), NROWS, 1024, 4096, 4096, 4096}, S, E);
.LBB0_78:
	v_readlane_b32 s0, v254, 1
	v_readlane_b32 s1, v254, 2
	s_waitcnt lgkmcnt(0)
	s_mov_b64 s[18:19], -1
	v_writelane_b32 v255, s0, 30
	s_nop 1
	v_writelane_b32 v255, s1, 31
	s_load_dwordx2 s[0:1], s[0:1], 0x118
	s_waitcnt lgkmcnt(0)
	s_add_u32 s2, s0, 0x2801000
	s_addc_u32 s3, s1, 0
	s_add_u32 s6, s0, 0xab01000
	s_addc_u32 s7, s1, 0
	v_writelane_b32 v255, s6, 32
	s_nop 1
	v_writelane_b32 v255, s7, 33
	s_add_u32 s6, s0, 0x12e01000
	s_addc_u32 s7, s1, 0
	v_writelane_b32 v255, s6, 34
	s_nop 1
	v_writelane_b32 v255, s7, 35
	s_add_u32 s6, s0, 0x21341000
	s_addc_u32 s7, s1, 0
	v_writelane_b32 v255, s6, 36
	s_nop 1
	v_writelane_b32 v255, s7, 37
	s_add_u32 s6, s0, 0x254c1000
	v_writelane_b32 v255, s0, 38
	s_addc_u32 s7, s1, 0
	s_nop 0
	v_writelane_b32 v255, s1, 39
	v_writelane_b32 v255, s6, 40
	s_ashr_i32 s0, s14, 3
	s_nop 0
	v_writelane_b32 v255, s7, 41
	v_writelane_b32 v255, s0, 42
	s_mov_b64 s[6:7], s[14:15]
	s_nop 0
	v_writelane_b32 v255, s1, 43
	v_writelane_b32 v255, s4, 44
	s_and_b32 s0, s14, 7
	s_cmp_lt_i32 s0, 4
	v_writelane_b32 v255, s5, 45
	v_writelane_b32 v255, s6, 46
	v_writelane_b32 v255, s7, 47
	v_writelane_b32 v255, s0, 48
	s_cbranch_scc1 .LBB0_224
	v_readlane_b32 s0, v255, 48
	s_cmp_lt_i32 s0, 6
	s_cbranch_scc1 .LBB0_108
	v_readlane_b32 s0, v255, 48
	s_cmp_gt_i32 s0, 6
	s_cbranch_scc0 .LBB0_94
	s_mov_b32 s0, s68
	v_readlane_b32 s1, v254, 0
	s_waitcnt vmcnt(0)
	v_mov_b32_e32 v16, v200
	s_cmpk_gt_i32 s1, 0x417
	v_readfirstlane_b32 s8, v16
	s_cbranch_scc1 .LBB0_93
	v_lshlrev_b32_e32 v1, 4, v16
	v_add_u32_e32 v2, 0x2000, v1
	v_ashrrev_i32_e32 v3, 31, v2
	v_lshrrev_b32_e32 v3, 22, v3
	v_add_u32_e32 v3, v2, v3
	v_ashrrev_i32_e32 v10, 10, v3
	v_mul_i32_i24_e32 v4, 0x400, v10
	v_sub_u32_e32 v2, v2, v4
	v_readlane_b32 s18, v255, 30
	v_lshrrev_b32_e32 v4, 4, v2
	v_readlane_b32 s19, v255, 31
	v_bitop3_b32 v2, v4, v2, 32 bitop3:0x6c
	s_load_dwordx2 s[6:7], s[18:19], 0x118
	v_ashrrev_i32_e32 v4, 31, v2
	v_lshrrev_b32_e32 v4, 26, v4
	v_add_u32_e32 v4, v2, v4
	v_ashrrev_i32_e32 v11, 6, v4
	v_and_b32_e32 v4, 0xc0, v4
	v_sub_u32_e32 v2, v2, v4
	s_waitcnt lgkmcnt(0)
	s_add_u32 s9, s6, 0x1e00000
	v_lshlrev_b32_e32 v3, 5, v10
	v_ashrrev_i16_sdwa v2, v201, sext(v2) dst_sel:DWORD dst_unused:UNUSED_PAD src0_sel:DWORD src1_sel:BYTE_0
	s_addc_u32 s10, s7, 0
	v_and_b32_e32 v3, 32, v3
	v_bfe_i32 v12, v2, 0, 16
	s_ashr_i32 s12, s1, 31
	v_add_u32_e32 v2, v3, v12
	v_lshlrev_b32_e32 v3, 3, v10
	s_lshr_b32 s6, s12, 29
	v_and_b32_e32 v3, 0x7fff0, v3
	s_add_i32 s6, s1, s6
	s_ashr_i32 s17, s8, 6
	v_add_lshl_u32 v3, v11, v3, 13
	s_ashr_i32 s7, s6, 3
	s_and_b32 s6, s6, -8
	s_ashr_i32 s21, s8, 8
	s_lshl_b32 s11, s17, 10
	v_lshl_add_u32 v130, v2, 1, v3
	v_bfe_i32 v3, v16, 27, 1
	s_sub_i32 s6, s1, s6
	v_lshrrev_b32_e32 v3, 22, v3
	s_cmp_lt_i32 s6, 0
	v_add_u32_e32 v3, v1, v3
	s_cselect_b32 s13, s69, 0x83
	v_and_b32_e32 v3, 0xfffffc00, v3
	s_mul_i32 s6, s6, s13
	v_sub_u32_e32 v1, v1, v3
	s_add_i32 s6, s6, s7
	v_lshrrev_b32_e32 v3, 4, v1
	s_ashr_i32 s7, s6, 31
	v_bitop3_b32 v3, v3, v1, 32 bitop3:0x6c
	v_ashrrev_i32_e32 v1, 31, v1
	s_lshr_b32 s7, s7, 27
	v_lshrrev_b32_e32 v1, 26, v1
	s_add_i32 s7, s6, s7
	v_ashrrev_i32_e32 v2, 31, v16
	v_add_u32_e32 v1, v3, v1
	s_ashr_i32 s13, s7, 5
	v_lshrrev_b32_e32 v2, 26, v2
	v_ashrrev_i32_e32 v14, 6, v1
	s_lshl_b32 s13, s13, 3
	v_add_u32_e32 v2, v16, v2
	v_mul_i32_i24_e32 v1, 64, v14
	s_sub_i32 s14, 0x106, s13
	v_ashrrev_i32_e32 v13, 6, v2
	v_sub_u32_e32 v1, v3, v1
	s_min_u32 s14, s14, 8
	s_andn2_b32 s7, s7, 31
	v_lshlrev_b32_e32 v2, 5, v13
	v_ashrrev_i16_sdwa v1, v201, sext(v1) dst_sel:DWORD dst_unused:UNUSED_PAD src0_sel:DWORD src1_sel:BYTE_0
	s_sub_i32 s15, s6, s7
	v_cvt_f32_ubyte0_e32 v4, s14
	v_and_b32_e32 v2, 32, v2
	v_bfe_i32 v15, v1, 0, 16
	v_cvt_f32_i32_e32 v3, s15
	v_rcp_iflag_f32_e32 v5, v4
	v_add_u32_e32 v1, v2, v15
	v_lshlrev_b32_e32 v2, 3, v13
	v_and_b32_e32 v2, 0x7fff0, v2
	v_add_lshl_u32 v2, v14, v2, 13
	v_lshl_add_u32 v132, v1, 1, v2
	v_mul_f32_e32 v1, v3, v5
	v_trunc_f32_e32 v1, v1
	v_fma_f32 v2, -v1, v4, v3
	v_cvt_i32_f32_e32 v1, v1
	s_ashr_i32 s6, s15, 30
	s_or_b32 s16, s6, 1
	v_cmp_ge_f32_e64 s[6:7], |v2|, v4
	s_and_b64 s[6:7], s[6:7], exec
	s_cselect_b32 s6, s16, 0
	v_readfirstlane_b32 s7, v1
	s_add_i32 s20, s7, s6
	s_mul_i32 s6, s20, s14
	s_sub_i32 s6, s15, s6
	s_sext_i32_i8 s6, s6
	s_add_i32 s30, s13, s6
	s_ashr_i32 s31, s30, 31
	s_bfe_i64 s[14:15], s[20:21], 0x80000
	s_lshl_b64 s[6:7], s[30:31], 21
	s_lshl_b64 s[14:15], s[14:15], 21
	s_add_u32 s36, s9, s14
	s_addc_u32 s37, s10, s15
	s_add_i32 s13, s11, 0
	s_add_i32 m0, s13, 0x10000
	v_readlane_b32 s14, v255, 32
	global_load_lds_dwordx4 v132, s[36:37]
	s_add_i32 m0, s13, 0x12000
	v_readlane_b32 s15, v255, 33
	s_add_u32 s34, s14, s6
	global_load_lds_dwordx4 v130, s[36:37]
	s_addc_u32 s35, s15, s7
	s_mov_b32 m0, s13
	s_add_i32 s14, s13, 0x2000
	global_load_lds_dwordx4 v132, s[34:35]
	s_mov_b32 m0, s14
	s_add_u32 s6, s36, 0x100000
	global_load_lds_dwordx4 v130, s[34:35]
	s_addc_u32 s7, s37, 0
	s_add_i32 m0, s13, 0x14000
	s_load_dwordx2 s[18:19], s[18:19], 0x110
	global_load_lds_dwordx4 v132, s[6:7]
	s_add_i32 m0, s13, 0x16000
	v_mov_b32_e32 v133, v0
	global_load_lds_dwordx4 v130, s[6:7]
	s_add_u32 s6, s34, 0x100000
	s_addc_u32 s7, s35, 0
	s_add_i32 s15, s13, 0x4000
	s_mov_b32 m0, s15
	s_add_i32 s16, s13, 0x6000
	global_load_lds_dwordx4 v132, s[6:7]
	s_mov_b32 m0, s16
	v_mov_b32_e32 v131, v0
	global_load_lds_dwordx4 v130, s[6:7]
	v_lshl_add_u64 v[8:9], s[36:37], 0, v[132:133]
	v_lshl_add_u64 v[6:7], s[36:37], 0, v[130:131]
	v_lshl_add_u64 v[4:5], s[34:35], 0, v[132:133]
	s_cmp_lg_u32 s21, 1
	v_lshl_add_u64 v[2:3], s[34:35], 0, v[130:131]
	s_cbranch_scc1 .LBB0_84
	s_barrier
	s_setprio 1

; #define PG8_STAGE(bufoff, gbase, voff) do { _Pragma("unroll") for (int _i = 0; _i < 2; ++_i) \
;         __builtin_amdgcn_global_load_lds((const unsigned*)((const char*)(gbase) + (voff)[_i]), (LAS unsigned*)(lds + (bufoff) + ldsw + _i * 8192), 16, 0, 0); } while (0)
; #define PG8_LDA(dst, b, h) do { _Pragma("unroll") for (int m = 0; m < 4; ++m) _Pragma("unroll") for (int k = 0; k < 2; ++k) dst[m][k] = *(const LAS bf16x8*)(lds + PG8_SA(b, h) + aoff + m * 2048 + k * 1024); } while (0)
; #define PG8_LDB(dst, b, h) do { _Pragma("unroll") for (int n = 0; n < 2; ++n) _Pragma("unroll") for (int k = 0; k < 2; ++k) dst[n][k] = *(const LAS bf16x8*)(lds + PG8_SB(b, h) + boff + n * 2048 + k * 1024); } while (0)
; #define PG8_MMA(ai, bj, At, Bt) do { __builtin_amdgcn_s_setprio(1); _Pragma("unroll") for (int m = 0; m < 4; ++m) _Pragma("unroll") for (int n = 0; n < 2; ++n) _Pragma("unroll") for (int k = 0; k < 2; ++k) \
;         acc[ai][bj][m][n] = __builtin_amdgcn_mfma_f32_16x16x32_bf16(Bt[n][k], At[m][k], acc[ai][bj][m][n], 0, 0, 0); __builtin_amdgcn_s_setprio(0); } while (0)
; #define PG8_WAIT_V(n) asm volatile("s_waitcnt vmcnt(" #n ")" ::: "memory")
; #define PG8_WAIT_L(n) asm volatile("s_waitcnt lgkmcnt(" #n ")" ::: "memory")
; #define PG8_BAR __builtin_amdgcn_s_barrier()
; #define PG8_SCHED __builtin_amdgcn_sched_barrier(0)
; template <class Epi>
; __device__ __forceinline__ void gemm_phase(LAS unsigned char* lds, const Gemm g, const StaticOrder& S, const Epi& E) {
;     ...
;             PG8_LDB(B0, 0, 0); PG8_SCHED; PG8_LDA(At, 0, 0); PG8_STAGE(PG8_SA(1, 1), a1 + hstepA, voffA);
;             PG8_WAIT_L(8); PG8_BAR; PG8_WAIT_L(0); PG8_MMA(0, 0, At, B0); PG8_BAR; PG8_SCHED;
;             PG8_LDB(B1, 0, 1); PG8_STAGE(PG8_SB(0, 0), b2, voffB);
;             PG8_BAR; PG8_WAIT_L(0); PG8_MMA(0, 1, At, B1); PG8_BAR;
;             PG8_LDA(At, 0, 1); PG8_STAGE(PG8_SA(0, 0), a2, voffA);
;             PG8_BAR; PG8_WAIT_L(0); PG8_MMA(1, 0, At, B0); PG8_BAR; PG8_SCHED;
;             PG8_STAGE(PG8_SB(0, 1), b2 + hstepB, voffB);
;             PG8_WAIT_V(6); PG8_BAR; PG8_MMA(1, 1, At, B1); PG8_BAR;
.LBB0_88:
	s_add_u32 s6, s34, 0xfff00080
	s_addc_u32 s7, s35, -1
	s_add_i32 s53, 0, 0x10000
	v_add_u32_e32 v142, s53, v144
	ds_read_b128 v[138:141], v142
	ds_read_b128 v[148:151], v142 offset:1024
	ds_read_b128 v[152:155], v142 offset:2048
	ds_read_b128 v[176:179], v142 offset:3072
	s_cmp_eq_u32 s52, 60
	s_cselect_b32 s43, s25, s7
	s_cselect_b32 s42, s48, s6
	s_cselect_b32 s37, s21, s51
	s_cselect_b32 s36, s49, s50
	v_lshl_add_u64 v[142:143], s[34:35], 0, v[134:135]
	s_add_i32 m0, s13, 0xc000
	ds_read_b128 v[180:183], v146
	ds_read_b128 v[184:187], v146 offset:1024
	ds_read_b128 v[188:191], v146 offset:2048
	ds_read_b128 v[192:195], v146 offset:3072
	ds_read_b128 v[196:199], v146 offset:4096
	ds_read_b128 v[216:219], v146 offset:5120
	ds_read_b128 v[220:223], v146 offset:6144
	ds_read_b128 v[224:227], v146 offset:7168
	global_load_lds_dwordx4 v[142:143], off
	v_lshl_add_u64 v[142:143], s[34:35], 0, v[136:137]
	s_add_i32 m0, s13, 0xe000
	s_nop 0
	global_load_lds_dwordx4 v[142:143], off
	s_waitcnt lgkmcnt(8)
	s_barrier
	s_waitcnt lgkmcnt(0)
	s_waitcnt lgkmcnt(0)
	v_mfma_f32_16x16x32_bf16 v[126:129], v[138:141], v[180:183], v[126:129]
	v_mfma_f32_16x16x32_bf16 v[122:125], v[152:155], v[180:183], v[122:125]
	v_mfma_f32_16x16x32_bf16 v[118:121], v[138:141], v[188:191], v[118:121]
	v_mfma_f32_16x16x32_bf16 v[114:117], v[152:155], v[188:191], v[114:117]
	v_mfma_f32_16x16x32_bf16 v[94:97], v[138:141], v[196:199], v[94:97]
	v_mfma_f32_16x16x32_bf16 v[90:93], v[152:155], v[196:199], v[90:93]
	v_mfma_f32_16x16x32_bf16 v[86:89], v[138:141], v[220:223], v[86:89]
	v_mfma_f32_16x16x32_bf16 v[82:85], v[152:155], v[220:223], v[82:85]
	v_mfma_f32_16x16x32_bf16 v[126:129], v[148:151], v[184:187], v[126:129]
	v_mfma_f32_16x16x32_bf16 v[122:125], v[176:179], v[184:187], v[122:125]
	v_mfma_f32_16x16x32_bf16 v[118:121], v[148:151], v[192:195], v[118:121]
	v_mfma_f32_16x16x32_bf16 v[114:117], v[176:179], v[192:195], v[114:117]
	v_mfma_f32_16x16x32_bf16 v[94:97], v[148:151], v[216:219], v[94:97]
	v_mfma_f32_16x16x32_bf16 v[90:93], v[176:179], v[216:219], v[90:93]
	v_mfma_f32_16x16x32_bf16 v[86:89], v[148:151], v[224:227], v[86:89]
	v_mfma_f32_16x16x32_bf16 v[82:85], v[176:179], v[224:227], v[82:85]
	s_barrier
	s_add_i32 s54, 0, 0x14000
	v_add_u32_e32 v142, s54, v144
	s_add_i32 s6, s53, s11
	ds_read_b128 v[228:231], v142
	ds_read_b128 v[232:235], v142 offset:1024
	ds_read_b128 v[236:239], v142 offset:2048
	ds_read_b128 v[240:243], v142 offset:3072
	v_lshl_add_u64 v[142:143], s[36:37], 0, v[132:133]
	s_mov_b32 m0, s6
	v_lshl_add_u64 v[212:213], s[36:37], 0, v[130:131]
	global_load_lds_dwordx4 v[142:143], off
	s_add_i32 m0, s6, 0x2000
	s_nop 0
	global_load_lds_dwordx4 v[212:213], off
	s_barrier
	s_waitcnt lgkmcnt(0)
	s_waitcnt lgkmcnt(0)
	v_mfma_f32_16x16x32_bf16 v[110:113], v[228:231], v[180:183], v[110:113]
	v_mfma_f32_16x16x32_bf16 v[106:109], v[236:239], v[180:183], v[106:109]
	v_mfma_f32_16x16x32_bf16 v[102:105], v[228:231], v[188:191], v[102:105]
	v_mfma_f32_16x16x32_bf16 v[98:101], v[236:239], v[188:191], v[98:101]
	v_mfma_f32_16x16x32_bf16 v[78:81], v[228:231], v[196:199], v[78:81]
	v_mfma_f32_16x16x32_bf16 v[74:77], v[236:239], v[196:199], v[74:77]
	v_mfma_f32_16x16x32_bf16 v[70:73], v[228:231], v[220:223], v[70:73]
	v_mfma_f32_16x16x32_bf16 v[66:69], v[236:239], v[220:223], v[66:69]
	v_mfma_f32_16x16x32_bf16 v[110:113], v[232:235], v[184:187], v[110:113]
	v_mfma_f32_16x16x32_bf16 v[106:109], v[240:243], v[184:187], v[106:109]
	v_mfma_f32_16x16x32_bf16 v[102:105], v[232:235], v[192:195], v[102:105]
	v_mfma_f32_16x16x32_bf16 v[98:101], v[240:243], v[192:195], v[98:101]
	v_mfma_f32_16x16x32_bf16 v[78:81], v[232:235], v[216:219], v[78:81]
	v_mfma_f32_16x16x32_bf16 v[74:77], v[240:243], v[216:219], v[74:77]
	v_mfma_f32_16x16x32_bf16 v[70:73], v[232:235], v[224:227], v[70:73]
	v_mfma_f32_16x16x32_bf16 v[66:69], v[240:243], v[224:227], v[66:69]
	s_mov_b32 m0, s13
	v_lshl_add_u64 v[244:245], s[42:43], 0, v[132:133]
	s_barrier
	ds_read_b128 v[180:183], v146 offset:16384
	ds_read_b128 v[184:187], v146 offset:17408
	ds_read_b128 v[188:191], v146 offset:18432
	ds_read_b128 v[192:195], v146 offset:19456
	ds_read_b128 v[196:199], v146 offset:20480
	ds_read_b128 v[216:219], v146 offset:21504
	ds_read_b128 v[220:223], v146 offset:22528
	ds_read_b128 v[224:227], v146 offset:23552
	global_load_lds_dwordx4 v[244:245], off
	v_lshl_add_u64 v[246:247], s[42:43], 0, v[130:131]
	s_mov_b32 m0, s14
	s_nop 0
	global_load_lds_dwordx4 v[246:247], off
	s_barrier
	s_waitcnt lgkmcnt(0)
	s_waitcnt lgkmcnt(0)
	v_mfma_f32_16x16x32_bf16 v[62:65], v[138:141], v[180:183], v[62:65]
	v_mfma_f32_16x16x32_bf16 v[58:61], v[152:155], v[180:183], v[58:61]
	v_mfma_f32_16x16x32_bf16 v[54:57], v[138:141], v[188:191], v[54:57]
	v_mfma_f32_16x16x32_bf16 v[50:53], v[152:155], v[188:191], v[50:53]
	v_mfma_f32_16x16x32_bf16 v[30:33], v[138:141], v[196:199], v[30:33]
	v_mfma_f32_16x16x32_bf16 v[26:29], v[152:155], v[196:199], v[26:29]
	v_mfma_f32_16x16x32_bf16 v[22:25], v[138:141], v[220:223], v[22:25]
	v_mfma_f32_16x16x32_bf16 v[14:17], v[152:155], v[220:223], v[14:17]
	v_mfma_f32_16x16x32_bf16 v[62:65], v[148:151], v[184:187], v[62:65]
	v_mfma_f32_16x16x32_bf16 v[58:61], v[176:179], v[184:187], v[58:61]
	v_mfma_f32_16x16x32_bf16 v[54:57], v[148:151], v[192:195], v[54:57]
	v_mfma_f32_16x16x32_bf16 v[50:53], v[176:179], v[192:195], v[50:53]
	v_mfma_f32_16x16x32_bf16 v[30:33], v[148:151], v[216:219], v[30:33]
	v_mfma_f32_16x16x32_bf16 v[26:29], v[176:179], v[216:219], v[26:29]
	v_mfma_f32_16x16x32_bf16 v[22:25], v[148:151], v[224:227], v[22:25]
	v_mfma_f32_16x16x32_bf16 v[14:17], v[176:179], v[224:227], v[14:17]
	s_barrier
; #define PG8_STAGE(bufoff, gbase, voff) do { _Pragma("unroll") for (int _i = 0; _i < 2; ++_i) \
;         __builtin_amdgcn_global_load_lds((const unsigned*)((const char*)(gbase) + (voff)[_i]), (LAS unsigned*)(lds + (bufoff) + ldsw + _i * 8192), 16, 0, 0); } while (0)
; #define PG8_LDA(dst, b, h) do { _Pragma("unroll") for (int m = 0; m < 4; ++m) _Pragma("unroll") for (int k = 0; k < 2; ++k) dst[m][k] = *(const LAS bf16x8*)(lds + PG8_SA(b, h) + aoff + m * 2048 + k * 1024); } while (0)
; #define PG8_LDB(dst, b, h) do { _Pragma("unroll") for (int n = 0; n < 2; ++n) _Pragma("unroll") for (int k = 0; k < 2; ++k) dst[n][k] = *(const LAS bf16x8*)(lds + PG8_SB(b, h) + boff + n * 2048 + k * 1024); } while (0)
; #define PG8_MMA(ai, bj, At, Bt) do { __builtin_amdgcn_s_setprio(1); _Pragma("unroll") for (int m = 0; m < 4; ++m) _Pragma("unroll") for (int n = 0; n < 2; ++n) _Pragma("unroll") for (int k = 0; k < 2; ++k) \
;         acc[ai][bj][m][n] = __builtin_amdgcn_mfma_f32_16x16x32_bf16(Bt[n][k], At[m][k], acc[ai][bj][m][n], 0, 0, 0); __builtin_amdgcn_s_setprio(0); } while (0)
; #define PG8_WAIT_V(n) asm volatile("s_waitcnt vmcnt(" #n ")" ::: "memory")
; #define PG8_WAIT_L(n) asm volatile("s_waitcnt lgkmcnt(" #n ")" ::: "memory")
; #define PG8_BAR __builtin_amdgcn_s_barrier()
; #define PG8_SCHED __builtin_amdgcn_sched_barrier(0)
; template <class Epi>
; __device__ __forceinline__ void gemm_phase(LAS unsigned char* lds, const Gemm g, const StaticOrder& S, const Epi& E) {
;     ...
;             PG8_WAIT_V(6); PG8_BAR; PG8_MMA(1, 1, At, B1); PG8_BAR;
;             PG8_LDB(B0, 1, 0); PG8_SCHED; PG8_LDA(At, 1, 0); PG8_STAGE(PG8_SA(0, 1), a2 + hstepA, voffA);
;             PG8_WAIT_L(8); PG8_BAR; PG8_WAIT_L(0); PG8_MMA(0, 0, At, B0); PG8_BAR; PG8_SCHED;
;             PG8_LDB(B1, 1, 1); PG8_STAGE(PG8_SB(1, 0), b3, voffB);
;             PG8_BAR; PG8_WAIT_L(0); PG8_MMA(0, 1, At, B1); PG8_BAR;
;             PG8_LDA(At, 1, 1); PG8_STAGE(PG8_SA(1, 0), a3, voffA);
;             PG8_BAR; PG8_WAIT_L(0); PG8_MMA(1, 0, At, B0); PG8_BAR; PG8_SCHED;
	s_add_u32 s6, s36, 0x100000
	s_addc_u32 s7, s37, 0
	s_add_i32 s53, s54, s11
	v_lshl_add_u64 v[138:139], s[6:7], 0, v[132:133]
	s_mov_b32 m0, s53
	s_nop 0
	global_load_lds_dwordx4 v[138:139], off
	v_lshl_add_u64 v[138:139], s[6:7], 0, v[130:131]
	s_add_i32 m0, s53, 0x2000
	s_nop 0
	global_load_lds_dwordx4 v[138:139], off
	s_waitcnt vmcnt(6)
	s_barrier
	v_mfma_f32_16x16x32_bf16 v[46:49], v[228:231], v[180:183], v[46:49]
	v_mfma_f32_16x16x32_bf16 v[42:45], v[236:239], v[180:183], v[42:45]
	v_mfma_f32_16x16x32_bf16 v[38:41], v[228:231], v[188:191], v[38:41]
	v_mfma_f32_16x16x32_bf16 v[34:37], v[236:239], v[188:191], v[34:37]
	v_mfma_f32_16x16x32_bf16 v[18:21], v[228:231], v[196:199], v[18:21]
	v_mfma_f32_16x16x32_bf16 v[10:13], v[236:239], v[196:199], v[10:13]
	v_mfma_f32_16x16x32_bf16 v[6:9], v[228:231], v[220:223], v[6:9]
	v_mfma_f32_16x16x32_bf16 v[2:5], v[236:239], v[220:223], v[2:5]
	v_mfma_f32_16x16x32_bf16 v[46:49], v[232:235], v[184:187], v[46:49]
	v_mfma_f32_16x16x32_bf16 v[42:45], v[240:243], v[184:187], v[42:45]
	v_mfma_f32_16x16x32_bf16 v[38:41], v[232:235], v[192:195], v[38:41]
	v_mfma_f32_16x16x32_bf16 v[34:37], v[240:243], v[192:195], v[34:37]
	v_mfma_f32_16x16x32_bf16 v[18:21], v[232:235], v[216:219], v[18:21]
	v_mfma_f32_16x16x32_bf16 v[10:13], v[240:243], v[216:219], v[10:13]
	v_mfma_f32_16x16x32_bf16 v[6:9], v[232:235], v[224:227], v[6:9]
	v_mfma_f32_16x16x32_bf16 v[2:5], v[240:243], v[224:227], v[2:5]
	s_add_i32 s53, 0, 0x18000
	v_add_u32_e32 v147, s53, v144
	s_barrier
	ds_read_b128 v[138:141], v147
	ds_read_b128 v[148:151], v147 offset:1024
	ds_read_b128 v[152:155], v147 offset:2048
	ds_read_b128 v[176:179], v147 offset:3072
	s_add_u32 s6, s42, 0x100000
	s_addc_u32 s7, s43, 0
	s_mov_b32 m0, s15
	v_lshl_add_u64 v[228:229], s[6:7], 0, v[132:133]
	ds_read_b128 v[180:183], v146 offset:32768
	ds_read_b128 v[184:187], v146 offset:33792
	ds_read_b128 v[188:191], v146 offset:34816
	ds_read_b128 v[192:195], v146 offset:35840
	ds_read_b128 v[196:199], v146 offset:36864
	ds_read_b128 v[216:219], v146 offset:37888
	ds_read_b128 v[220:223], v146 offset:38912
	ds_read_b128 v[224:227], v146 offset:39936
	global_load_lds_dwordx4 v[228:229], off
	v_lshl_add_u64 v[228:229], s[6:7], 0, v[130:131]
	s_mov_b32 m0, s16
	s_nop 0
	global_load_lds_dwordx4 v[228:229], off
	s_waitcnt lgkmcnt(8)
	s_barrier
	s_waitcnt lgkmcnt(0)
	s_waitcnt lgkmcnt(0)
	v_mfma_f32_16x16x32_bf16 v[126:129], v[138:141], v[180:183], v[126:129]
	v_mfma_f32_16x16x32_bf16 v[122:125], v[152:155], v[180:183], v[122:125]
	v_mfma_f32_16x16x32_bf16 v[118:121], v[138:141], v[188:191], v[118:121]
	v_mfma_f32_16x16x32_bf16 v[114:117], v[152:155], v[188:191], v[114:117]
	v_mfma_f32_16x16x32_bf16 v[94:97], v[138:141], v[196:199], v[94:97]
	v_mfma_f32_16x16x32_bf16 v[90:93], v[152:155], v[196:199], v[90:93]
	v_mfma_f32_16x16x32_bf16 v[86:89], v[138:141], v[220:223], v[86:89]
	v_mfma_f32_16x16x32_bf16 v[82:85], v[152:155], v[220:223], v[82:85]
	v_mfma_f32_16x16x32_bf16 v[126:129], v[148:151], v[184:187], v[126:129]
	v_mfma_f32_16x16x32_bf16 v[122:125], v[176:179], v[184:187], v[122:125]
	v_mfma_f32_16x16x32_bf16 v[118:121], v[148:151], v[192:195], v[118:121]
	v_mfma_f32_16x16x32_bf16 v[114:117], v[176:179], v[192:195], v[114:117]
	v_mfma_f32_16x16x32_bf16 v[94:97], v[148:151], v[216:219], v[94:97]
	v_mfma_f32_16x16x32_bf16 v[90:93], v[176:179], v[216:219], v[90:93]
	v_mfma_f32_16x16x32_bf16 v[86:89], v[148:151], v[224:227], v[86:89]
	v_mfma_f32_16x16x32_bf16 v[82:85], v[176:179], v[224:227], v[82:85]
	s_barrier
	s_add_i32 s42, 0, 0x1c000
	s_add_i32 s6, s53, s11
	v_add_u32_e32 v147, s42, v144
	v_lshl_add_u64 v[142:143], v[142:143], 0, s[88:89]
	s_mov_b32 m0, s6
	ds_read_b128 v[228:231], v147
	ds_read_b128 v[232:235], v147 offset:1024
	ds_read_b128 v[236:239], v147 offset:2048
	ds_read_b128 v[240:243], v147 offset:3072
	global_load_lds_dwordx4 v[142:143], off
	v_lshl_add_u64 v[142:143], v[212:213], 0, s[88:89]
	s_add_i32 m0, s6, 0x2000
	s_nop 0
	global_load_lds_dwordx4 v[142:143], off
	s_barrier
	s_waitcnt lgkmcnt(0)
	s_waitcnt lgkmcnt(0)
	v_mfma_f32_16x16x32_bf16 v[110:113], v[228:231], v[180:183], v[110:113]
	v_mfma_f32_16x16x32_bf16 v[106:109], v[236:239], v[180:183], v[106:109]
	v_mfma_f32_16x16x32_bf16 v[102:105], v[228:231], v[188:191], v[102:105]
	v_mfma_f32_16x16x32_bf16 v[98:101], v[236:239], v[188:191], v[98:101]
	v_mfma_f32_16x16x32_bf16 v[78:81], v[228:231], v[196:199], v[78:81]
	v_mfma_f32_16x16x32_bf16 v[74:77], v[236:239], v[196:199], v[74:77]
	v_mfma_f32_16x16x32_bf16 v[70:73], v[228:231], v[220:223], v[70:73]
	v_mfma_f32_16x16x32_bf16 v[66:69], v[236:239], v[220:223], v[66:69]
	v_mfma_f32_16x16x32_bf16 v[110:113], v[232:235], v[184:187], v[110:113]
	v_mfma_f32_16x16x32_bf16 v[106:109], v[240:243], v[184:187], v[106:109]
	v_mfma_f32_16x16x32_bf16 v[102:105], v[232:235], v[192:195], v[102:105]
	v_mfma_f32_16x16x32_bf16 v[98:101], v[240:243], v[192:195], v[98:101]
	v_mfma_f32_16x16x32_bf16 v[78:81], v[232:235], v[216:219], v[78:81]
	v_mfma_f32_16x16x32_bf16 v[74:77], v[240:243], v[216:219], v[74:77]
	v_mfma_f32_16x16x32_bf16 v[70:73], v[232:235], v[224:227], v[70:73]
	v_mfma_f32_16x16x32_bf16 v[66:69], v[240:243], v[224:227], v[66:69]
	s_mov_b32 m0, s17
	v_lshl_add_u64 v[142:143], v[244:245], 0, s[88:89]
	s_barrier
	ds_read_b128 v[180:183], v146 offset:49152
	ds_read_b128 v[184:187], v146 offset:50176
	ds_read_b128 v[188:191], v146 offset:51200
	ds_read_b128 v[192:195], v146 offset:52224
	ds_read_b128 v[196:199], v146 offset:53248
	ds_read_b128 v[216:219], v146 offset:54272
	ds_read_b128 v[220:223], v146 offset:55296
	ds_read_b128 v[224:227], v146 offset:56320
	global_load_lds_dwordx4 v[142:143], off
	v_lshl_add_u64 v[142:143], v[246:247], 0, s[88:89]
	s_mov_b32 m0, s33
	s_nop 0
	global_load_lds_dwordx4 v[142:143], off
	s_barrier
; __device__ __forceinline__ unsigned pk2(float lo, float hi) { unsigned r; asm volatile("v_cvt_pk_bf16_f32 %0, %1, %2" : "=v"(r) : "v"(lo), "v"(hi)); return r; }
; #define PG8_STAGE(bufoff, gbase, voff) do { _Pragma("unroll") for (int _i = 0; _i < 2; ++_i) \
;         __builtin_amdgcn_global_load_lds((const unsigned*)((const char*)(gbase) + (voff)[_i]), (LAS unsigned*)(lds + (bufoff) + ldsw + _i * 8192), 16, 0, 0); } while (0)
; #define PG8_MMA(ai, bj, At, Bt) do { __builtin_amdgcn_s_setprio(1); _Pragma("unroll") for (int m = 0; m < 4; ++m) _Pragma("unroll") for (int n = 0; n < 2; ++n) _Pragma("unroll") for (int k = 0; k < 2; ++k) \
;         acc[ai][bj][m][n] = __builtin_amdgcn_mfma_f32_16x16x32_bf16(Bt[n][k], At[m][k], acc[ai][bj][m][n], 0, 0, 0); __builtin_amdgcn_s_setprio(0); } while (0)
; #define PG8_BAR __builtin_amdgcn_s_barrier()
; template <class Epi>
; __device__ __forceinline__ void gemm_phase(LAS unsigned char* lds, const Gemm g, const StaticOrder& S, const Epi& E) {
;     ...
;             PG8_BAR; PG8_WAIT_L(0); PG8_MMA(1, 0, At, B0); PG8_BAR; PG8_SCHED;
;             PG8_STAGE(PG8_SB(1, 1), b3 + hstepB, voffB);
;             PG8_WAIT_V(6); PG8_BAR; PG8_MMA(1, 1, At, B1); PG8_BAR;
;     __device__ __forceinline__ void operator()(const f32x4 (&acc)[2][2][4][2], const Unit& u, int wr, int wc, int fr, int fq) const {
;     ...
;                         for (int n = 0; n < 2; ++n) { const int rr = rowb + ai * 128 + (mh * 2 + m2) * 16; const float* lp = !xin_p ? base + (size_t)rr * 1024 : (u.pm < 256 ? xin_p + (size_t)rr * 1024 : (u.pm < 260 ? xin_s + (size_t)(rr - NS0) * 1024 : xin_m + (size_t)fr * 1024));
;                             xv[m2][bj][n] = *(const f32x4*)(lp + colb + bj * 128 + n * 16); }
; #pragma unroll
;                 for (int m2 = 0; m2 < 2; ++m2) { const int m = mh * 2 + m2, row = rowb + ai * 128 + m * 16; float* rp = base + (size_t)row * 1024 + colb; float ss = 0.f;
; #pragma unroll
;                     for (int bj = 0; bj < 2; ++bj)
; #pragma unroll
;                         for (int n = 0; n < 2; ++n) { const f32x4 v = xv[m2][bj][n] + acc[ai][bj][m][n]; *(f32x4*)(rp + bj * 128 + n * 16) = v;
;                             if (XB) { u32x2 o; o[0] = pk2(v[0], v[1]); o[1] = pk2(v[2], v[3]); *(u32x2*)(XB + (size_t)row * 1024 + colb + bj * 128 + n * 16) = o; ss += (v[0] * v[0] + v[1] * v[1]) + (v[2] * v[2] + v[3] * v[3]); } }
	s_waitcnt lgkmcnt(0)
	s_waitcnt lgkmcnt(0)
	v_mfma_f32_16x16x32_bf16 v[62:65], v[138:141], v[180:183], v[62:65]
	v_mfma_f32_16x16x32_bf16 v[58:61], v[152:155], v[180:183], v[58:61]
	v_mfma_f32_16x16x32_bf16 v[54:57], v[138:141], v[188:191], v[54:57]
	v_mfma_f32_16x16x32_bf16 v[50:53], v[152:155], v[188:191], v[50:53]
	v_mfma_f32_16x16x32_bf16 v[30:33], v[138:141], v[196:199], v[30:33]
	v_mfma_f32_16x16x32_bf16 v[26:29], v[152:155], v[196:199], v[26:29]
	v_mfma_f32_16x16x32_bf16 v[22:25], v[138:141], v[220:223], v[22:25]
	v_mfma_f32_16x16x32_bf16 v[14:17], v[152:155], v[220:223], v[14:17]
	v_mfma_f32_16x16x32_bf16 v[62:65], v[148:151], v[184:187], v[62:65]
	v_mfma_f32_16x16x32_bf16 v[58:61], v[176:179], v[184:187], v[58:61]
	v_mfma_f32_16x16x32_bf16 v[54:57], v[148:151], v[192:195], v[54:57]
	v_mfma_f32_16x16x32_bf16 v[50:53], v[176:179], v[192:195], v[50:53]
	v_mfma_f32_16x16x32_bf16 v[30:33], v[148:151], v[216:219], v[30:33]
	v_mfma_f32_16x16x32_bf16 v[26:29], v[176:179], v[216:219], v[26:29]
	v_mfma_f32_16x16x32_bf16 v[22:25], v[148:151], v[224:227], v[22:25]
	v_mfma_f32_16x16x32_bf16 v[14:17], v[176:179], v[224:227], v[14:17]
	s_barrier
	s_add_u32 s6, s36, 0x100080
	s_addc_u32 s7, s37, 0
	s_add_i32 s36, s42, s11
	v_lshl_add_u64 v[138:139], s[6:7], 0, v[132:133]
	s_mov_b32 m0, s36
	s_nop 0
	global_load_lds_dwordx4 v[138:139], off
	v_lshl_add_u64 v[138:139], s[6:7], 0, v[130:131]
	s_add_i32 m0, s36, 0x2000
	s_nop 0
	global_load_lds_dwordx4 v[138:139], off
	s_waitcnt vmcnt(6)
	s_barrier
	v_mfma_f32_16x16x32_bf16 v[46:49], v[228:231], v[180:183], v[46:49]
	v_mfma_f32_16x16x32_bf16 v[42:45], v[236:239], v[180:183], v[42:45]
	v_mfma_f32_16x16x32_bf16 v[38:41], v[228:231], v[188:191], v[38:41]
	v_mfma_f32_16x16x32_bf16 v[34:37], v[236:239], v[188:191], v[34:37]
	v_mfma_f32_16x16x32_bf16 v[18:21], v[228:231], v[196:199], v[18:21]
	v_mfma_f32_16x16x32_bf16 v[10:13], v[236:239], v[196:199], v[10:13]
	v_mfma_f32_16x16x32_bf16 v[6:9], v[228:231], v[220:223], v[6:9]
	v_mfma_f32_16x16x32_bf16 v[2:5], v[236:239], v[220:223], v[2:5]
	v_mfma_f32_16x16x32_bf16 v[46:49], v[232:235], v[184:187], v[46:49]
	v_mfma_f32_16x16x32_bf16 v[42:45], v[240:243], v[184:187], v[42:45]
	v_mfma_f32_16x16x32_bf16 v[38:41], v[232:235], v[192:195], v[38:41]
	v_mfma_f32_16x16x32_bf16 v[34:37], v[240:243], v[192:195], v[34:37]
	v_mfma_f32_16x16x32_bf16 v[18:21], v[232:235], v[216:219], v[18:21]
	v_mfma_f32_16x16x32_bf16 v[10:13], v[240:243], v[216:219], v[10:13]
	v_mfma_f32_16x16x32_bf16 v[6:9], v[232:235], v[224:227], v[6:9]
	v_mfma_f32_16x16x32_bf16 v[2:5], v[240:243], v[224:227], v[2:5]
	s_add_i32 s52, s52, 2
	s_add_u32 s34, s34, 0x100
	s_addc_u32 s35, s35, 0
	s_add_u32 s50, s50, 0x100
	s_addc_u32 s51, s51, 0
	s_cmp_gt_u32 s52, 61
	s_barrier
	s_cbranch_scc0 .LBB0_88
	v_lshl_add_u32 v212, s30, 8, v1
	v_or_b32_e32 v184, 16, v212
	v_lshl_or_b32 v138, s31, 8, v145
	s_cmpk_lt_i32 s30, 0x104
	v_ashrrev_i32_e32 v213, 31, v212
	v_ashrrev_i32_e32 v185, 31, v184
	s_cselect_b32 s31, s19, s46
	s_cselect_b32 s30, s18, s45
	v_ashrrev_i32_e32 v139, 31, v138
	v_lshlrev_b64 v[142:143], 12, v[212:213]
	v_lshlrev_b64 v[216:217], 12, v[184:185]
	v_lshlrev_b64 v[140:141], 2, v[138:139]
	v_lshl_add_u64 v[148:149], s[30:31], 0, v[142:143]
	v_lshl_add_u64 v[184:185], s[30:31], 0, v[216:217]
	v_lshl_add_u64 v[180:181], v[148:149], 0, v[140:141]
	v_lshl_add_u64 v[196:197], v[184:185], 0, v[140:141]
	global_load_dwordx4 v[148:151], v[180:181], off
	global_load_dwordx4 v[152:155], v[180:181], off offset:64
	global_load_dwordx4 v[176:179], v[180:181], off offset:512
	s_nop 0
	global_load_dwordx4 v[180:183], v[180:181], off offset:576
	s_nop 0
	global_load_dwordx4 v[184:187], v[196:197], off
	global_load_dwordx4 v[188:191], v[196:197], off offset:64
	global_load_dwordx4 v[192:195], v[196:197], off offset:512
	s_nop 0
	global_load_dwordx4 v[196:199], v[196:197], off offset:576
	v_lshl_add_u64 v[138:139], s[30:31], 0, v[140:141]
	v_lshl_add_u64 v[218:219], v[138:139], 0, v[142:143]
	s_mov_b64 s[6:7], 0x80000
	s_and_b64 vcc, exec, s[40:41]
	s_mov_b64 s[36:37], s[28:29]
	s_mov_b64 s[34:35], s[26:27]
	s_waitcnt vmcnt(0)
	v_pk_add_f32 v[126:127], v[126:127], v[148:149]
	v_pk_add_f32 v[128:129], v[128:129], v[150:151]
	v_pk_add_f32 v[112:113], v[112:113], v[178:179]
	v_pk_add_f32 v[110:111], v[110:111], v[176:177]
	global_store_dwordx4 v[218:219], v[110:113], off offset:512
	v_pk_add_f32 v[108:109], v[108:109], v[182:183]
	v_pk_add_f32 v[106:107], v[106:107], v[180:181]
	v_lshl_add_u64 v[110:111], v[138:139], 0, v[216:217]
	v_pk_add_f32 v[100:101], v[100:101], v[198:199]
	v_pk_add_f32 v[98:99], v[98:99], v[196:197]
	global_store_dwordx4 v[218:219], v[106:109], off offset:576
	global_store_dwordx4 v[110:111], v[98:101], off offset:576
	v_pk_add_f32 v[124:125], v[124:125], v[154:155]
	v_pk_add_f32 v[108:109], v[120:121], v[186:187]
	v_pk_add_f32 v[106:107], v[118:119], v[184:185]
	v_or_b32_e32 v98, 32, v212
	global_store_dwordx4 v[110:111], v[106:109], off
	v_ashrrev_i32_e32 v99, 31, v98
	v_lshlrev_b64 v[148:149], 12, v[98:99]
	v_pk_add_f32 v[106:107], v[114:115], v[188:189]
	v_or_b32_e32 v114, 48, v212
	v_ashrrev_i32_e32 v115, 31, v114
	v_pk_add_f32 v[122:123], v[122:123], v[152:153]
	v_pk_add_f32 v[108:109], v[116:117], v[190:191]
	v_pk_add_f32 v[104:105], v[104:105], v[194:195]
	v_pk_add_f32 v[102:103], v[102:103], v[192:193]
	v_lshl_add_u64 v[98:99], s[30:31], 0, v[148:149]
	v_lshlrev_b64 v[150:151], 12, v[114:115]
	global_store_dwordx4 v[218:219], v[126:129], off
	global_store_dwordx4 v[218:219], v[122:125], off offset:64
	global_store_dwordx4 v[110:111], v[106:109], off offset:64
	global_store_dwordx4 v[110:111], v[102:105], off offset:512
	v_lshl_add_u64 v[110:111], v[98:99], 0, v[140:141]
	v_lshl_add_u64 v[114:115], s[30:31], 0, v[150:151]
	global_load_dwordx4 v[98:101], v[110:111], off
	global_load_dwordx4 v[102:105], v[110:111], off offset:64
	global_load_dwordx4 v[106:109], v[110:111], off offset:512
	s_nop 0
	global_load_dwordx4 v[110:113], v[110:111], off offset:576
	v_lshl_add_u64 v[126:127], v[114:115], 0, v[140:141]
	global_load_dwordx4 v[114:117], v[126:127], off
	global_load_dwordx4 v[118:121], v[126:127], off offset:64
	global_load_dwordx4 v[122:125], v[126:127], off offset:512
	s_nop 0
	global_load_dwordx4 v[126:129], v[126:127], off offset:576
	v_lshl_add_u64 v[148:149], v[138:139], 0, v[148:149]
	s_waitcnt vmcnt(0)
; #define PG8_WAIT_V(n) asm volatile("s_waitcnt vmcnt(" #n ")" ::: "memory")
; #define PG8_BAR __builtin_amdgcn_s_barrier()
; template <class Epi>
; __device__ __forceinline__ void gemm_phase(LAS unsigned char* lds, const Gemm g, const StaticOrder& S, const Epi& E) {
;     ...
;     PG8_WAIT_V(0);
;     if (wr == 0) PG8_BAR;
;     PG8_BAR;
;     __device__ __forceinline__ void operator()(const f32x4 (&acc)[2][2][4][2], const Unit& u, int wr, int wc, int fr, int fq) const {
;     ...
;                         for (int n = 0; n < 2; ++n) { const int rr = rowb + ai * 128 + (mh * 2 + m2) * 16; const float* lp = !xin_p ? base + (size_t)rr * 1024 : (u.pm < 256 ? xin_p + (size_t)rr * 1024 : (u.pm < 260 ? xin_s + (size_t)(rr - NS0) * 1024 : xin_m + (size_t)fr * 1024));
;                             xv[m2][bj][n] = *(const f32x4*)(lp + colb + bj * 128 + n * 16); }
; #pragma unroll
;                 for (int m2 = 0; m2 < 2; ++m2) { const int m = mh * 2 + m2, row = rowb + ai * 128 + m * 16; float* rp = base + (size_t)row * 1024 + colb; float ss = 0.f;
; #pragma unroll
;                     for (int bj = 0; bj < 2; ++bj)
; #pragma unroll
;                         for (int n = 0; n < 2; ++n) { const f32x4 v = xv[m2][bj][n] + acc[ai][bj][m][n]; *(f32x4*)(rp + bj * 128 + n * 16) = v;
	v_pk_add_f32 v[94:95], v[94:95], v[98:99]
	v_lshl_add_u64 v[98:99], v[142:143], 0, s[6:7]
	v_pk_add_f32 v[80:81], v[80:81], v[108:109]
	v_pk_add_f32 v[78:79], v[78:79], v[106:107]
	v_pk_add_f32 v[76:77], v[76:77], v[112:113]
	v_pk_add_f32 v[74:75], v[74:75], v[110:111]
	global_store_dwordx4 v[148:149], v[78:81], off offset:512
	global_store_dwordx4 v[148:149], v[74:77], off offset:576
	v_pk_add_f32 v[68:69], v[68:69], v[128:129]
	v_lshl_add_u64 v[78:79], v[138:139], 0, v[150:151]
	v_pk_add_f32 v[76:77], v[88:89], v[116:117]
	v_pk_add_f32 v[74:75], v[86:87], v[114:115]
	v_pk_add_f32 v[66:67], v[66:67], v[126:127]
	s_mov_b64 s[6:7], 0x90000
	v_pk_add_f32 v[96:97], v[96:97], v[100:101]
	v_pk_add_f32 v[92:93], v[92:93], v[104:105]
	v_pk_add_f32 v[90:91], v[90:91], v[102:103]
	global_store_dwordx4 v[78:79], v[74:77], off
	v_pk_add_f32 v[72:73], v[72:73], v[124:125]
	v_pk_add_f32 v[70:71], v[70:71], v[122:123]
	v_pk_add_f32 v[76:77], v[84:85], v[120:121]
	v_pk_add_f32 v[74:75], v[82:83], v[118:119]
	global_store_dwordx4 v[78:79], v[66:69], off offset:576
	v_lshl_add_u64 v[100:101], v[142:143], 0, s[6:7]
	global_store_dwordx4 v[148:149], v[94:97], off
	v_lshl_add_u64 v[66:67], s[30:31], 0, v[98:99]
	global_store_dwordx4 v[148:149], v[90:93], off offset:64
	global_store_dwordx4 v[78:79], v[74:77], off offset:64
	global_store_dwordx4 v[78:79], v[70:73], off offset:512
	v_lshl_add_u64 v[78:79], v[66:67], 0, v[140:141]
	v_lshl_add_u64 v[82:83], s[30:31], 0, v[100:101]
	global_load_dwordx4 v[66:69], v[78:79], off
	global_load_dwordx4 v[70:73], v[78:79], off offset:64
	global_load_dwordx4 v[74:77], v[78:79], off offset:512
	s_nop 0
	global_load_dwordx4 v[78:81], v[78:79], off offset:576
	v_lshl_add_u64 v[94:95], v[82:83], 0, v[140:141]
	global_load_dwordx4 v[82:85], v[94:95], off
	global_load_dwordx4 v[86:89], v[94:95], off offset:64
	global_load_dwordx4 v[90:93], v[94:95], off offset:512
	s_nop 0
	global_load_dwordx4 v[94:97], v[94:95], off offset:576
	v_lshl_add_u64 v[98:99], v[138:139], 0, v[98:99]
	s_mov_b64 s[6:7], 0xa0000
	s_waitcnt vmcnt(0)
	v_pk_add_f32 v[62:63], v[62:63], v[66:67]
	v_lshl_add_u64 v[66:67], v[142:143], 0, s[6:7]
	v_pk_add_f32 v[48:49], v[48:49], v[76:77]
	v_pk_add_f32 v[46:47], v[46:47], v[74:75]
	v_pk_add_f32 v[44:45], v[44:45], v[80:81]
	v_pk_add_f32 v[42:43], v[42:43], v[78:79]
	global_store_dwordx4 v[98:99], v[46:49], off offset:512
	global_store_dwordx4 v[98:99], v[42:45], off offset:576
	v_pk_add_f32 v[36:37], v[36:37], v[96:97]
	v_lshl_add_u64 v[46:47], v[138:139], 0, v[100:101]
	v_pk_add_f32 v[44:45], v[56:57], v[84:85]
	v_pk_add_f32 v[42:43], v[54:55], v[82:83]
	v_pk_add_f32 v[34:35], v[34:35], v[94:95]
	v_pk_add_f32 v[64:65], v[64:65], v[68:69]
	v_pk_add_f32 v[60:61], v[60:61], v[72:73]
	v_pk_add_f32 v[58:59], v[58:59], v[70:71]
	global_store_dwordx4 v[46:47], v[42:45], off
	v_pk_add_f32 v[40:41], v[40:41], v[92:93]
	v_pk_add_f32 v[38:39], v[38:39], v[90:91]
	v_pk_add_f32 v[44:45], v[52:53], v[88:89]
	v_pk_add_f32 v[42:43], v[50:51], v[86:87]
	global_store_dwordx4 v[46:47], v[34:37], off offset:576
	s_mov_b64 s[6:7], 0xb0000
	global_store_dwordx4 v[98:99], v[62:65], off
	v_lshl_add_u64 v[34:35], s[30:31], 0, v[66:67]
	global_store_dwordx4 v[98:99], v[58:61], off offset:64
	global_store_dwordx4 v[46:47], v[42:45], off offset:64
	global_store_dwordx4 v[46:47], v[38:41], off offset:512
	v_lshl_add_u64 v[34:35], v[34:35], 0, v[140:141]
	v_lshl_add_u64 v[68:69], v[142:143], 0, s[6:7]
	global_load_dwordx4 v[46:49], v[34:35], off
	global_load_dwordx4 v[42:45], v[34:35], off offset:64
	global_load_dwordx4 v[38:41], v[34:35], off offset:512
	s_nop 0
	global_load_dwordx4 v[34:37], v[34:35], off offset:576
	v_lshl_add_u64 v[50:51], s[30:31], 0, v[68:69]
	v_lshl_add_u64 v[58:59], v[50:51], 0, v[140:141]
	global_load_dwordx4 v[54:57], v[58:59], off
	global_load_dwordx4 v[50:53], v[58:59], off offset:64
	global_load_dwordx4 v[62:65], v[58:59], off offset:512
	s_nop 0
	global_load_dwordx4 v[58:61], v[58:59], off offset:576
	v_lshl_add_u64 v[66:67], v[138:139], 0, v[66:67]
	s_mov_b32 s31, s20
	s_mov_b32 s30, s24
	s_waitcnt vmcnt(0)
	v_pk_add_f32 v[32:33], v[32:33], v[48:49]
	v_pk_add_f32 v[30:31], v[30:31], v[46:47]
	v_pk_add_f32 v[20:21], v[20:21], v[40:41]
	v_pk_add_f32 v[18:19], v[18:19], v[38:39]
	v_pk_add_f32 v[12:13], v[12:13], v[36:37]
	v_pk_add_f32 v[10:11], v[10:11], v[34:35]
	global_store_dwordx4 v[66:67], v[18:21], off offset:512
	global_store_dwordx4 v[66:67], v[10:13], off offset:576
	v_pk_add_f32 v[28:29], v[28:29], v[44:45]
	v_lshl_add_u64 v[18:19], v[138:139], 0, v[68:69]
	v_pk_add_f32 v[12:13], v[24:25], v[56:57]
	v_pk_add_f32 v[10:11], v[22:23], v[54:55]
	v_pk_add_f32 v[26:27], v[26:27], v[42:43]
	global_store_dwordx4 v[18:19], v[10:13], off
	v_pk_add_f32 v[8:9], v[8:9], v[64:65]
	v_pk_add_f32 v[6:7], v[6:7], v[62:63]
	v_pk_add_f32 v[12:13], v[16:17], v[52:53]
	v_pk_add_f32 v[10:11], v[14:15], v[50:51]
	v_pk_add_f32 v[4:5], v[4:5], v[60:61]
	v_pk_add_f32 v[2:3], v[2:3], v[58:59]
	global_store_dwordx4 v[66:67], v[30:33], off
	global_store_dwordx4 v[66:67], v[26:29], off offset:64
	global_store_dwordx4 v[18:19], v[10:13], off offset:64
	global_store_dwordx4 v[18:19], v[6:9], off offset:512
	global_store_dwordx4 v[18:19], v[2:5], off offset:576
	s_cbranch_vccz .LBB0_85
	s_waitcnt vmcnt(0)
	s_cmpk_gt_u32 s8, 0xff
	s_cbranch_scc1 .LBB0_92
	s_barrier

; #define LAS __attribute__((address_space(3)))
; __device__ __forceinline__ int ltid() { int t = threadIdx.x; asm volatile("" : "+v"(t)); return t; }
; #define PG8_BAR __builtin_amdgcn_s_barrier()
;     __device__ bool next(int i, Unit& u) const {
;         const long L = (long)i * G + c; if (L >= nwg) return false;
;         int wgid = (int)L; { const int q = nwg / NXCD, r = nwg % NXCD, xcd = wgid % NXCD, off = wgid / NXCD; wgid = (xcd < r ? xcd * (q + 1) : r * (q + 1) + (xcd - r) * q) + off; }
;         const int nig = WGM * nN, gid = wgid / nig, fm = gid * WGM, gsz = (nM - fm) < WGM ? (nM - fm) : WGM;
;         u.pm = fm + ((wgid % nig) % gsz); u.pn = (wgid % nig) / gsz; return true;
;     }
; template <class Epi>
; __device__ __forceinline__ void gemm_phase(LAS unsigned char* lds, const Gemm g, const StaticOrder& S, const Epi& E) {
;     const int tid = ltid(), wid = __builtin_amdgcn_readfirstlane(tid >> 6), lane = tid & 63, wr = wid >> 2, wc = wid & 3, fr = lane & 15, fq = lane >> 4;
;     const int K = g.K, nt = K / BK;
;     unsigned voffA[2], voffB[2];
; #pragma unroll
;     for (int i = 0; i < 2; ++i) { int R, C; stage_rc(tid * 16 + i * 8192, R, C); voffA[i] = (unsigned)(R * g.lda + C) * 2u; voffB[i] = (unsigned)(R * g.ldb + C) * 2u; }
;     const size_t kstep = (size_t)(BK * 2);
;     const size_t hstepA = (size_t)HALF * g.lda * 2, hstepB = (size_t)HALF * g.ldb * 2;
;     const size_t tstepA = 2 * hstepA, tstepB = 2 * hstepB;
;     const unsigned ldsw = (unsigned)wid * 1024u;
;     const int aoff = lds_byte(wr * 64 + fr, fq * 8), boff = lds_byte(wc * 32 + fr, fq * 8);
;     ...
;     Unit cur, nxt; int ui = 0;
;     if (!S.next(0, cur)) return;
;     f32x4 acc[2][2][4][2];
; #pragma unroll
;     for (int a = 0; a < 2; ++a)
; #pragma unroll
;         for (int b = 0; b < 2; ++b)
; #pragma unroll
;             for (int m = 0; m < 4; ++m)
; #pragma unroll
;                 for (int n = 0; n < 2; ++n) acc[a][b][m][n] = (f32x4){0.f, 0.f, 0.f, 0.f};
;     bf16x8 At[4][2], B0[2][2], B1[2][2];
;     const char* cA = (const char*)g.A + (size_t)cur.pm * tstepA; const char* cB = (const char*)g.Bt + (size_t)cur.pn * tstepB;
;     PG8_STAGE(PG8_SB(0, 0), cB, voffB); PG8_STAGE(PG8_SA(0, 0), cA, voffA); PG8_STAGE(PG8_SB(0, 1), cB + hstepB, voffB); PG8_STAGE(PG8_SA(0, 1), cA + hstepA, voffA);
;     if (wr == 1) PG8_BAR;
.LBB0_94:
	s_andn2_b64 vcc, exec, s[18:19]
	s_cbranch_vccnz .LBB0_107
	s_mov_b32 s0, s68
	v_readlane_b32 s1, v254, 0
	s_waitcnt vmcnt(0)
	v_mov_b32_e32 v16, v200
	s_cmpk_gt_i32 s1, 0x105f
	v_readfirstlane_b32 s8, v16
	s_cbranch_scc1 .LBB0_107
	v_lshlrev_b32_e32 v1, 4, v16
	v_add_u32_e32 v2, 0x2000, v1
	v_ashrrev_i32_e32 v3, 31, v2
	v_lshrrev_b32_e32 v3, 22, v3
	v_add_u32_e32 v3, v2, v3
	v_ashrrev_i32_e32 v10, 10, v3
	v_readlane_b32 s6, v255, 30
	v_mul_i32_i24_e32 v4, 0x400, v10
	v_readlane_b32 s7, v255, 31
	v_sub_u32_e32 v2, v2, v4
	s_load_dwordx2 s[6:7], s[6:7], 0x118
	v_lshrrev_b32_e32 v4, 4, v2
	v_bitop3_b32 v2, v4, v2, 32 bitop3:0x6c
	v_ashrrev_i32_e32 v4, 31, v2
	v_lshrrev_b32_e32 v4, 26, v4
	v_add_u32_e32 v4, v2, v4
	s_waitcnt lgkmcnt(0)
	s_add_u32 s9, s6, 0x35ac1000
	v_ashrrev_i32_e32 v11, 6, v4
	v_and_b32_e32 v4, 0xc0, v4
	s_addc_u32 s10, s7, 0
	v_sub_u32_e32 v2, v2, v4
	s_add_u32 s11, s6, 0x1600000
	v_lshlrev_b32_e32 v3, 5, v10
	v_ashrrev_i16_sdwa v2, v201, sext(v2) dst_sel:DWORD dst_unused:UNUSED_PAD src0_sel:DWORD src1_sel:BYTE_0
	s_addc_u32 s12, s7, 0
	v_and_b32_e32 v3, 32, v3
	v_bfe_i32 v12, v2, 0, 16
	s_ashr_i32 s14, s1, 31
	v_add_u32_e32 v2, v3, v12
	v_lshlrev_b32_e32 v3, 3, v10
	s_lshr_b32 s6, s14, 29
	v_and_b32_e32 v3, 0x1ffff0, v3
	s_add_i32 s6, s1, s6
	s_ashr_i32 s20, s8, 6
	v_add_lshl_u32 v3, v11, v3, 11
	s_ashr_i32 s7, s6, 3
	s_and_b32 s6, s6, -8
	s_ashr_i32 s21, s8, 8
	s_lshl_b32 s13, s20, 10
	v_lshl_add_u32 v130, v2, 1, v3
	v_bfe_i32 v3, v16, 27, 1
	s_sub_i32 s6, s1, s6
	v_lshrrev_b32_e32 v3, 22, v3
	s_cmp_lt_i32 s6, 0
	s_movk_i32 s15, 0x20d
	v_add_u32_e32 v3, v1, v3
	s_cselect_b32 s15, s15, 0x20c
	v_and_b32_e32 v3, 0xfffffc00, v3
	s_mul_i32 s6, s6, s15
	v_sub_u32_e32 v1, v1, v3
	s_add_i32 s6, s6, s7
	v_lshrrev_b32_e32 v3, 4, v1
	s_ashr_i32 s7, s6, 31
	v_bitop3_b32 v3, v3, v1, 32 bitop3:0x6c
	v_ashrrev_i32_e32 v1, 31, v1
	s_lshr_b32 s7, s7, 25
	v_lshrrev_b32_e32 v1, 26, v1
	s_add_i32 s7, s6, s7
	v_ashrrev_i32_e32 v2, 31, v16
	v_add_u32_e32 v1, v3, v1
	s_ashr_i32 s15, s7, 7
	v_lshrrev_b32_e32 v2, 26, v2
	v_ashrrev_i32_e32 v14, 6, v1
	s_lshl_b32 s15, s15, 3
	v_add_u32_e32 v2, v16, v2
	v_mul_i32_i24_e32 v1, 64, v14
	s_sub_i32 s16, 0x106, s15
	v_ashrrev_i32_e32 v13, 6, v2
	v_sub_u32_e32 v1, v3, v1
	s_min_u32 s16, s16, 8
	s_and_b32 s7, s7, 0xffffff80
	v_lshlrev_b32_e32 v2, 5, v13
	v_ashrrev_i16_sdwa v1, v201, sext(v1) dst_sel:DWORD dst_unused:UNUSED_PAD src0_sel:DWORD src1_sel:BYTE_0
	s_sub_i32 s17, s6, s7
	v_cvt_f32_ubyte0_e32 v4, s16
	v_and_b32_e32 v2, 32, v2
	v_bfe_i32 v15, v1, 0, 16
	v_cvt_f32_i32_e32 v3, s17
	v_rcp_iflag_f32_e32 v5, v4
	v_add_u32_e32 v1, v2, v15
	v_lshlrev_b32_e32 v2, 3, v13
	v_and_b32_e32 v2, 0x1ffff0, v2
	v_add_lshl_u32 v2, v14, v2, 11
	v_lshl_add_u32 v132, v1, 1, v2
	v_mul_f32_e32 v1, v3, v5
	v_trunc_f32_e32 v1, v1
	v_fma_f32 v2, -v1, v4, v3
	v_cvt_i32_f32_e32 v1, v1
	s_ashr_i32 s6, s17, 30
	s_or_b32 s18, s6, 1
	v_cmp_ge_f32_e64 s[6:7], |v2|, v4
	s_and_b64 s[6:7], s[6:7], exec
	s_cselect_b32 s6, s18, 0
	v_readfirstlane_b32 s7, v1
	s_add_i32 s18, s7, s6
	s_mul_i32 s6, s18, s16
	s_sub_i32 s6, s17, s6
	s_sext_i32_i8 s6, s6
	s_add_i32 s30, s15, s6
	s_ashr_i32 s31, s30, 31
	s_bfe_i64 s[16:17], s[18:19], 0x80000
	s_lshl_b64 s[6:7], s[30:31], 19
	s_lshl_b64 s[16:17], s[16:17], 19
	s_add_u32 s36, s11, s16
	s_addc_u32 s37, s12, s17
	s_add_i32 s15, s13, 0
	s_add_i32 m0, s15, 0x10000
	v_mov_b32_e32 v133, v0
	global_load_lds_dwordx4 v132, s[36:37]
	s_add_i32 m0, s15, 0x12000
	s_add_u32 s34, s9, s6
	global_load_lds_dwordx4 v130, s[36:37]
	s_addc_u32 s35, s10, s7
	s_mov_b32 m0, s15
	s_add_i32 s16, s15, 0x2000
	global_load_lds_dwordx4 v132, s[34:35]
	s_mov_b32 m0, s16
	s_add_u32 s6, s36, 0x40000
	global_load_lds_dwordx4 v130, s[34:35]
	s_addc_u32 s7, s37, 0
	s_add_i32 m0, s15, 0x14000
	v_mov_b32_e32 v131, v0
	global_load_lds_dwordx4 v132, s[6:7]
	s_add_i32 m0, s15, 0x16000
	v_lshl_add_u64 v[8:9], s[36:37], 0, v[132:133]
	global_load_lds_dwordx4 v130, s[6:7]
	s_add_u32 s6, s34, 0x40000
	s_addc_u32 s7, s35, 0
	s_add_i32 s17, s15, 0x4000
	s_mov_b32 m0, s17
	s_add_i32 s33, s15, 0x6000
	global_load_lds_dwordx4 v132, s[6:7]
	s_mov_b32 m0, s33
	v_lshl_add_u64 v[6:7], s[36:37], 0, v[130:131]
	global_load_lds_dwordx4 v130, s[6:7]
	v_lshl_add_u64 v[4:5], s[34:35], 0, v[132:133]
	s_cmp_lg_u32 s21, 1
	v_lshl_add_u64 v[2:3], s[34:35], 0, v[130:131]
	s_cbranch_scc1 .LBB0_98
	s_barrier
	s_setprio 1

; #define PG8_STAGE(bufoff, gbase, voff) do { _Pragma("unroll") for (int _i = 0; _i < 2; ++_i) \
;         __builtin_amdgcn_global_load_lds((const unsigned*)((const char*)(gbase) + (voff)[_i]), (LAS unsigned*)(lds + (bufoff) + ldsw + _i * 8192), 16, 0, 0); } while (0)
; #define PG8_LDA(dst, b, h) do { _Pragma("unroll") for (int m = 0; m < 4; ++m) _Pragma("unroll") for (int k = 0; k < 2; ++k) dst[m][k] = *(const LAS bf16x8*)(lds + PG8_SA(b, h) + aoff + m * 2048 + k * 1024); } while (0)
; #define PG8_LDB(dst, b, h) do { _Pragma("unroll") for (int n = 0; n < 2; ++n) _Pragma("unroll") for (int k = 0; k < 2; ++k) dst[n][k] = *(const LAS bf16x8*)(lds + PG8_SB(b, h) + boff + n * 2048 + k * 1024); } while (0)
; #define PG8_MMA(ai, bj, At, Bt) do { __builtin_amdgcn_s_setprio(1); _Pragma("unroll") for (int m = 0; m < 4; ++m) _Pragma("unroll") for (int n = 0; n < 2; ++n) _Pragma("unroll") for (int k = 0; k < 2; ++k) \
;         acc[ai][bj][m][n] = __builtin_amdgcn_mfma_f32_16x16x32_bf16(Bt[n][k], At[m][k], acc[ai][bj][m][n], 0, 0, 0); __builtin_amdgcn_s_setprio(0); } while (0)
; #define PG8_WAIT_L(n) asm volatile("s_waitcnt lgkmcnt(" #n ")" ::: "memory")
; #define PG8_BAR __builtin_amdgcn_s_barrier()
; #define PG8_SCHED __builtin_amdgcn_sched_barrier(0)
; template <class Epi>
; __device__ __forceinline__ void gemm_phase(LAS unsigned char* lds, const Gemm g, const StaticOrder& S, const Epi& E) {
;     ...
;             const char* a1 = cA + (size_t)(t + 1) * kstep;
;             const char* a2 = last ? nA : cA + (size_t)(t + 2) * kstep; const char* b2 = last ? nB : cB + (size_t)(t + 2) * kstep;
;             const char* a3 = a2 + kstep; const char* b3 = b2 + kstep;
;             PG8_LDB(B0, 0, 0); PG8_SCHED; PG8_LDA(At, 0, 0); PG8_STAGE(PG8_SA(1, 1), a1 + hstepA, voffA);
;             PG8_WAIT_L(8); PG8_BAR; PG8_WAIT_L(0); PG8_MMA(0, 0, At, B0); PG8_BAR; PG8_SCHED;
;             PG8_LDB(B1, 0, 1); PG8_STAGE(PG8_SB(0, 0), b2, voffB);
;             PG8_BAR; PG8_WAIT_L(0); PG8_MMA(0, 1, At, B1); PG8_BAR;
;             PG8_LDA(At, 0, 1); PG8_STAGE(PG8_SA(0, 0), a2, voffA);
;             PG8_BAR; PG8_WAIT_L(0); PG8_MMA(1, 0, At, B0); PG8_BAR; PG8_SCHED;
.LBB0_102:
	s_add_u32 s6, s34, 0xfffc0080
	s_addc_u32 s7, s35, -1
	s_add_i32 s53, 0, 0x10000
	v_add_u32_e32 v139, s53, v148
	ds_read_b128 v[140:143], v139
	ds_read_b128 v[144:147], v139 offset:1024
	ds_read_b128 v[150:153], v139 offset:2048
	ds_read_b128 v[176:179], v139 offset:3072
	s_cmp_eq_u32 s52, 12
	s_cselect_b32 s43, s25, s7
	s_cselect_b32 s42, s48, s6
	s_cselect_b32 s37, s21, s51
	s_cselect_b32 s36, s49, s50
	v_lshl_add_u64 v[154:155], s[34:35], 0, v[134:135]
	s_add_i32 m0, s15, 0xc000
	ds_read_b128 v[180:183], v149
	ds_read_b128 v[184:187], v149 offset:1024
	ds_read_b128 v[188:191], v149 offset:2048
	ds_read_b128 v[192:195], v149 offset:3072
	ds_read_b128 v[196:199], v149 offset:4096
	ds_read_b128 v[216:219], v149 offset:5120
	ds_read_b128 v[220:223], v149 offset:6144
	ds_read_b128 v[224:227], v149 offset:7168
	global_load_lds_dwordx4 v[154:155], off
	v_lshl_add_u64 v[154:155], s[34:35], 0, v[136:137]
	s_add_i32 m0, s15, 0xe000
	s_nop 0
	global_load_lds_dwordx4 v[154:155], off
	s_waitcnt lgkmcnt(8)
	s_barrier
	s_waitcnt lgkmcnt(0)
	s_waitcnt lgkmcnt(0)
	v_mfma_f32_16x16x32_bf16 v[126:129], v[140:143], v[180:183], v[126:129]
	v_mfma_f32_16x16x32_bf16 v[122:125], v[150:153], v[180:183], v[122:125]
	v_mfma_f32_16x16x32_bf16 v[110:113], v[140:143], v[188:191], v[110:113]
	v_mfma_f32_16x16x32_bf16 v[106:109], v[150:153], v[188:191], v[106:109]
	v_mfma_f32_16x16x32_bf16 v[94:97], v[140:143], v[196:199], v[94:97]
	v_mfma_f32_16x16x32_bf16 v[90:93], v[150:153], v[196:199], v[90:93]
	v_mfma_f32_16x16x32_bf16 v[78:81], v[140:143], v[220:223], v[78:81]
	v_mfma_f32_16x16x32_bf16 v[74:77], v[150:153], v[220:223], v[74:77]
	v_mfma_f32_16x16x32_bf16 v[126:129], v[144:147], v[184:187], v[126:129]
	v_mfma_f32_16x16x32_bf16 v[122:125], v[176:179], v[184:187], v[122:125]
	v_mfma_f32_16x16x32_bf16 v[110:113], v[144:147], v[192:195], v[110:113]
	v_mfma_f32_16x16x32_bf16 v[106:109], v[176:179], v[192:195], v[106:109]
	v_mfma_f32_16x16x32_bf16 v[94:97], v[144:147], v[216:219], v[94:97]
	v_mfma_f32_16x16x32_bf16 v[90:93], v[176:179], v[216:219], v[90:93]
	v_mfma_f32_16x16x32_bf16 v[78:81], v[144:147], v[224:227], v[78:81]
	v_mfma_f32_16x16x32_bf16 v[74:77], v[176:179], v[224:227], v[74:77]
	s_barrier
	s_add_i32 s54, 0, 0x14000
	s_add_i32 s6, s53, s13
	v_add_u32_e32 v139, s54, v148
	v_lshl_add_u64 v[154:155], s[36:37], 0, v[132:133]
	s_mov_b32 m0, s6
	ds_read_b128 v[228:231], v139
	ds_read_b128 v[232:235], v139 offset:1024
	ds_read_b128 v[236:239], v139 offset:2048
	ds_read_b128 v[240:243], v139 offset:3072
	global_load_lds_dwordx4 v[154:155], off
	v_lshl_add_u64 v[212:213], s[36:37], 0, v[130:131]
	s_add_i32 m0, s6, 0x2000
	s_nop 0
	global_load_lds_dwordx4 v[212:213], off
	s_barrier
	s_waitcnt lgkmcnt(0)
	s_waitcnt lgkmcnt(0)
	v_mfma_f32_16x16x32_bf16 v[118:121], v[228:231], v[180:183], v[118:121]
	v_mfma_f32_16x16x32_bf16 v[114:117], v[236:239], v[180:183], v[114:117]
	v_mfma_f32_16x16x32_bf16 v[102:105], v[228:231], v[188:191], v[102:105]
	v_mfma_f32_16x16x32_bf16 v[98:101], v[236:239], v[188:191], v[98:101]
	v_mfma_f32_16x16x32_bf16 v[86:89], v[228:231], v[196:199], v[86:89]
	v_mfma_f32_16x16x32_bf16 v[82:85], v[236:239], v[196:199], v[82:85]
	v_mfma_f32_16x16x32_bf16 v[70:73], v[228:231], v[220:223], v[70:73]
	v_mfma_f32_16x16x32_bf16 v[66:69], v[236:239], v[220:223], v[66:69]
	v_mfma_f32_16x16x32_bf16 v[118:121], v[232:235], v[184:187], v[118:121]
	v_mfma_f32_16x16x32_bf16 v[114:117], v[240:243], v[184:187], v[114:117]
	v_mfma_f32_16x16x32_bf16 v[102:105], v[232:235], v[192:195], v[102:105]
	v_mfma_f32_16x16x32_bf16 v[98:101], v[240:243], v[192:195], v[98:101]
	v_mfma_f32_16x16x32_bf16 v[86:89], v[232:235], v[216:219], v[86:89]
	v_mfma_f32_16x16x32_bf16 v[82:85], v[240:243], v[216:219], v[82:85]
	v_mfma_f32_16x16x32_bf16 v[70:73], v[232:235], v[224:227], v[70:73]
	v_mfma_f32_16x16x32_bf16 v[66:69], v[240:243], v[224:227], v[66:69]
	s_mov_b32 m0, s15
	v_lshl_add_u64 v[244:245], s[42:43], 0, v[132:133]
	s_barrier
	ds_read_b128 v[180:183], v149 offset:16384
	ds_read_b128 v[184:187], v149 offset:17408
	ds_read_b128 v[188:191], v149 offset:18432
	ds_read_b128 v[192:195], v149 offset:19456
	ds_read_b128 v[196:199], v149 offset:20480
	ds_read_b128 v[216:219], v149 offset:21504
	ds_read_b128 v[220:223], v149 offset:22528
	ds_read_b128 v[224:227], v149 offset:23552
	global_load_lds_dwordx4 v[244:245], off
	v_lshl_add_u64 v[246:247], s[42:43], 0, v[130:131]
	s_mov_b32 m0, s16
	s_nop 0
	global_load_lds_dwordx4 v[246:247], off
	s_barrier
	s_waitcnt lgkmcnt(0)
	s_waitcnt lgkmcnt(0)
	v_mfma_f32_16x16x32_bf16 v[62:65], v[140:143], v[180:183], v[62:65]
	v_mfma_f32_16x16x32_bf16 v[58:61], v[150:153], v[180:183], v[58:61]
	v_mfma_f32_16x16x32_bf16 v[46:49], v[140:143], v[188:191], v[46:49]
	v_mfma_f32_16x16x32_bf16 v[42:45], v[150:153], v[188:191], v[42:45]
	v_mfma_f32_16x16x32_bf16 v[30:33], v[140:143], v[196:199], v[30:33]
	v_mfma_f32_16x16x32_bf16 v[26:29], v[150:153], v[196:199], v[26:29]
	v_mfma_f32_16x16x32_bf16 v[14:17], v[140:143], v[220:223], v[14:17]
	v_mfma_f32_16x16x32_bf16 v[10:13], v[150:153], v[220:223], v[10:13]
	v_mfma_f32_16x16x32_bf16 v[62:65], v[144:147], v[184:187], v[62:65]
	v_mfma_f32_16x16x32_bf16 v[58:61], v[176:179], v[184:187], v[58:61]
	v_mfma_f32_16x16x32_bf16 v[46:49], v[144:147], v[192:195], v[46:49]
	v_mfma_f32_16x16x32_bf16 v[42:45], v[176:179], v[192:195], v[42:45]
	v_mfma_f32_16x16x32_bf16 v[30:33], v[144:147], v[216:219], v[30:33]
	v_mfma_f32_16x16x32_bf16 v[26:29], v[176:179], v[216:219], v[26:29]
	v_mfma_f32_16x16x32_bf16 v[14:17], v[144:147], v[224:227], v[14:17]
	v_mfma_f32_16x16x32_bf16 v[10:13], v[176:179], v[224:227], v[10:13]
	s_barrier
; #define PG8_STAGE(bufoff, gbase, voff) do { _Pragma("unroll") for (int _i = 0; _i < 2; ++_i) \
;         __builtin_amdgcn_global_load_lds((const unsigned*)((const char*)(gbase) + (voff)[_i]), (LAS unsigned*)(lds + (bufoff) + ldsw + _i * 8192), 16, 0, 0); } while (0)
; #define PG8_LDA(dst, b, h) do { _Pragma("unroll") for (int m = 0; m < 4; ++m) _Pragma("unroll") for (int k = 0; k < 2; ++k) dst[m][k] = *(const LAS bf16x8*)(lds + PG8_SA(b, h) + aoff + m * 2048 + k * 1024); } while (0)
; #define PG8_LDB(dst, b, h) do { _Pragma("unroll") for (int n = 0; n < 2; ++n) _Pragma("unroll") for (int k = 0; k < 2; ++k) dst[n][k] = *(const LAS bf16x8*)(lds + PG8_SB(b, h) + boff + n * 2048 + k * 1024); } while (0)
; #define PG8_MMA(ai, bj, At, Bt) do { __builtin_amdgcn_s_setprio(1); _Pragma("unroll") for (int m = 0; m < 4; ++m) _Pragma("unroll") for (int n = 0; n < 2; ++n) _Pragma("unroll") for (int k = 0; k < 2; ++k) \
;         acc[ai][bj][m][n] = __builtin_amdgcn_mfma_f32_16x16x32_bf16(Bt[n][k], At[m][k], acc[ai][bj][m][n], 0, 0, 0); __builtin_amdgcn_s_setprio(0); } while (0)
; #define PG8_WAIT_V(n) asm volatile("s_waitcnt vmcnt(" #n ")" ::: "memory")
; #define PG8_WAIT_L(n) asm volatile("s_waitcnt lgkmcnt(" #n ")" ::: "memory")
; #define PG8_BAR __builtin_amdgcn_s_barrier()
; #define PG8_SCHED __builtin_amdgcn_sched_barrier(0)
; template <class Epi>
; __device__ __forceinline__ void gemm_phase(LAS unsigned char* lds, const Gemm g, const StaticOrder& S, const Epi& E) {
;     ...
;             PG8_STAGE(PG8_SB(0, 1), b2 + hstepB, voffB);
;             PG8_WAIT_V(6); PG8_BAR; PG8_MMA(1, 1, At, B1); PG8_BAR;
;             PG8_LDB(B0, 1, 0); PG8_SCHED; PG8_LDA(At, 1, 0); PG8_STAGE(PG8_SA(0, 1), a2 + hstepA, voffA);
;             PG8_WAIT_L(8); PG8_BAR; PG8_WAIT_L(0); PG8_MMA(0, 0, At, B0); PG8_BAR; PG8_SCHED;
;             PG8_LDB(B1, 1, 1); PG8_STAGE(PG8_SB(1, 0), b3, voffB);
;             PG8_BAR; PG8_WAIT_L(0); PG8_MMA(0, 1, At, B1); PG8_BAR;
	s_add_u32 s6, s36, 0x40000
	s_addc_u32 s7, s37, 0
	s_add_i32 s53, s54, s13
	v_lshl_add_u64 v[140:141], s[6:7], 0, v[132:133]
	s_mov_b32 m0, s53
	s_nop 0
	global_load_lds_dwordx4 v[140:141], off
	v_lshl_add_u64 v[140:141], s[6:7], 0, v[130:131]
	s_add_i32 m0, s53, 0x2000
	s_nop 0
	global_load_lds_dwordx4 v[140:141], off
	s_waitcnt vmcnt(6)
	s_barrier
	v_mfma_f32_16x16x32_bf16 v[54:57], v[228:231], v[180:183], v[54:57]
	v_mfma_f32_16x16x32_bf16 v[50:53], v[236:239], v[180:183], v[50:53]
	v_mfma_f32_16x16x32_bf16 v[38:41], v[228:231], v[188:191], v[38:41]
	v_mfma_f32_16x16x32_bf16 v[34:37], v[236:239], v[188:191], v[34:37]
	v_mfma_f32_16x16x32_bf16 v[22:25], v[228:231], v[196:199], v[22:25]
	v_mfma_f32_16x16x32_bf16 v[18:21], v[236:239], v[196:199], v[18:21]
	v_mfma_f32_16x16x32_bf16 v[6:9], v[228:231], v[220:223], v[6:9]
	v_mfma_f32_16x16x32_bf16 v[2:5], v[236:239], v[220:223], v[2:5]
	v_mfma_f32_16x16x32_bf16 v[54:57], v[232:235], v[184:187], v[54:57]
	v_mfma_f32_16x16x32_bf16 v[50:53], v[240:243], v[184:187], v[50:53]
	v_mfma_f32_16x16x32_bf16 v[38:41], v[232:235], v[192:195], v[38:41]
	v_mfma_f32_16x16x32_bf16 v[34:37], v[240:243], v[192:195], v[34:37]
	v_mfma_f32_16x16x32_bf16 v[22:25], v[232:235], v[216:219], v[22:25]
	v_mfma_f32_16x16x32_bf16 v[18:21], v[240:243], v[216:219], v[18:21]
	v_mfma_f32_16x16x32_bf16 v[6:9], v[232:235], v[224:227], v[6:9]
	v_mfma_f32_16x16x32_bf16 v[2:5], v[240:243], v[224:227], v[2:5]
	s_add_i32 s53, 0, 0x18000
	v_add_u32_e32 v139, s53, v148
	s_barrier
	ds_read_b128 v[140:143], v139
	ds_read_b128 v[144:147], v139 offset:1024
	ds_read_b128 v[150:153], v139 offset:2048
	ds_read_b128 v[176:179], v139 offset:3072
	s_add_u32 s6, s42, 0x40000
	s_addc_u32 s7, s43, 0
	s_mov_b32 m0, s17
	v_lshl_add_u64 v[228:229], s[6:7], 0, v[132:133]
	ds_read_b128 v[180:183], v149 offset:32768
	ds_read_b128 v[184:187], v149 offset:33792
	ds_read_b128 v[188:191], v149 offset:34816
	ds_read_b128 v[192:195], v149 offset:35840
	ds_read_b128 v[196:199], v149 offset:36864
	ds_read_b128 v[216:219], v149 offset:37888
	ds_read_b128 v[220:223], v149 offset:38912
	ds_read_b128 v[224:227], v149 offset:39936
	global_load_lds_dwordx4 v[228:229], off
	v_lshl_add_u64 v[228:229], s[6:7], 0, v[130:131]
	s_mov_b32 m0, s33
	s_nop 0
	global_load_lds_dwordx4 v[228:229], off
	s_waitcnt lgkmcnt(8)
	s_barrier
	s_waitcnt lgkmcnt(0)
	s_waitcnt lgkmcnt(0)
	v_mfma_f32_16x16x32_bf16 v[126:129], v[140:143], v[180:183], v[126:129]
	v_mfma_f32_16x16x32_bf16 v[122:125], v[150:153], v[180:183], v[122:125]
	v_mfma_f32_16x16x32_bf16 v[110:113], v[140:143], v[188:191], v[110:113]
	v_mfma_f32_16x16x32_bf16 v[106:109], v[150:153], v[188:191], v[106:109]
	v_mfma_f32_16x16x32_bf16 v[94:97], v[140:143], v[196:199], v[94:97]
	v_mfma_f32_16x16x32_bf16 v[90:93], v[150:153], v[196:199], v[90:93]
	v_mfma_f32_16x16x32_bf16 v[78:81], v[140:143], v[220:223], v[78:81]
	v_mfma_f32_16x16x32_bf16 v[74:77], v[150:153], v[220:223], v[74:77]
	v_mfma_f32_16x16x32_bf16 v[126:129], v[144:147], v[184:187], v[126:129]
	v_mfma_f32_16x16x32_bf16 v[122:125], v[176:179], v[184:187], v[122:125]
	v_mfma_f32_16x16x32_bf16 v[110:113], v[144:147], v[192:195], v[110:113]
	v_mfma_f32_16x16x32_bf16 v[106:109], v[176:179], v[192:195], v[106:109]
	v_mfma_f32_16x16x32_bf16 v[94:97], v[144:147], v[216:219], v[94:97]
	v_mfma_f32_16x16x32_bf16 v[90:93], v[176:179], v[216:219], v[90:93]
	v_mfma_f32_16x16x32_bf16 v[78:81], v[144:147], v[224:227], v[78:81]
	v_mfma_f32_16x16x32_bf16 v[74:77], v[176:179], v[224:227], v[74:77]
	s_barrier
	s_add_i32 s42, 0, 0x1c000
	s_add_i32 s6, s53, s13
	v_add_u32_e32 v139, s42, v148
	v_lshl_add_u64 v[154:155], v[154:155], 0, s[88:89]
	s_mov_b32 m0, s6
	ds_read_b128 v[228:231], v139
	ds_read_b128 v[232:235], v139 offset:1024
	ds_read_b128 v[236:239], v139 offset:2048
	ds_read_b128 v[240:243], v139 offset:3072
	global_load_lds_dwordx4 v[154:155], off
	v_lshl_add_u64 v[154:155], v[212:213], 0, s[88:89]
	s_add_i32 m0, s6, 0x2000
	s_nop 0
	global_load_lds_dwordx4 v[154:155], off
	s_barrier
	s_waitcnt lgkmcnt(0)
	s_waitcnt lgkmcnt(0)
	v_mfma_f32_16x16x32_bf16 v[118:121], v[228:231], v[180:183], v[118:121]
	v_mfma_f32_16x16x32_bf16 v[114:117], v[236:239], v[180:183], v[114:117]
	v_mfma_f32_16x16x32_bf16 v[102:105], v[228:231], v[188:191], v[102:105]
	v_mfma_f32_16x16x32_bf16 v[98:101], v[236:239], v[188:191], v[98:101]
	v_mfma_f32_16x16x32_bf16 v[86:89], v[228:231], v[196:199], v[86:89]
	v_mfma_f32_16x16x32_bf16 v[82:85], v[236:239], v[196:199], v[82:85]
	v_mfma_f32_16x16x32_bf16 v[70:73], v[228:231], v[220:223], v[70:73]
	v_mfma_f32_16x16x32_bf16 v[66:69], v[236:239], v[220:223], v[66:69]
	v_mfma_f32_16x16x32_bf16 v[118:121], v[232:235], v[184:187], v[118:121]
	v_mfma_f32_16x16x32_bf16 v[114:117], v[240:243], v[184:187], v[114:117]
	v_mfma_f32_16x16x32_bf16 v[102:105], v[232:235], v[192:195], v[102:105]
	v_mfma_f32_16x16x32_bf16 v[98:101], v[240:243], v[192:195], v[98:101]
	v_mfma_f32_16x16x32_bf16 v[86:89], v[232:235], v[216:219], v[86:89]
	v_mfma_f32_16x16x32_bf16 v[82:85], v[240:243], v[216:219], v[82:85]
	v_mfma_f32_16x16x32_bf16 v[70:73], v[232:235], v[224:227], v[70:73]
	v_mfma_f32_16x16x32_bf16 v[66:69], v[240:243], v[224:227], v[66:69]
	s_mov_b32 m0, s44
	v_lshl_add_u64 v[154:155], v[244:245], 0, s[88:89]
	s_barrier
	ds_read_b128 v[180:183], v149 offset:49152
	ds_read_b128 v[184:187], v149 offset:50176
	ds_read_b128 v[188:191], v149 offset:51200
	ds_read_b128 v[192:195], v149 offset:52224
	ds_read_b128 v[196:199], v149 offset:53248
	ds_read_b128 v[216:219], v149 offset:54272
	ds_read_b128 v[220:223], v149 offset:55296
	ds_read_b128 v[224:227], v149 offset:56320
	global_load_lds_dwordx4 v[154:155], off
	v_lshl_add_u64 v[154:155], v[246:247], 0, s[88:89]
	s_mov_b32 m0, s45
	s_nop 0
	global_load_lds_dwordx4 v[154:155], off
	s_barrier
; __device__ __forceinline__ unsigned pk2(float lo, float hi) { unsigned r; asm volatile("v_cvt_pk_bf16_f32 %0, %1, %2" : "=v"(r) : "v"(lo), "v"(hi)); return r; }
; #define PG8_STAGE(bufoff, gbase, voff) do { _Pragma("unroll") for (int _i = 0; _i < 2; ++_i) \
;         __builtin_amdgcn_global_load_lds((const unsigned*)((const char*)(gbase) + (voff)[_i]), (LAS unsigned*)(lds + (bufoff) + ldsw + _i * 8192), 16, 0, 0); } while (0)
; #define PG8_LDA(dst, b, h) do { _Pragma("unroll") for (int m = 0; m < 4; ++m) _Pragma("unroll") for (int k = 0; k < 2; ++k) dst[m][k] = *(const LAS bf16x8*)(lds + PG8_SA(b, h) + aoff + m * 2048 + k * 1024); } while (0)
; #define PG8_WAIT_V(n) asm volatile("s_waitcnt vmcnt(" #n ")" ::: "memory")
; #define PG8_WAIT_L(n) asm volatile("s_waitcnt lgkmcnt(" #n ")" ::: "memory")
; template <class Epi>
; __device__ __forceinline__ void gemm_phase(LAS unsigned char* lds, const Gemm g, const StaticOrder& S, const Epi& E) {
;     ...
;             PG8_LDA(At, 1, 1); PG8_STAGE(PG8_SA(1, 0), a3, voffA);
;             PG8_BAR; PG8_WAIT_L(0); PG8_MMA(1, 0, At, B0); PG8_BAR; PG8_SCHED;
;             PG8_STAGE(PG8_SB(1, 1), b3 + hstepB, voffB);
;             PG8_WAIT_V(6); PG8_BAR; PG8_MMA(1, 1, At, B1); PG8_BAR;
;     __device__ __forceinline__ void operator()(const f32x4 (&acc)[2][2][4][2], const Unit& u, int wr, int wc, int fr, int fq) const {
;         const int rowb = u.pm * 256 + wr * 64 + fr, colb = u.pn * 256 + wc * 32 + fq * 4;
;         float rs[2][4];
; #pragma unroll
;         for (int ai = 0; ai < 2; ++ai)
; #pragma unroll
;             for (int m = 0; m < 4; ++m) rs[ai][m] = ssq[rowb + ai * 128 + m * 16];
; #pragma unroll
;         for (int ai = 0; ai < 2; ++ai)
; #pragma unroll
;             for (int m = 0; m < 4; ++m) { bf16_t* rp = ACT + (size_t)(rowb + ai * 128 + m * 16) * 4096 + u.pn * 256 + wc * 32 + fq * 8; const float r_ = rsqrtf(rs[ai][m] * (1.f / 1024.f) + EPS);
; #pragma unroll
;                 for (int bj = 0; bj < 2; ++bj) { f32x4 v0 = acc[ai][bj][m][0], v1 = acc[ai][bj][m][1];
; #pragma unroll
;                     for (int j = 0; j < 4; ++j) { const float r0 = fmaxf(v0[j] * r_, 0.f), r1 = fmaxf(v1[j] * r_, 0.f); v0[j] = r0 * r0; v1[j] = r1 * r1; }
;                     u32x4 o; o[0] = pk2(v0[0], v0[1]); o[1] = pk2(v0[2], v0[3]); o[2] = pk2(v1[0], v1[1]); o[3] = pk2(v1[2], v1[3]); *(u32x4*)(rp + bj * 128) = o; } }
	s_waitcnt lgkmcnt(0)
	s_waitcnt lgkmcnt(0)
	v_mfma_f32_16x16x32_bf16 v[62:65], v[140:143], v[180:183], v[62:65]
	v_mfma_f32_16x16x32_bf16 v[58:61], v[150:153], v[180:183], v[58:61]
	v_mfma_f32_16x16x32_bf16 v[46:49], v[140:143], v[188:191], v[46:49]
	v_mfma_f32_16x16x32_bf16 v[42:45], v[150:153], v[188:191], v[42:45]
	v_mfma_f32_16x16x32_bf16 v[30:33], v[140:143], v[196:199], v[30:33]
	v_mfma_f32_16x16x32_bf16 v[26:29], v[150:153], v[196:199], v[26:29]
	v_mfma_f32_16x16x32_bf16 v[14:17], v[140:143], v[220:223], v[14:17]
	v_mfma_f32_16x16x32_bf16 v[10:13], v[150:153], v[220:223], v[10:13]
	v_mfma_f32_16x16x32_bf16 v[62:65], v[144:147], v[184:187], v[62:65]
	v_mfma_f32_16x16x32_bf16 v[58:61], v[176:179], v[184:187], v[58:61]
	v_mfma_f32_16x16x32_bf16 v[46:49], v[144:147], v[192:195], v[46:49]
	v_mfma_f32_16x16x32_bf16 v[42:45], v[176:179], v[192:195], v[42:45]
	v_mfma_f32_16x16x32_bf16 v[30:33], v[144:147], v[216:219], v[30:33]
	v_mfma_f32_16x16x32_bf16 v[26:29], v[176:179], v[216:219], v[26:29]
	v_mfma_f32_16x16x32_bf16 v[14:17], v[144:147], v[224:227], v[14:17]
	v_mfma_f32_16x16x32_bf16 v[10:13], v[176:179], v[224:227], v[10:13]
	s_barrier
	s_add_u32 s6, s36, 0x40080
	s_addc_u32 s7, s37, 0
	s_add_i32 s36, s42, s13
	v_lshl_add_u64 v[140:141], s[6:7], 0, v[132:133]
	s_mov_b32 m0, s36
	s_nop 0
	global_load_lds_dwordx4 v[140:141], off
	v_lshl_add_u64 v[140:141], s[6:7], 0, v[130:131]
	s_add_i32 m0, s36, 0x2000
	s_nop 0
	global_load_lds_dwordx4 v[140:141], off
	s_waitcnt vmcnt(6)
	s_barrier
	v_mfma_f32_16x16x32_bf16 v[54:57], v[228:231], v[180:183], v[54:57]
	v_mfma_f32_16x16x32_bf16 v[50:53], v[236:239], v[180:183], v[50:53]
	v_mfma_f32_16x16x32_bf16 v[38:41], v[228:231], v[188:191], v[38:41]
	v_mfma_f32_16x16x32_bf16 v[34:37], v[236:239], v[188:191], v[34:37]
	v_mfma_f32_16x16x32_bf16 v[22:25], v[228:231], v[196:199], v[22:25]
	v_mfma_f32_16x16x32_bf16 v[18:21], v[236:239], v[196:199], v[18:21]
	v_mfma_f32_16x16x32_bf16 v[6:9], v[228:231], v[220:223], v[6:9]
	v_mfma_f32_16x16x32_bf16 v[2:5], v[236:239], v[220:223], v[2:5]
	v_mfma_f32_16x16x32_bf16 v[54:57], v[232:235], v[184:187], v[54:57]
	v_mfma_f32_16x16x32_bf16 v[50:53], v[240:243], v[184:187], v[50:53]
	v_mfma_f32_16x16x32_bf16 v[38:41], v[232:235], v[192:195], v[38:41]
	v_mfma_f32_16x16x32_bf16 v[34:37], v[240:243], v[192:195], v[34:37]
	v_mfma_f32_16x16x32_bf16 v[22:25], v[232:235], v[216:219], v[22:25]
	v_mfma_f32_16x16x32_bf16 v[18:21], v[240:243], v[216:219], v[18:21]
	v_mfma_f32_16x16x32_bf16 v[6:9], v[232:235], v[224:227], v[6:9]
	v_mfma_f32_16x16x32_bf16 v[2:5], v[240:243], v[224:227], v[2:5]
	s_add_i32 s52, s52, 2
	s_add_u32 s34, s34, 0x100
	s_addc_u32 s35, s35, 0
	s_add_u32 s50, s50, 0x100
	s_addc_u32 s51, s51, 0
	s_cmp_gt_u32 s52, 13
	s_barrier
	s_cbranch_scc0 .LBB0_102
	v_lshl_add_u32 v140, s30, 8, v1
	v_ashrrev_i32_e32 v141, 31, v140
	v_lshl_add_u64 v[176:177], v[140:141], 2, s[18:19]
	global_load_dword v158, v[176:177], off
	global_load_dword v157, v[176:177], off offset:64
	global_load_dword v155, v[176:177], off offset:128
	global_load_dword v154, v[176:177], off offset:192
	global_load_dword v153, v[176:177], off offset:512
	global_load_dword v152, v[176:177], off offset:576
	global_load_dword v151, v[176:177], off offset:640
	global_load_dword v150, v[176:177], off offset:704
	s_lshl_b32 s6, s31, 8
	v_readlane_b32 s34, v255, 32
	v_or_b32_e32 v146, 16, v140
	v_or_b32_e32 v144, 32, v140
	v_or_b32_e32 v142, 48, v140
	s_ashr_i32 s7, s6, 31
	v_lshlrev_b64 v[140:141], 13, v[140:141]
	v_readlane_b32 s35, v255, 33
	s_lshl_b64 s[30:31], s[6:7], 1
	v_mov_b32_e32 v139, v0
	v_lshl_add_u64 v[140:141], s[34:35], 0, v[140:141]
	v_lshl_add_u64 v[140:141], v[140:141], 0, s[30:31]
	v_lshl_add_u64 v[140:141], v[140:141], 0, s[84:85]
	v_lshl_add_u64 v[140:141], v[140:141], 0, v[138:139]
	v_ashrrev_i32_e32 v147, 31, v146
	v_ashrrev_i32_e32 v145, 31, v144
	v_ashrrev_i32_e32 v143, 31, v142
	s_mov_b64 s[6:7], 0x100000
	s_mov_b64 s[36:37], s[28:29]
	s_waitcnt vmcnt(0)
	v_fmamk_f32 v158, v158, 0x3a800000, v202
	v_cmp_gt_f32_e32 vcc, s38, v158
	v_mul_f32_e32 v171, 0x4b800000, v158
	s_nop 0
	v_cndmask_b32_e32 v158, v158, v171, vcc
	v_rsq_f32_e32 v158, v158
	s_nop 0
	v_mul_f32_e32 v171, 0x45800000, v158
	v_cndmask_b32_e32 v158, v158, v171, vcc
	v_mul_f32_e32 v122, v122, v158
	v_max_f32_e32 v122, 0, v122
	v_mul_f32_e32 v123, v123, v158
	v_mul_f32_e32 v124, v124, v158
	v_mul_f32_e32 v171, v122, v122
	v_mul_f32_e32 v122, v127, v158
	v_max_f32_e32 v123, 0, v123
	v_max_f32_e32 v124, 0, v124
	v_mul_f32_e32 v126, v126, v158
	v_max_f32_e32 v122, 0, v122
	v_mul_f32_e32 v127, v123, v123
	v_mul_f32_e32 v123, v128, v158
	v_mul_f32_e32 v128, v124, v124
	v_mul_f32_e32 v124, v129, v158
	v_mul_f32_e32 v125, v125, v158
	v_max_f32_e32 v126, 0, v126
	v_mul_f32_e32 v122, v122, v122
	v_max_f32_e32 v123, 0, v123
	v_max_f32_e32 v124, 0, v124
	v_max_f32_e32 v125, 0, v125
	v_mul_f32_e32 v114, v114, v158
	v_mul_f32_e32 v115, v115, v158
	v_mul_f32_e32 v116, v116, v158
	v_mul_f32_e32 v126, v126, v126
	v_mul_f32_e32 v123, v123, v123
	v_mul_f32_e32 v124, v124, v124
	v_mul_f32_e32 v125, v125, v125
	v_cvt_pk_bf16_f32 v122, v126, v122
	v_max_f32_e32 v114, 0, v114
	v_max_f32_e32 v115, 0, v115
	v_max_f32_e32 v116, 0, v116
	v_cvt_pk_bf16_f32 v123, v123, v124
	v_cvt_pk_bf16_f32 v124, v171, v127
	v_cvt_pk_bf16_f32 v125, v128, v125
	global_store_dwordx4 v[140:141], v[122:125], off
	v_mul_f32_e32 v118, v118, v158
	v_mul_f32_e32 v117, v117, v158
	v_mul_f32_e32 v122, v114, v114
	v_mul_f32_e32 v114, v119, v158
	v_mul_f32_e32 v119, v115, v115
	v_mul_f32_e32 v115, v120, v158
	v_mul_f32_e32 v120, v116, v116
	v_mul_f32_e32 v116, v121, v158
; __device__ __forceinline__ unsigned pk2(float lo, float hi) { unsigned r; asm volatile("v_cvt_pk_bf16_f32 %0, %1, %2" : "=v"(r) : "v"(lo), "v"(hi)); return r; }
;     __device__ __forceinline__ void operator()(const f32x4 (&acc)[2][2][4][2], const Unit& u, int wr, int wc, int fr, int fq) const {
;     ...
;         for (int ai = 0; ai < 2; ++ai)
; #pragma unroll
;             for (int m = 0; m < 4; ++m) { bf16_t* rp = ACT + (size_t)(rowb + ai * 128 + m * 16) * 4096 + u.pn * 256 + wc * 32 + fq * 8; const float r_ = rsqrtf(rs[ai][m] * (1.f / 1024.f) + EPS);
; #pragma unroll
;                 for (int bj = 0; bj < 2; ++bj) { f32x4 v0 = acc[ai][bj][m][0], v1 = acc[ai][bj][m][1];
; #pragma unroll
;                     for (int j = 0; j < 4; ++j) { const float r0 = fmaxf(v0[j] * r_, 0.f), r1 = fmaxf(v1[j] * r_, 0.f); v0[j] = r0 * r0; v1[j] = r1 * r1; }
;                     u32x4 o; o[0] = pk2(v0[0], v0[1]); o[1] = pk2(v0[2], v0[3]); o[2] = pk2(v1[0], v1[1]); o[3] = pk2(v1[2], v1[3]); *(u32x4*)(rp + bj * 128) = o; } }
	v_max_f32_e32 v114, 0, v114
	v_max_f32_e32 v115, 0, v115
	v_max_f32_e32 v116, 0, v116
	v_max_f32_e32 v118, 0, v118
	v_mul_f32_e32 v114, v114, v114
	v_mul_f32_e32 v115, v115, v115
	v_max_f32_e32 v117, 0, v117
	v_mul_f32_e32 v116, v116, v116
	v_mul_f32_e32 v118, v118, v118
	v_mul_f32_e32 v117, v117, v117
	v_cvt_pk_bf16_f32 v114, v118, v114
	v_cvt_pk_bf16_f32 v115, v115, v116
	v_cvt_pk_bf16_f32 v116, v122, v119
	v_cvt_pk_bf16_f32 v117, v120, v117
	global_store_dwordx4 v[140:141], v[114:117], off offset:256
	s_nop 1
	v_fmamk_f32 v116, v157, 0x3a800000, v202
	v_cmp_gt_f32_e32 vcc, s38, v116
	v_mul_f32_e32 v117, 0x4b800000, v116
	v_lshlrev_b64 v[114:115], 13, v[146:147]
	v_cndmask_b32_e32 v116, v116, v117, vcc
	v_rsq_f32_e32 v116, v116
	v_lshl_add_u64 v[114:115], s[34:35], 0, v[114:115]
	v_lshl_add_u64 v[114:115], v[114:115], 0, s[30:31]
	v_lshl_add_u64 v[114:115], v[114:115], 0, s[84:85]
	v_mul_f32_e32 v117, 0x45800000, v116
	v_cndmask_b32_e32 v116, v116, v117, vcc
	v_mul_f32_e32 v106, v106, v116
	v_max_f32_e32 v106, 0, v106
	v_mul_f32_e32 v107, v107, v116
	v_mul_f32_e32 v108, v108, v116
	v_mul_f32_e32 v117, v106, v106
	v_mul_f32_e32 v106, v111, v116
	v_max_f32_e32 v107, 0, v107
	v_max_f32_e32 v108, 0, v108
	v_mul_f32_e32 v110, v110, v116
	v_max_f32_e32 v106, 0, v106
	v_mul_f32_e32 v111, v107, v107
	v_mul_f32_e32 v107, v112, v116
	v_mul_f32_e32 v112, v108, v108
	v_mul_f32_e32 v108, v113, v116
	v_mul_f32_e32 v109, v109, v116
	v_max_f32_e32 v110, 0, v110
	v_mul_f32_e32 v106, v106, v106
	v_max_f32_e32 v107, 0, v107
	v_max_f32_e32 v108, 0, v108
	v_max_f32_e32 v109, 0, v109
	v_mul_f32_e32 v98, v98, v116
	v_mul_f32_e32 v99, v99, v116
	v_mul_f32_e32 v100, v100, v116
	v_lshl_add_u64 v[114:115], v[114:115], 0, v[138:139]
	v_mul_f32_e32 v110, v110, v110
	v_mul_f32_e32 v107, v107, v107
	v_mul_f32_e32 v108, v108, v108
	v_mul_f32_e32 v109, v109, v109
	v_cvt_pk_bf16_f32 v106, v110, v106
	v_max_f32_e32 v98, 0, v98
	v_max_f32_e32 v99, 0, v99
	v_max_f32_e32 v100, 0, v100
	v_cvt_pk_bf16_f32 v107, v107, v108
	v_cvt_pk_bf16_f32 v108, v117, v111
	v_cvt_pk_bf16_f32 v109, v112, v109
	global_store_dwordx4 v[114:115], v[106:109], off
	v_mul_f32_e32 v102, v102, v116
	v_mul_f32_e32 v101, v101, v116
	v_mul_f32_e32 v106, v98, v98
	v_mul_f32_e32 v98, v103, v116
	v_mul_f32_e32 v103, v99, v99
	v_mul_f32_e32 v99, v104, v116
	v_mul_f32_e32 v104, v100, v100
	v_mul_f32_e32 v100, v105, v116
	v_max_f32_e32 v98, 0, v98
	v_max_f32_e32 v99, 0, v99
	v_max_f32_e32 v100, 0, v100
	v_max_f32_e32 v102, 0, v102
	v_mul_f32_e32 v98, v98, v98
	v_mul_f32_e32 v99, v99, v99
	v_max_f32_e32 v101, 0, v101
	v_mul_f32_e32 v100, v100, v100
	v_mul_f32_e32 v102, v102, v102
	v_mul_f32_e32 v101, v101, v101
	v_cvt_pk_bf16_f32 v98, v102, v98
	v_cvt_pk_bf16_f32 v99, v99, v100
	v_cvt_pk_bf16_f32 v100, v106, v103
	v_cvt_pk_bf16_f32 v101, v104, v101
	global_store_dwordx4 v[114:115], v[98:101], off offset:256
	s_nop 1
	v_fmamk_f32 v100, v155, 0x3a800000, v202
	v_cmp_gt_f32_e32 vcc, s38, v100
	v_mul_f32_e32 v101, 0x4b800000, v100
	v_lshlrev_b64 v[98:99], 13, v[144:145]
	v_cndmask_b32_e32 v100, v100, v101, vcc
	v_rsq_f32_e32 v100, v100
	v_lshl_add_u64 v[98:99], s[34:35], 0, v[98:99]
	v_lshl_add_u64 v[98:99], v[98:99], 0, s[30:31]
	v_lshl_add_u64 v[98:99], v[98:99], 0, s[84:85]
	v_mul_f32_e32 v101, 0x45800000, v100
	v_cndmask_b32_e32 v100, v100, v101, vcc
	v_mul_f32_e32 v90, v90, v100
	v_max_f32_e32 v90, 0, v90
	v_mul_f32_e32 v91, v91, v100
	v_mul_f32_e32 v92, v92, v100
	v_mul_f32_e32 v101, v90, v90
	v_mul_f32_e32 v90, v95, v100
	v_max_f32_e32 v91, 0, v91
	v_max_f32_e32 v92, 0, v92
	v_mul_f32_e32 v94, v94, v100
	v_max_f32_e32 v90, 0, v90
	v_mul_f32_e32 v95, v91, v91
	v_mul_f32_e32 v91, v96, v100
	v_mul_f32_e32 v96, v92, v92
	v_mul_f32_e32 v92, v97, v100
	v_mul_f32_e32 v93, v93, v100
	v_max_f32_e32 v94, 0, v94
	v_mul_f32_e32 v90, v90, v90
	v_max_f32_e32 v91, 0, v91
	v_max_f32_e32 v92, 0, v92
	v_max_f32_e32 v93, 0, v93
	v_mul_f32_e32 v82, v82, v100
	v_mul_f32_e32 v83, v83, v100
	v_mul_f32_e32 v84, v84, v100
	v_lshl_add_u64 v[98:99], v[98:99], 0, v[138:139]
	v_mul_f32_e32 v94, v94, v94
	v_mul_f32_e32 v91, v91, v91
	v_mul_f32_e32 v92, v92, v92
	v_mul_f32_e32 v93, v93, v93
	v_cvt_pk_bf16_f32 v90, v94, v90
	v_max_f32_e32 v82, 0, v82
	v_max_f32_e32 v83, 0, v83
	v_max_f32_e32 v84, 0, v84
	v_cvt_pk_bf16_f32 v91, v91, v92
	v_cvt_pk_bf16_f32 v92, v101, v95
	v_cvt_pk_bf16_f32 v93, v96, v93
	global_store_dwordx4 v[98:99], v[90:93], off
	v_mul_f32_e32 v86, v86, v100
	v_mul_f32_e32 v85, v85, v100
	v_mul_f32_e32 v90, v82, v82
	v_mul_f32_e32 v82, v87, v100
	v_mul_f32_e32 v87, v83, v83
	v_mul_f32_e32 v83, v88, v100
	v_mul_f32_e32 v88, v84, v84
	v_mul_f32_e32 v84, v89, v100
	v_max_f32_e32 v82, 0, v82
	v_max_f32_e32 v83, 0, v83
	v_max_f32_e32 v84, 0, v84
	v_max_f32_e32 v86, 0, v86
	v_mul_f32_e32 v82, v82, v82
	v_mul_f32_e32 v83, v83, v83
	v_max_f32_e32 v85, 0, v85
	v_mul_f32_e32 v84, v84, v84
	v_mul_f32_e32 v86, v86, v86
	v_mul_f32_e32 v85, v85, v85
	v_cvt_pk_bf16_f32 v82, v86, v82
	v_cvt_pk_bf16_f32 v83, v83, v84
	v_cvt_pk_bf16_f32 v84, v90, v87
	v_cvt_pk_bf16_f32 v85, v88, v85
	global_store_dwordx4 v[98:99], v[82:85], off offset:256
	s_nop 1
	v_fmamk_f32 v84, v154, 0x3a800000, v202
	v_cmp_gt_f32_e32 vcc, s38, v84
	v_mul_f32_e32 v85, 0x4b800000, v84
	v_lshlrev_b64 v[82:83], 13, v[142:143]
	v_cndmask_b32_e32 v84, v84, v85, vcc
	v_rsq_f32_e32 v84, v84
	v_lshl_add_u64 v[82:83], s[34:35], 0, v[82:83]
	v_lshl_add_u64 v[82:83], v[82:83], 0, s[30:31]
	v_lshl_add_u64 v[82:83], v[82:83], 0, s[84:85]
	v_mul_f32_e32 v85, 0x45800000, v84
	v_cndmask_b32_e32 v84, v84, v85, vcc
	v_mul_f32_e32 v74, v74, v84
	v_max_f32_e32 v74, 0, v74
; __device__ __forceinline__ unsigned pk2(float lo, float hi) { unsigned r; asm volatile("v_cvt_pk_bf16_f32 %0, %1, %2" : "=v"(r) : "v"(lo), "v"(hi)); return r; }
;     __device__ __forceinline__ void operator()(const f32x4 (&acc)[2][2][4][2], const Unit& u, int wr, int wc, int fr, int fq) const {
;     ...
;         for (int ai = 0; ai < 2; ++ai)
; #pragma unroll
;             for (int m = 0; m < 4; ++m) { bf16_t* rp = ACT + (size_t)(rowb + ai * 128 + m * 16) * 4096 + u.pn * 256 + wc * 32 + fq * 8; const float r_ = rsqrtf(rs[ai][m] * (1.f / 1024.f) + EPS);
; #pragma unroll
;                 for (int bj = 0; bj < 2; ++bj) { f32x4 v0 = acc[ai][bj][m][0], v1 = acc[ai][bj][m][1];
; #pragma unroll
;                     for (int j = 0; j < 4; ++j) { const float r0 = fmaxf(v0[j] * r_, 0.f), r1 = fmaxf(v1[j] * r_, 0.f); v0[j] = r0 * r0; v1[j] = r1 * r1; }
;                     u32x4 o; o[0] = pk2(v0[0], v0[1]); o[1] = pk2(v0[2], v0[3]); o[2] = pk2(v1[0], v1[1]); o[3] = pk2(v1[2], v1[3]); *(u32x4*)(rp + bj * 128) = o; } }
	v_mul_f32_e32 v75, v75, v84
	v_mul_f32_e32 v76, v76, v84
	v_mul_f32_e32 v85, v74, v74
	v_mul_f32_e32 v74, v79, v84
	v_max_f32_e32 v75, 0, v75
	v_max_f32_e32 v76, 0, v76
	v_mul_f32_e32 v78, v78, v84
	v_max_f32_e32 v74, 0, v74
	v_mul_f32_e32 v79, v75, v75
	v_mul_f32_e32 v75, v80, v84
	v_mul_f32_e32 v80, v76, v76
	v_mul_f32_e32 v76, v81, v84
	v_mul_f32_e32 v77, v77, v84
	v_max_f32_e32 v78, 0, v78
	v_mul_f32_e32 v74, v74, v74
	v_max_f32_e32 v75, 0, v75
	v_max_f32_e32 v76, 0, v76
	v_max_f32_e32 v77, 0, v77
	v_mul_f32_e32 v66, v66, v84
	v_mul_f32_e32 v67, v67, v84
	v_mul_f32_e32 v68, v68, v84
	v_lshl_add_u64 v[82:83], v[82:83], 0, v[138:139]
	v_mul_f32_e32 v78, v78, v78
	v_mul_f32_e32 v75, v75, v75
	v_mul_f32_e32 v76, v76, v76
	v_mul_f32_e32 v77, v77, v77
	v_cvt_pk_bf16_f32 v74, v78, v74
	v_max_f32_e32 v66, 0, v66
	v_max_f32_e32 v67, 0, v67
	v_max_f32_e32 v68, 0, v68
	v_cvt_pk_bf16_f32 v75, v75, v76
	v_cvt_pk_bf16_f32 v76, v85, v79
	v_cvt_pk_bf16_f32 v77, v80, v77
	global_store_dwordx4 v[82:83], v[74:77], off
	v_mul_f32_e32 v70, v70, v84
	v_mul_f32_e32 v69, v69, v84
	v_mul_f32_e32 v74, v66, v66
	v_mul_f32_e32 v66, v71, v84
	v_mul_f32_e32 v71, v67, v67
	v_mul_f32_e32 v67, v72, v84
	v_mul_f32_e32 v72, v68, v68
	v_mul_f32_e32 v68, v73, v84
	v_max_f32_e32 v66, 0, v66
	v_max_f32_e32 v67, 0, v67
	v_max_f32_e32 v68, 0, v68
	v_max_f32_e32 v70, 0, v70
	v_mul_f32_e32 v66, v66, v66
	v_mul_f32_e32 v67, v67, v67
	v_max_f32_e32 v69, 0, v69
	v_mul_f32_e32 v68, v68, v68
	v_mul_f32_e32 v70, v70, v70
	v_mul_f32_e32 v69, v69, v69
	v_cvt_pk_bf16_f32 v66, v70, v66
	v_cvt_pk_bf16_f32 v67, v67, v68
	v_cvt_pk_bf16_f32 v68, v74, v71
	v_cvt_pk_bf16_f32 v69, v72, v69
	global_store_dwordx4 v[82:83], v[66:69], off offset:256
	s_mov_b32 s31, s20
	s_mov_b32 s30, s24
	v_fmamk_f32 v68, v153, 0x3a800000, v202
	v_cmp_gt_f32_e32 vcc, s38, v68
	v_mul_f32_e32 v69, 0x4b800000, v68
	v_lshl_add_u64 v[66:67], v[140:141], 0, s[6:7]
	v_cndmask_b32_e32 v68, v68, v69, vcc
	v_rsq_f32_e32 v68, v68
	s_mov_b32 s6, 0x100000
	s_mov_b64 s[34:35], s[26:27]
	v_mul_f32_e32 v69, 0x45800000, v68
	v_cndmask_b32_e32 v68, v68, v69, vcc
	v_mul_f32_e32 v58, v58, v68
	v_max_f32_e32 v58, 0, v58
	v_mul_f32_e32 v59, v59, v68
	v_mul_f32_e32 v60, v60, v68
	v_mul_f32_e32 v62, v62, v68
	v_mul_f32_e32 v69, v58, v58
	v_mul_f32_e32 v58, v63, v68
	v_max_f32_e32 v59, 0, v59
	v_max_f32_e32 v60, 0, v60
	v_max_f32_e32 v62, 0, v62
	v_max_f32_e32 v58, 0, v58
	v_mul_f32_e32 v63, v59, v59
	v_mul_f32_e32 v59, v64, v68
	v_mul_f32_e32 v64, v60, v60
	v_mul_f32_e32 v60, v65, v68
	v_mul_f32_e32 v62, v62, v62
	v_mul_f32_e32 v58, v58, v58
	v_max_f32_e32 v59, 0, v59
	v_max_f32_e32 v60, 0, v60
	v_mul_f32_e32 v61, v61, v68
	v_mul_f32_e32 v59, v59, v59
	v_max_f32_e32 v61, 0, v61
	v_mul_f32_e32 v60, v60, v60
	v_cvt_pk_bf16_f32 v58, v62, v58
	v_add_co_u32_e32 v62, vcc, s6, v140
	v_mul_f32_e32 v50, v50, v68
	v_mul_f32_e32 v51, v51, v68
	v_mul_f32_e32 v52, v52, v68
	v_mul_f32_e32 v61, v61, v61
	v_cvt_pk_bf16_f32 v59, v59, v60
	v_cvt_pk_bf16_f32 v60, v69, v63
	v_addc_co_u32_e32 v63, vcc, 0, v141, vcc
	v_max_f32_e32 v50, 0, v50
	v_max_f32_e32 v51, 0, v51
	v_max_f32_e32 v52, 0, v52
	v_cvt_pk_bf16_f32 v61, v64, v61
	global_store_dwordx4 v[62:63], v[58:61], off
	v_mul_f32_e32 v54, v54, v68
	v_mul_f32_e32 v53, v53, v68
	v_mul_f32_e32 v58, v50, v50
	v_mul_f32_e32 v50, v55, v68
	v_mul_f32_e32 v55, v51, v51
	v_mul_f32_e32 v51, v56, v68
	v_mul_f32_e32 v56, v52, v52
	v_mul_f32_e32 v52, v57, v68
	v_max_f32_e32 v50, 0, v50
	v_max_f32_e32 v51, 0, v51
	v_max_f32_e32 v52, 0, v52
	v_max_f32_e32 v54, 0, v54
	v_mul_f32_e32 v50, v50, v50
	v_mul_f32_e32 v51, v51, v51
	v_max_f32_e32 v53, 0, v53
	v_mul_f32_e32 v52, v52, v52
	v_mul_f32_e32 v54, v54, v54
	v_mul_f32_e32 v53, v53, v53
	v_cvt_pk_bf16_f32 v50, v54, v50
	v_cvt_pk_bf16_f32 v51, v51, v52
	v_cvt_pk_bf16_f32 v52, v58, v55
	v_cvt_pk_bf16_f32 v53, v56, v53
	global_store_dwordx4 v[66:67], v[50:53], off offset:256
	s_mov_b64 s[6:7], 0x120000
	s_nop 0
	v_fmamk_f32 v52, v152, 0x3a800000, v202
	v_cmp_gt_f32_e32 vcc, s38, v52
	v_mul_f32_e32 v53, 0x4b800000, v52
	v_lshl_add_u64 v[50:51], v[140:141], 0, s[6:7]
	v_cndmask_b32_e32 v52, v52, v53, vcc
	v_rsq_f32_e32 v52, v52
	s_mov_b32 s6, 0x120000
	v_mul_f32_e32 v53, 0x45800000, v52
	v_cndmask_b32_e32 v52, v52, v53, vcc
	v_mul_f32_e32 v42, v42, v52
	v_max_f32_e32 v42, 0, v42
	v_mul_f32_e32 v43, v43, v52
	v_mul_f32_e32 v44, v44, v52
	v_mul_f32_e32 v46, v46, v52
	v_mul_f32_e32 v53, v42, v42
	v_mul_f32_e32 v42, v47, v52
	v_max_f32_e32 v43, 0, v43
	v_max_f32_e32 v44, 0, v44
	v_max_f32_e32 v46, 0, v46
	v_max_f32_e32 v42, 0, v42
	v_mul_f32_e32 v47, v43, v43
	v_mul_f32_e32 v43, v48, v52
	v_mul_f32_e32 v48, v44, v44
	v_mul_f32_e32 v44, v49, v52
	v_mul_f32_e32 v46, v46, v46
	v_mul_f32_e32 v42, v42, v42
	v_max_f32_e32 v43, 0, v43
	v_max_f32_e32 v44, 0, v44
	v_mul_f32_e32 v45, v45, v52
	v_mul_f32_e32 v43, v43, v43
	v_max_f32_e32 v45, 0, v45
	v_mul_f32_e32 v44, v44, v44
	v_cvt_pk_bf16_f32 v42, v46, v42
	v_add_co_u32_e32 v46, vcc, s6, v140
	v_mul_f32_e32 v34, v34, v52
	v_mul_f32_e32 v35, v35, v52
	v_mul_f32_e32 v36, v36, v52
	v_mul_f32_e32 v45, v45, v45
	v_cvt_pk_bf16_f32 v43, v43, v44
	v_cvt_pk_bf16_f32 v44, v53, v47
	v_addc_co_u32_e32 v47, vcc, 0, v141, vcc
	v_max_f32_e32 v34, 0, v34
; __device__ __forceinline__ unsigned pk2(float lo, float hi) { unsigned r; asm volatile("v_cvt_pk_bf16_f32 %0, %1, %2" : "=v"(r) : "v"(lo), "v"(hi)); return r; }
; #define PG8_WAIT_V(n) asm volatile("s_waitcnt vmcnt(" #n ")" ::: "memory")
; #define PG8_BAR __builtin_amdgcn_s_barrier()
; template <class Epi>
; __device__ __forceinline__ void gemm_phase(LAS unsigned char* lds, const Gemm g, const StaticOrder& S, const Epi& E) {
;     ...
;         if (!has_next) break;
; #pragma unroll
;         for (int a = 0; a < 2; ++a)
; #pragma unroll
;             for (int b = 0; b < 2; ++b)
; #pragma unroll
;                 for (int m = 0; m < 4; ++m)
; #pragma unroll
;                     for (int n = 0; n < 2; ++n) acc[a][b][m][n] = (f32x4){0.f, 0.f, 0.f, 0.f};
;         cur = nxt; cA = nA; cB = nB; ++ui;
;     }
;     PG8_WAIT_V(0);
;     if (wr == 0) PG8_BAR;
;     PG8_BAR;
;     __device__ __forceinline__ void operator()(const f32x4 (&acc)[2][2][4][2], const Unit& u, int wr, int wc, int fr, int fq) const {
;     ...
;         for (int ai = 0; ai < 2; ++ai)
; #pragma unroll
;             for (int m = 0; m < 4; ++m) { bf16_t* rp = ACT + (size_t)(rowb + ai * 128 + m * 16) * 4096 + u.pn * 256 + wc * 32 + fq * 8; const float r_ = rsqrtf(rs[ai][m] * (1.f / 1024.f) + EPS);
; #pragma unroll
;                 for (int bj = 0; bj < 2; ++bj) { f32x4 v0 = acc[ai][bj][m][0], v1 = acc[ai][bj][m][1];
; #pragma unroll
;                     for (int j = 0; j < 4; ++j) { const float r0 = fmaxf(v0[j] * r_, 0.f), r1 = fmaxf(v1[j] * r_, 0.f); v0[j] = r0 * r0; v1[j] = r1 * r1; }
;                     u32x4 o; o[0] = pk2(v0[0], v0[1]); o[1] = pk2(v0[2], v0[3]); o[2] = pk2(v1[0], v1[1]); o[3] = pk2(v1[2], v1[3]); *(u32x4*)(rp + bj * 128) = o; } }
	v_max_f32_e32 v35, 0, v35
	v_max_f32_e32 v36, 0, v36
	v_cvt_pk_bf16_f32 v45, v48, v45
	global_store_dwordx4 v[46:47], v[42:45], off
	v_mul_f32_e32 v38, v38, v52
	v_mul_f32_e32 v37, v37, v52
	v_mul_f32_e32 v42, v34, v34
	v_mul_f32_e32 v34, v39, v52
	v_mul_f32_e32 v39, v35, v35
	v_mul_f32_e32 v35, v40, v52
	v_mul_f32_e32 v40, v36, v36
	v_mul_f32_e32 v36, v41, v52
	v_max_f32_e32 v34, 0, v34
	v_max_f32_e32 v35, 0, v35
	v_max_f32_e32 v36, 0, v36
	v_max_f32_e32 v38, 0, v38
	v_mul_f32_e32 v34, v34, v34
	v_mul_f32_e32 v35, v35, v35
	v_max_f32_e32 v37, 0, v37
	v_mul_f32_e32 v36, v36, v36
	v_mul_f32_e32 v38, v38, v38
	v_mul_f32_e32 v37, v37, v37
	v_cvt_pk_bf16_f32 v34, v38, v34
	v_cvt_pk_bf16_f32 v35, v35, v36
	v_cvt_pk_bf16_f32 v36, v42, v39
	v_cvt_pk_bf16_f32 v37, v40, v37
	global_store_dwordx4 v[50:51], v[34:37], off offset:256
	s_mov_b64 s[6:7], 0x140000
	s_nop 0
	v_fmamk_f32 v36, v151, 0x3a800000, v202
	v_cmp_gt_f32_e32 vcc, s38, v36
	v_mul_f32_e32 v37, 0x4b800000, v36
	v_lshl_add_u64 v[34:35], v[140:141], 0, s[6:7]
	v_cndmask_b32_e32 v36, v36, v37, vcc
	v_rsq_f32_e32 v36, v36
	s_mov_b32 s6, 0x140000
	v_mul_f32_e32 v37, 0x45800000, v36
	v_cndmask_b32_e32 v36, v36, v37, vcc
	v_mul_f32_e32 v26, v26, v36
	v_max_f32_e32 v26, 0, v26
	v_mul_f32_e32 v27, v27, v36
	v_mul_f32_e32 v28, v28, v36
	v_mul_f32_e32 v30, v30, v36
	v_mul_f32_e32 v37, v26, v26
	v_mul_f32_e32 v26, v31, v36
	v_max_f32_e32 v27, 0, v27
	v_max_f32_e32 v28, 0, v28
	v_max_f32_e32 v30, 0, v30
	v_max_f32_e32 v26, 0, v26
	v_mul_f32_e32 v31, v27, v27
	v_mul_f32_e32 v27, v32, v36
	v_mul_f32_e32 v32, v28, v28
	v_mul_f32_e32 v28, v33, v36
	v_mul_f32_e32 v30, v30, v30
	v_mul_f32_e32 v26, v26, v26
	v_max_f32_e32 v27, 0, v27
	v_max_f32_e32 v28, 0, v28
	v_mul_f32_e32 v29, v29, v36
	v_mul_f32_e32 v27, v27, v27
	v_max_f32_e32 v29, 0, v29
	v_mul_f32_e32 v28, v28, v28
	v_cvt_pk_bf16_f32 v26, v30, v26
	v_add_co_u32_e32 v30, vcc, s6, v140
	v_mul_f32_e32 v18, v18, v36
	v_mul_f32_e32 v19, v19, v36
	v_mul_f32_e32 v20, v20, v36
	v_mul_f32_e32 v29, v29, v29
	v_cvt_pk_bf16_f32 v27, v27, v28
	v_cvt_pk_bf16_f32 v28, v37, v31
	v_addc_co_u32_e32 v31, vcc, 0, v141, vcc
	v_max_f32_e32 v18, 0, v18
	v_max_f32_e32 v19, 0, v19
	v_max_f32_e32 v20, 0, v20
	v_cvt_pk_bf16_f32 v29, v32, v29
	global_store_dwordx4 v[30:31], v[26:29], off
	v_mul_f32_e32 v22, v22, v36
	v_mul_f32_e32 v21, v21, v36
	v_mul_f32_e32 v26, v18, v18
	v_mul_f32_e32 v18, v23, v36
	v_mul_f32_e32 v23, v19, v19
	v_mul_f32_e32 v19, v24, v36
	v_mul_f32_e32 v24, v20, v20
	v_mul_f32_e32 v20, v25, v36
	v_max_f32_e32 v18, 0, v18
	v_max_f32_e32 v19, 0, v19
	v_max_f32_e32 v20, 0, v20
	v_max_f32_e32 v22, 0, v22
	v_mul_f32_e32 v18, v18, v18
	v_mul_f32_e32 v19, v19, v19
	v_max_f32_e32 v21, 0, v21
	v_mul_f32_e32 v20, v20, v20
	v_mul_f32_e32 v22, v22, v22
	v_mul_f32_e32 v21, v21, v21
	v_cvt_pk_bf16_f32 v18, v22, v18
	v_cvt_pk_bf16_f32 v19, v19, v20
	v_cvt_pk_bf16_f32 v20, v26, v23
	v_cvt_pk_bf16_f32 v21, v24, v21
	global_store_dwordx4 v[34:35], v[18:21], off offset:256
	s_mov_b64 s[6:7], 0x160000
	s_nop 0
	v_fmamk_f32 v20, v150, 0x3a800000, v202
	v_cmp_gt_f32_e32 vcc, s38, v20
	v_mul_f32_e32 v21, 0x4b800000, v20
	v_lshl_add_u64 v[18:19], v[140:141], 0, s[6:7]
	v_cndmask_b32_e32 v20, v20, v21, vcc
	v_rsq_f32_e32 v20, v20
	s_mov_b32 s6, 0x160000
	v_mul_f32_e32 v21, 0x45800000, v20
	v_cndmask_b32_e32 v20, v20, v21, vcc
	v_mul_f32_e32 v10, v10, v20
	v_max_f32_e32 v10, 0, v10
	v_mul_f32_e32 v11, v11, v20
	v_mul_f32_e32 v12, v12, v20
	v_mul_f32_e32 v14, v14, v20
	v_mul_f32_e32 v21, v10, v10
	v_mul_f32_e32 v10, v15, v20
	v_max_f32_e32 v11, 0, v11
	v_max_f32_e32 v12, 0, v12
	v_max_f32_e32 v14, 0, v14
	v_max_f32_e32 v10, 0, v10
	v_mul_f32_e32 v15, v11, v11
	v_mul_f32_e32 v11, v16, v20
	v_mul_f32_e32 v16, v12, v12
	v_mul_f32_e32 v12, v17, v20
	v_mul_f32_e32 v14, v14, v14
	v_mul_f32_e32 v10, v10, v10
	v_max_f32_e32 v11, 0, v11
	v_max_f32_e32 v12, 0, v12
	v_mul_f32_e32 v13, v13, v20
	v_mul_f32_e32 v11, v11, v11
	v_max_f32_e32 v13, 0, v13
	v_mul_f32_e32 v12, v12, v12
	v_cvt_pk_bf16_f32 v10, v14, v10
	v_add_co_u32_e32 v14, vcc, s6, v140
	v_mul_f32_e32 v2, v2, v20
	v_mul_f32_e32 v3, v3, v20
	v_mul_f32_e32 v4, v4, v20
	v_mul_f32_e32 v13, v13, v13
	v_cvt_pk_bf16_f32 v11, v11, v12
	v_cvt_pk_bf16_f32 v12, v21, v15
	v_addc_co_u32_e32 v15, vcc, 0, v141, vcc
	v_max_f32_e32 v2, 0, v2
	v_max_f32_e32 v3, 0, v3
	v_max_f32_e32 v4, 0, v4
	v_cvt_pk_bf16_f32 v13, v16, v13
	global_store_dwordx4 v[14:15], v[10:13], off
	v_mul_f32_e32 v5, v5, v20
	v_mul_f32_e32 v6, v6, v20
	v_mul_f32_e32 v10, v2, v2
	v_mul_f32_e32 v2, v7, v20
	v_mul_f32_e32 v7, v3, v3
	v_mul_f32_e32 v3, v8, v20
	v_mul_f32_e32 v8, v4, v4
	v_mul_f32_e32 v4, v9, v20
	v_max_f32_e32 v2, 0, v2
	v_max_f32_e32 v3, 0, v3
	v_max_f32_e32 v4, 0, v4
	v_max_f32_e32 v5, 0, v5
	v_max_f32_e32 v6, 0, v6
	v_mul_f32_e32 v2, v2, v2
	v_mul_f32_e32 v3, v3, v3
	v_mul_f32_e32 v4, v4, v4
	v_mul_f32_e32 v5, v5, v5
	s_and_b64 vcc, exec, s[40:41]
	v_mul_f32_e32 v6, v6, v6
	v_cvt_pk_bf16_f32 v2, v6, v2
	v_cvt_pk_bf16_f32 v3, v3, v4
	v_cvt_pk_bf16_f32 v4, v10, v7
	v_cvt_pk_bf16_f32 v5, v8, v5
	global_store_dwordx4 v[18:19], v[2:5], off offset:256
	s_cbranch_vccz .LBB0_99
	s_waitcnt vmcnt(0)
	s_cmpk_gt_u32 s8, 0xff
	s_cbranch_scc1 .LBB0_106
	s_barrier

; #define LAS __attribute__((address_space(3)))
; __device__ __forceinline__ int ltid() { int t = threadIdx.x; asm volatile("" : "+v"(t)); return t; }
; #define PG8_BAR __builtin_amdgcn_s_barrier()
;     __device__ bool next(int i, Unit& u) const {
;         const long L = (long)i * G + c; if (L >= nwg) return false;
;         int wgid = (int)L; { const int q = nwg / NXCD, r = nwg % NXCD, xcd = wgid % NXCD, off = wgid / NXCD; wgid = (xcd < r ? xcd * (q + 1) : r * (q + 1) + (xcd - r) * q) + off; }
;         const int nig = WGM * nN, gid = wgid / nig, fm = gid * WGM, gsz = (nM - fm) < WGM ? (nM - fm) : WGM;
;         u.pm = fm + ((wgid % nig) % gsz); u.pn = (wgid % nig) / gsz; return true;
;     }
; template <class Epi>
; __device__ __forceinline__ void gemm_phase(LAS unsigned char* lds, const Gemm g, const StaticOrder& S, const Epi& E) {
;     const int tid = ltid(), wid = __builtin_amdgcn_readfirstlane(tid >> 6), lane = tid & 63, wr = wid >> 2, wc = wid & 3, fr = lane & 15, fq = lane >> 4;
;     const int K = g.K, nt = K / BK;
;     unsigned voffA[2], voffB[2];
; #pragma unroll
;     for (int i = 0; i < 2; ++i) { int R, C; stage_rc(tid * 16 + i * 8192, R, C); voffA[i] = (unsigned)(R * g.lda + C) * 2u; voffB[i] = (unsigned)(R * g.ldb + C) * 2u; }
;     const size_t kstep = (size_t)(BK * 2);
;     const size_t hstepA = (size_t)HALF * g.lda * 2, hstepB = (size_t)HALF * g.ldb * 2;
;     const size_t tstepA = 2 * hstepA, tstepB = 2 * hstepB;
;     const unsigned ldsw = (unsigned)wid * 1024u;
;     const int aoff = lds_byte(wr * 64 + fr, fq * 8), boff = lds_byte(wc * 32 + fr, fq * 8);
;     ...
;     Unit cur, nxt; int ui = 0;
;     if (!S.next(0, cur)) return;
;     f32x4 acc[2][2][4][2];
; #pragma unroll
;     for (int a = 0; a < 2; ++a)
; #pragma unroll
;         for (int b = 0; b < 2; ++b)
; #pragma unroll
;             for (int m = 0; m < 4; ++m)
; #pragma unroll
;                 for (int n = 0; n < 2; ++n) acc[a][b][m][n] = (f32x4){0.f, 0.f, 0.f, 0.f};
;     bf16x8 At[4][2], B0[2][2], B1[2][2];
;     const char* cA = (const char*)g.A + (size_t)cur.pm * tstepA; const char* cB = (const char*)g.Bt + (size_t)cur.pn * tstepB;
;     PG8_STAGE(PG8_SB(0, 0), cB, voffB); PG8_STAGE(PG8_SA(0, 0), cA, voffA); PG8_STAGE(PG8_SB(0, 1), cB + hstepB, voffB); PG8_STAGE(PG8_SA(0, 1), cA + hstepA, voffA);
;     if (wr == 1) PG8_BAR;
.LBB0_112:
	s_waitcnt vmcnt(0)
	v_mov_b32_e32 v16, v200
	s_cmpk_gt_i32 s1, 0x417
	v_readfirstlane_b32 s8, v16
	s_cbranch_scc1 .LBB0_140
	v_lshlrev_b32_e32 v1, 4, v16
	v_add_u32_e32 v2, 0x2000, v1
	v_ashrrev_i32_e32 v3, 31, v2
	v_lshrrev_b32_e32 v3, 22, v3
	v_add_u32_e32 v3, v2, v3
	v_ashrrev_i32_e32 v10, 10, v3
	v_mul_i32_i24_e32 v4, 0x400, v10
	v_sub_u32_e32 v2, v2, v4
	v_readlane_b32 s20, v255, 30
	v_lshrrev_b32_e32 v4, 4, v2
	v_readlane_b32 s21, v255, 31
	v_bitop3_b32 v2, v4, v2, 32 bitop3:0x6c
	s_load_dwordx2 s[6:7], s[20:21], 0x118
	v_ashrrev_i32_e32 v4, 31, v2
	v_lshrrev_b32_e32 v4, 26, v4
	v_add_u32_e32 v4, v2, v4
	v_ashrrev_i32_e32 v11, 6, v4
	v_and_b32_e32 v4, 0xc0, v4
	v_sub_u32_e32 v2, v2, v4
	s_waitcnt lgkmcnt(0)
	s_add_u32 s9, s6, 0x1400000
	v_lshlrev_b32_e32 v3, 5, v10
	v_ashrrev_i16_sdwa v2, v201, sext(v2) dst_sel:DWORD dst_unused:UNUSED_PAD src0_sel:DWORD src1_sel:BYTE_0
	s_addc_u32 s10, s7, 0
	v_and_b32_e32 v3, 32, v3
	v_bfe_i32 v12, v2, 0, 16
	s_ashr_i32 s12, s1, 31
	v_add_u32_e32 v2, v3, v12
	v_lshlrev_b32_e32 v3, 3, v10
	s_lshr_b32 s6, s12, 29
	v_and_b32_e32 v3, 0x1ffff0, v3
	s_add_i32 s6, s1, s6
	s_ashr_i32 s17, s8, 6
	v_add_lshl_u32 v3, v11, v3, 11
	s_ashr_i32 s7, s6, 3
	s_and_b32 s6, s6, -8
	s_ashr_i32 s25, s8, 8
	s_lshl_b32 s11, s17, 10
	v_lshl_add_u32 v146, v2, 1, v3
	v_bfe_i32 v3, v16, 27, 1
	s_sub_i32 s6, s1, s6
	v_lshrrev_b32_e32 v3, 22, v3
	s_cmp_lt_i32 s6, 0
	v_add_u32_e32 v3, v1, v3
	s_cselect_b32 s13, s69, 0x83
	v_and_b32_e32 v3, 0xfffffc00, v3
	s_mul_i32 s6, s6, s13
	v_sub_u32_e32 v1, v1, v3
	s_add_i32 s6, s6, s7
	v_lshrrev_b32_e32 v3, 4, v1
	s_ashr_i32 s7, s6, 31
	v_bitop3_b32 v3, v3, v1, 32 bitop3:0x6c
	v_ashrrev_i32_e32 v1, 31, v1
	s_lshr_b32 s7, s7, 27
	v_lshrrev_b32_e32 v1, 26, v1
	s_add_i32 s7, s6, s7
	v_ashrrev_i32_e32 v2, 31, v16
	v_add_u32_e32 v1, v3, v1
	s_ashr_i32 s13, s7, 5
	v_lshrrev_b32_e32 v2, 26, v2
	v_ashrrev_i32_e32 v14, 6, v1
	s_lshl_b32 s13, s13, 3
	v_add_u32_e32 v2, v16, v2
	v_mul_i32_i24_e32 v1, 64, v14
	s_sub_i32 s14, 0x106, s13
	v_ashrrev_i32_e32 v13, 6, v2
	v_sub_u32_e32 v1, v3, v1
	s_min_u32 s14, s14, 8
	s_andn2_b32 s7, s7, 31
	v_lshlrev_b32_e32 v2, 5, v13
	v_ashrrev_i16_sdwa v1, v201, sext(v1) dst_sel:DWORD dst_unused:UNUSED_PAD src0_sel:DWORD src1_sel:BYTE_0
	s_sub_i32 s15, s6, s7
	v_cvt_f32_ubyte0_e32 v4, s14
	v_and_b32_e32 v2, 32, v2
	v_bfe_i32 v15, v1, 0, 16
	v_cvt_f32_i32_e32 v3, s15
	v_rcp_iflag_f32_e32 v5, v4
	v_add_u32_e32 v1, v2, v15
	v_lshlrev_b32_e32 v2, 3, v13
	v_and_b32_e32 v2, 0x1ffff0, v2
	v_add_lshl_u32 v2, v14, v2, 11
	v_lshl_add_u32 v148, v1, 1, v2
	v_mul_f32_e32 v1, v3, v5
	v_trunc_f32_e32 v1, v1
	v_fma_f32 v2, -v1, v4, v3
	v_cvt_i32_f32_e32 v1, v1
	s_ashr_i32 s6, s15, 30
	s_or_b32 s16, s6, 1
	v_cmp_ge_f32_e64 s[6:7], |v2|, v4
	s_and_b64 s[6:7], s[6:7], exec
	s_cselect_b32 s6, s16, 0
	v_readfirstlane_b32 s7, v1
	s_add_i32 s24, s7, s6
	s_mul_i32 s6, s24, s14
	s_sub_i32 s6, s15, s6
	s_sext_i32_i8 s6, s6
	s_add_i32 s46, s13, s6
	s_ashr_i32 s47, s46, 31
	s_bfe_i64 s[14:15], s[24:25], 0x80000
	s_lshl_b64 s[6:7], s[46:47], 19
	s_lshl_b64 s[14:15], s[14:15], 19
	s_add_u32 s48, s9, s14
	s_addc_u32 s49, s10, s15
	s_add_i32 s13, s11, 0
	s_add_i32 m0, s13, 0x10000
	s_load_dwordx2 s[20:21], s[20:21], 0x110
	global_load_lds_dwordx4 v148, s[48:49]
	s_add_i32 m0, s13, 0x12000
	s_add_u32 s36, s2, s6
	global_load_lds_dwordx4 v146, s[48:49]
	s_addc_u32 s37, s3, s7
	s_mov_b32 m0, s13
	s_add_i32 s14, s13, 0x2000
	global_load_lds_dwordx4 v148, s[36:37]
	s_mov_b32 m0, s14
	s_add_u32 s6, s48, 0x40000
	global_load_lds_dwordx4 v146, s[36:37]
	s_addc_u32 s7, s49, 0
	s_add_i32 m0, s13, 0x14000
	v_mov_b32_e32 v149, v0
	global_load_lds_dwordx4 v148, s[6:7]
	s_add_i32 m0, s13, 0x16000
	v_mov_b32_e32 v147, v0
	global_load_lds_dwordx4 v146, s[6:7]
	s_add_u32 s6, s36, 0x40000
	s_addc_u32 s7, s37, 0
	s_add_i32 s15, s13, 0x4000
	s_mov_b32 m0, s15
	s_add_i32 s16, s13, 0x6000
	global_load_lds_dwordx4 v148, s[6:7]
	s_mov_b32 m0, s16
	v_lshl_add_u64 v[8:9], s[48:49], 0, v[148:149]
	global_load_lds_dwordx4 v146, s[6:7]
	v_lshl_add_u64 v[6:7], s[48:49], 0, v[146:147]
	v_lshl_add_u64 v[4:5], s[36:37], 0, v[148:149]
	s_cmp_lg_u32 s25, 1
	v_lshl_add_u64 v[2:3], s[36:37], 0, v[146:147]
	s_cbranch_scc1 .LBB0_115
	s_barrier
	s_setprio 1

; #define PG8_STAGE(bufoff, gbase, voff) do { _Pragma("unroll") for (int _i = 0; _i < 2; ++_i) \
;         __builtin_amdgcn_global_load_lds((const unsigned*)((const char*)(gbase) + (voff)[_i]), (LAS unsigned*)(lds + (bufoff) + ldsw + _i * 8192), 16, 0, 0); } while (0)
; #define PG8_LDA(dst, b, h) do { _Pragma("unroll") for (int m = 0; m < 4; ++m) _Pragma("unroll") for (int k = 0; k < 2; ++k) dst[m][k] = *(const LAS bf16x8*)(lds + PG8_SA(b, h) + aoff + m * 2048 + k * 1024); } while (0)
; #define PG8_LDB(dst, b, h) do { _Pragma("unroll") for (int n = 0; n < 2; ++n) _Pragma("unroll") for (int k = 0; k < 2; ++k) dst[n][k] = *(const LAS bf16x8*)(lds + PG8_SB(b, h) + boff + n * 2048 + k * 1024); } while (0)
; #define PG8_MMA(ai, bj, At, Bt) do { __builtin_amdgcn_s_setprio(1); _Pragma("unroll") for (int m = 0; m < 4; ++m) _Pragma("unroll") for (int n = 0; n < 2; ++n) _Pragma("unroll") for (int k = 0; k < 2; ++k) \
;         acc[ai][bj][m][n] = __builtin_amdgcn_mfma_f32_16x16x32_bf16(Bt[n][k], At[m][k], acc[ai][bj][m][n], 0, 0, 0); __builtin_amdgcn_s_setprio(0); } while (0)
; #define PG8_WAIT_L(n) asm volatile("s_waitcnt lgkmcnt(" #n ")" ::: "memory")
; #define PG8_BAR __builtin_amdgcn_s_barrier()
; #define PG8_SCHED __builtin_amdgcn_sched_barrier(0)
; template <class Epi>
; __device__ __forceinline__ void gemm_phase(LAS unsigned char* lds, const Gemm g, const StaticOrder& S, const Epi& E) {
;     ...
;             const char* a1 = cA + (size_t)(t + 1) * kstep;
;             const char* a2 = last ? nA : cA + (size_t)(t + 2) * kstep; const char* b2 = last ? nB : cB + (size_t)(t + 2) * kstep;
;             const char* a3 = a2 + kstep; const char* b3 = b2 + kstep;
;             PG8_LDB(B0, 0, 0); PG8_SCHED; PG8_LDA(At, 0, 0); PG8_STAGE(PG8_SA(1, 1), a1 + hstepA, voffA);
;             PG8_WAIT_L(8); PG8_BAR; PG8_WAIT_L(0); PG8_MMA(0, 0, At, B0); PG8_BAR; PG8_SCHED;
;             PG8_LDB(B1, 0, 1); PG8_STAGE(PG8_SB(0, 0), b2, voffB);
;             PG8_BAR; PG8_WAIT_L(0); PG8_MMA(0, 1, At, B1); PG8_BAR;
;             PG8_LDA(At, 0, 1); PG8_STAGE(PG8_SA(0, 0), a2, voffA);
;             PG8_BAR; PG8_WAIT_L(0); PG8_MMA(1, 0, At, B0); PG8_BAR; PG8_SCHED;
.LBB0_120:
	s_add_u32 s6, s36, 0xfffc0080
	s_addc_u32 s7, s37, -1
	s_add_i32 s63, 0, 0x10000
	v_add_u32_e32 v142, s63, v157
	ds_read_b128 v[130:133], v142
	ds_read_b128 v[134:137], v142 offset:1024
	ds_read_b128 v[138:141], v142 offset:2048
	ds_read_b128 v[142:145], v142 offset:3072
	s_cmp_eq_u32 s62, 12
	s_cselect_b32 s53, s31, s7
	s_cselect_b32 s52, s58, s6
	s_cselect_b32 s49, s29, s61
	s_cselect_b32 s48, s59, s60
	v_lshl_add_u64 v[212:213], s[36:37], 0, v[152:153]
	s_add_i32 m0, s13, 0xc000
	ds_read_b128 v[176:179], v171
	ds_read_b128 v[180:183], v171 offset:1024
	ds_read_b128 v[184:187], v171 offset:2048
	ds_read_b128 v[188:191], v171 offset:3072
	ds_read_b128 v[192:195], v171 offset:4096
	ds_read_b128 v[196:199], v171 offset:5120
	ds_read_b128 v[216:219], v171 offset:6144
	ds_read_b128 v[220:223], v171 offset:7168
	global_load_lds_dwordx4 v[212:213], off
	v_lshl_add_u64 v[212:213], s[36:37], 0, v[154:155]
	s_add_i32 m0, s13, 0xe000
	s_nop 0
	global_load_lds_dwordx4 v[212:213], off
	s_waitcnt lgkmcnt(8)
	s_barrier
	s_waitcnt lgkmcnt(0)
	s_waitcnt lgkmcnt(0)
	v_mfma_f32_16x16x32_bf16 v[126:129], v[130:133], v[176:179], v[126:129]
	v_mfma_f32_16x16x32_bf16 v[122:125], v[138:141], v[176:179], v[122:125]
	v_mfma_f32_16x16x32_bf16 v[110:113], v[130:133], v[184:187], v[110:113]
	v_mfma_f32_16x16x32_bf16 v[106:109], v[138:141], v[184:187], v[106:109]
	v_mfma_f32_16x16x32_bf16 v[94:97], v[130:133], v[192:195], v[94:97]
	v_mfma_f32_16x16x32_bf16 v[90:93], v[138:141], v[192:195], v[90:93]
	v_mfma_f32_16x16x32_bf16 v[78:81], v[130:133], v[216:219], v[78:81]
	v_mfma_f32_16x16x32_bf16 v[74:77], v[138:141], v[216:219], v[74:77]
	v_mfma_f32_16x16x32_bf16 v[126:129], v[134:137], v[180:183], v[126:129]
	v_mfma_f32_16x16x32_bf16 v[122:125], v[142:145], v[180:183], v[122:125]
	v_mfma_f32_16x16x32_bf16 v[110:113], v[134:137], v[188:191], v[110:113]
	v_mfma_f32_16x16x32_bf16 v[106:109], v[142:145], v[188:191], v[106:109]
	v_mfma_f32_16x16x32_bf16 v[94:97], v[134:137], v[196:199], v[94:97]
	v_mfma_f32_16x16x32_bf16 v[90:93], v[142:145], v[196:199], v[90:93]
	v_mfma_f32_16x16x32_bf16 v[78:81], v[134:137], v[220:223], v[78:81]
	v_mfma_f32_16x16x32_bf16 v[74:77], v[142:145], v[220:223], v[74:77]
	s_barrier
	s_add_i32 s64, 0, 0x14000
	v_add_u32_e32 v212, s64, v157
	s_add_i32 s6, s63, s11
	ds_read_b128 v[224:227], v212
	ds_read_b128 v[228:231], v212 offset:1024
	ds_read_b128 v[232:235], v212 offset:2048
	ds_read_b128 v[236:239], v212 offset:3072
	v_lshl_add_u64 v[212:213], s[48:49], 0, v[148:149]
	s_mov_b32 m0, s6
	v_lshl_add_u64 v[240:241], s[48:49], 0, v[146:147]
	global_load_lds_dwordx4 v[212:213], off
	s_add_i32 m0, s6, 0x2000
	s_nop 0
	global_load_lds_dwordx4 v[240:241], off
	s_barrier
	s_waitcnt lgkmcnt(0)
	s_waitcnt lgkmcnt(0)
	v_mfma_f32_16x16x32_bf16 v[118:121], v[224:227], v[176:179], v[118:121]
	v_mfma_f32_16x16x32_bf16 v[114:117], v[232:235], v[176:179], v[114:117]
	v_mfma_f32_16x16x32_bf16 v[102:105], v[224:227], v[184:187], v[102:105]
	v_mfma_f32_16x16x32_bf16 v[98:101], v[232:235], v[184:187], v[98:101]
	v_mfma_f32_16x16x32_bf16 v[86:89], v[224:227], v[192:195], v[86:89]
	v_mfma_f32_16x16x32_bf16 v[82:85], v[232:235], v[192:195], v[82:85]
	v_mfma_f32_16x16x32_bf16 v[70:73], v[224:227], v[216:219], v[70:73]
	v_mfma_f32_16x16x32_bf16 v[66:69], v[232:235], v[216:219], v[66:69]
	v_mfma_f32_16x16x32_bf16 v[118:121], v[228:231], v[180:183], v[118:121]
	v_mfma_f32_16x16x32_bf16 v[114:117], v[236:239], v[180:183], v[114:117]
	v_mfma_f32_16x16x32_bf16 v[102:105], v[228:231], v[188:191], v[102:105]
	v_mfma_f32_16x16x32_bf16 v[98:101], v[236:239], v[188:191], v[98:101]
	v_mfma_f32_16x16x32_bf16 v[86:89], v[228:231], v[196:199], v[86:89]
	v_mfma_f32_16x16x32_bf16 v[82:85], v[236:239], v[196:199], v[82:85]
	v_mfma_f32_16x16x32_bf16 v[70:73], v[228:231], v[220:223], v[70:73]
	v_mfma_f32_16x16x32_bf16 v[66:69], v[236:239], v[220:223], v[66:69]
	s_mov_b32 m0, s13
	v_lshl_add_u64 v[242:243], s[52:53], 0, v[148:149]
	s_barrier
	ds_read_b128 v[176:179], v171 offset:16384
	ds_read_b128 v[180:183], v171 offset:17408
	ds_read_b128 v[184:187], v171 offset:18432
	ds_read_b128 v[188:191], v171 offset:19456
	ds_read_b128 v[192:195], v171 offset:20480
	ds_read_b128 v[196:199], v171 offset:21504
	ds_read_b128 v[216:219], v171 offset:22528
	ds_read_b128 v[220:223], v171 offset:23552
	global_load_lds_dwordx4 v[242:243], off
	v_lshl_add_u64 v[244:245], s[52:53], 0, v[146:147]
	s_mov_b32 m0, s14
	s_nop 0
	global_load_lds_dwordx4 v[244:245], off
	s_barrier
	s_waitcnt lgkmcnt(0)
	s_waitcnt lgkmcnt(0)
	v_mfma_f32_16x16x32_bf16 v[62:65], v[130:133], v[176:179], v[62:65]
	v_mfma_f32_16x16x32_bf16 v[58:61], v[138:141], v[176:179], v[58:61]
	v_mfma_f32_16x16x32_bf16 v[46:49], v[130:133], v[184:187], v[46:49]
	v_mfma_f32_16x16x32_bf16 v[42:45], v[138:141], v[184:187], v[42:45]
	v_mfma_f32_16x16x32_bf16 v[30:33], v[130:133], v[192:195], v[30:33]
	v_mfma_f32_16x16x32_bf16 v[26:29], v[138:141], v[192:195], v[26:29]
	v_mfma_f32_16x16x32_bf16 v[14:17], v[130:133], v[216:219], v[14:17]
	v_mfma_f32_16x16x32_bf16 v[10:13], v[138:141], v[216:219], v[10:13]
	v_mfma_f32_16x16x32_bf16 v[62:65], v[134:137], v[180:183], v[62:65]
	v_mfma_f32_16x16x32_bf16 v[58:61], v[142:145], v[180:183], v[58:61]
	v_mfma_f32_16x16x32_bf16 v[46:49], v[134:137], v[188:191], v[46:49]
	v_mfma_f32_16x16x32_bf16 v[42:45], v[142:145], v[188:191], v[42:45]
	v_mfma_f32_16x16x32_bf16 v[30:33], v[134:137], v[196:199], v[30:33]
	v_mfma_f32_16x16x32_bf16 v[26:29], v[142:145], v[196:199], v[26:29]
	v_mfma_f32_16x16x32_bf16 v[14:17], v[134:137], v[220:223], v[14:17]
	v_mfma_f32_16x16x32_bf16 v[10:13], v[142:145], v[220:223], v[10:13]
	s_barrier
; #define PG8_STAGE(bufoff, gbase, voff) do { _Pragma("unroll") for (int _i = 0; _i < 2; ++_i) \
;         __builtin_amdgcn_global_load_lds((const unsigned*)((const char*)(gbase) + (voff)[_i]), (LAS unsigned*)(lds + (bufoff) + ldsw + _i * 8192), 16, 0, 0); } while (0)
; #define PG8_LDA(dst, b, h) do { _Pragma("unroll") for (int m = 0; m < 4; ++m) _Pragma("unroll") for (int k = 0; k < 2; ++k) dst[m][k] = *(const LAS bf16x8*)(lds + PG8_SA(b, h) + aoff + m * 2048 + k * 1024); } while (0)
; #define PG8_LDB(dst, b, h) do { _Pragma("unroll") for (int n = 0; n < 2; ++n) _Pragma("unroll") for (int k = 0; k < 2; ++k) dst[n][k] = *(const LAS bf16x8*)(lds + PG8_SB(b, h) + boff + n * 2048 + k * 1024); } while (0)
; #define PG8_MMA(ai, bj, At, Bt) do { __builtin_amdgcn_s_setprio(1); _Pragma("unroll") for (int m = 0; m < 4; ++m) _Pragma("unroll") for (int n = 0; n < 2; ++n) _Pragma("unroll") for (int k = 0; k < 2; ++k) \
;         acc[ai][bj][m][n] = __builtin_amdgcn_mfma_f32_16x16x32_bf16(Bt[n][k], At[m][k], acc[ai][bj][m][n], 0, 0, 0); __builtin_amdgcn_s_setprio(0); } while (0)
; #define PG8_WAIT_V(n) asm volatile("s_waitcnt vmcnt(" #n ")" ::: "memory")
; #define PG8_WAIT_L(n) asm volatile("s_waitcnt lgkmcnt(" #n ")" ::: "memory")
; #define PG8_BAR __builtin_amdgcn_s_barrier()
; #define PG8_SCHED __builtin_amdgcn_sched_barrier(0)
; template <class Epi>
; __device__ __forceinline__ void gemm_phase(LAS unsigned char* lds, const Gemm g, const StaticOrder& S, const Epi& E) {
;     ...
;             PG8_STAGE(PG8_SB(0, 1), b2 + hstepB, voffB);
;             PG8_WAIT_V(6); PG8_BAR; PG8_MMA(1, 1, At, B1); PG8_BAR;
;             PG8_LDB(B0, 1, 0); PG8_SCHED; PG8_LDA(At, 1, 0); PG8_STAGE(PG8_SA(0, 1), a2 + hstepA, voffA);
;             PG8_WAIT_L(8); PG8_BAR; PG8_WAIT_L(0); PG8_MMA(0, 0, At, B0); PG8_BAR; PG8_SCHED;
;             PG8_LDB(B1, 1, 1); PG8_STAGE(PG8_SB(1, 0), b3, voffB);
;             PG8_BAR; PG8_WAIT_L(0); PG8_MMA(0, 1, At, B1); PG8_BAR;
	s_add_u32 s6, s48, 0x40000
	s_addc_u32 s7, s49, 0
	s_add_i32 s63, s64, s11
	v_lshl_add_u64 v[130:131], s[6:7], 0, v[148:149]
	s_mov_b32 m0, s63
	s_nop 0
	global_load_lds_dwordx4 v[130:131], off
	v_lshl_add_u64 v[130:131], s[6:7], 0, v[146:147]
	s_add_i32 m0, s63, 0x2000
	s_nop 0
	global_load_lds_dwordx4 v[130:131], off
	s_waitcnt vmcnt(6)
	s_barrier
	v_mfma_f32_16x16x32_bf16 v[54:57], v[224:227], v[176:179], v[54:57]
	v_mfma_f32_16x16x32_bf16 v[50:53], v[232:235], v[176:179], v[50:53]
	v_mfma_f32_16x16x32_bf16 v[38:41], v[224:227], v[184:187], v[38:41]
	v_mfma_f32_16x16x32_bf16 v[34:37], v[232:235], v[184:187], v[34:37]
	v_mfma_f32_16x16x32_bf16 v[22:25], v[224:227], v[192:195], v[22:25]
	v_mfma_f32_16x16x32_bf16 v[18:21], v[232:235], v[192:195], v[18:21]
	v_mfma_f32_16x16x32_bf16 v[6:9], v[224:227], v[216:219], v[6:9]
	v_mfma_f32_16x16x32_bf16 v[2:5], v[232:235], v[216:219], v[2:5]
	v_mfma_f32_16x16x32_bf16 v[54:57], v[228:231], v[180:183], v[54:57]
	v_mfma_f32_16x16x32_bf16 v[50:53], v[236:239], v[180:183], v[50:53]
	v_mfma_f32_16x16x32_bf16 v[38:41], v[228:231], v[188:191], v[38:41]
	v_mfma_f32_16x16x32_bf16 v[34:37], v[236:239], v[188:191], v[34:37]
	v_mfma_f32_16x16x32_bf16 v[22:25], v[228:231], v[196:199], v[22:25]
	v_mfma_f32_16x16x32_bf16 v[18:21], v[236:239], v[196:199], v[18:21]
	v_mfma_f32_16x16x32_bf16 v[6:9], v[228:231], v[220:223], v[6:9]
	v_mfma_f32_16x16x32_bf16 v[2:5], v[236:239], v[220:223], v[2:5]
	s_add_i32 s63, 0, 0x18000
	v_add_u32_e32 v142, s63, v157
	s_barrier
	ds_read_b128 v[130:133], v142
	ds_read_b128 v[134:137], v142 offset:1024
	ds_read_b128 v[138:141], v142 offset:2048
	ds_read_b128 v[142:145], v142 offset:3072
	s_add_u32 s6, s52, 0x40000
	s_addc_u32 s7, s53, 0
	s_mov_b32 m0, s15
	v_lshl_add_u64 v[224:225], s[6:7], 0, v[148:149]
	ds_read_b128 v[176:179], v171 offset:32768
	ds_read_b128 v[180:183], v171 offset:33792
	ds_read_b128 v[184:187], v171 offset:34816
	ds_read_b128 v[188:191], v171 offset:35840
	ds_read_b128 v[192:195], v171 offset:36864
	ds_read_b128 v[196:199], v171 offset:37888
	ds_read_b128 v[216:219], v171 offset:38912
	ds_read_b128 v[220:223], v171 offset:39936
	global_load_lds_dwordx4 v[224:225], off
	v_lshl_add_u64 v[224:225], s[6:7], 0, v[146:147]
	s_mov_b32 m0, s16
	s_nop 0
	global_load_lds_dwordx4 v[224:225], off
	s_waitcnt lgkmcnt(8)
	s_barrier
	s_waitcnt lgkmcnt(0)
	s_waitcnt lgkmcnt(0)
	v_mfma_f32_16x16x32_bf16 v[126:129], v[130:133], v[176:179], v[126:129]
	v_mfma_f32_16x16x32_bf16 v[122:125], v[138:141], v[176:179], v[122:125]
	v_mfma_f32_16x16x32_bf16 v[110:113], v[130:133], v[184:187], v[110:113]
	v_mfma_f32_16x16x32_bf16 v[106:109], v[138:141], v[184:187], v[106:109]
	v_mfma_f32_16x16x32_bf16 v[94:97], v[130:133], v[192:195], v[94:97]
	v_mfma_f32_16x16x32_bf16 v[90:93], v[138:141], v[192:195], v[90:93]
	v_mfma_f32_16x16x32_bf16 v[78:81], v[130:133], v[216:219], v[78:81]
	v_mfma_f32_16x16x32_bf16 v[74:77], v[138:141], v[216:219], v[74:77]
	v_mfma_f32_16x16x32_bf16 v[126:129], v[134:137], v[180:183], v[126:129]
	v_mfma_f32_16x16x32_bf16 v[122:125], v[142:145], v[180:183], v[122:125]
	v_mfma_f32_16x16x32_bf16 v[110:113], v[134:137], v[188:191], v[110:113]
	v_mfma_f32_16x16x32_bf16 v[106:109], v[142:145], v[188:191], v[106:109]
	v_mfma_f32_16x16x32_bf16 v[94:97], v[134:137], v[196:199], v[94:97]
	v_mfma_f32_16x16x32_bf16 v[90:93], v[142:145], v[196:199], v[90:93]
	v_mfma_f32_16x16x32_bf16 v[78:81], v[134:137], v[220:223], v[78:81]
	v_mfma_f32_16x16x32_bf16 v[74:77], v[142:145], v[220:223], v[74:77]
	s_barrier
	s_add_i32 s52, 0, 0x1c000
	s_add_i32 s6, s63, s11
	v_add_u32_e32 v236, s52, v157
	v_lshl_add_u64 v[212:213], v[212:213], 0, s[88:89]
	s_mov_b32 m0, s6
	ds_read_b128 v[224:227], v236
	ds_read_b128 v[228:231], v236 offset:1024
	ds_read_b128 v[232:235], v236 offset:2048
	ds_read_b128 v[236:239], v236 offset:3072
	global_load_lds_dwordx4 v[212:213], off
	v_lshl_add_u64 v[212:213], v[240:241], 0, s[88:89]
	s_add_i32 m0, s6, 0x2000
	s_nop 0
	global_load_lds_dwordx4 v[212:213], off
	s_barrier
	s_waitcnt lgkmcnt(0)
	s_waitcnt lgkmcnt(0)
	v_mfma_f32_16x16x32_bf16 v[118:121], v[224:227], v[176:179], v[118:121]
	v_mfma_f32_16x16x32_bf16 v[114:117], v[232:235], v[176:179], v[114:117]
	v_mfma_f32_16x16x32_bf16 v[102:105], v[224:227], v[184:187], v[102:105]
	v_mfma_f32_16x16x32_bf16 v[98:101], v[232:235], v[184:187], v[98:101]
	v_mfma_f32_16x16x32_bf16 v[86:89], v[224:227], v[192:195], v[86:89]
	v_mfma_f32_16x16x32_bf16 v[82:85], v[232:235], v[192:195], v[82:85]
	v_mfma_f32_16x16x32_bf16 v[70:73], v[224:227], v[216:219], v[70:73]
	v_mfma_f32_16x16x32_bf16 v[66:69], v[232:235], v[216:219], v[66:69]
	v_mfma_f32_16x16x32_bf16 v[118:121], v[228:231], v[180:183], v[118:121]
	v_mfma_f32_16x16x32_bf16 v[114:117], v[236:239], v[180:183], v[114:117]
	v_mfma_f32_16x16x32_bf16 v[102:105], v[228:231], v[188:191], v[102:105]
	v_mfma_f32_16x16x32_bf16 v[98:101], v[236:239], v[188:191], v[98:101]
	v_mfma_f32_16x16x32_bf16 v[86:89], v[228:231], v[196:199], v[86:89]
	v_mfma_f32_16x16x32_bf16 v[82:85], v[236:239], v[196:199], v[82:85]
	v_mfma_f32_16x16x32_bf16 v[70:73], v[228:231], v[220:223], v[70:73]
	v_mfma_f32_16x16x32_bf16 v[66:69], v[236:239], v[220:223], v[66:69]
	s_mov_b32 m0, s17
	v_lshl_add_u64 v[212:213], v[242:243], 0, s[88:89]
	s_barrier
	ds_read_b128 v[176:179], v171 offset:49152
	ds_read_b128 v[180:183], v171 offset:50176
	ds_read_b128 v[184:187], v171 offset:51200
	ds_read_b128 v[188:191], v171 offset:52224
	ds_read_b128 v[192:195], v171 offset:53248
	ds_read_b128 v[196:199], v171 offset:54272
	ds_read_b128 v[216:219], v171 offset:55296
	ds_read_b128 v[220:223], v171 offset:56320
	global_load_lds_dwordx4 v[212:213], off
	v_lshl_add_u64 v[212:213], v[244:245], 0, s[88:89]
	s_mov_b32 m0, s33
	s_nop 0
	global_load_lds_dwordx4 v[212:213], off
	s_barrier
; #define PG8_STAGE(bufoff, gbase, voff) do { _Pragma("unroll") for (int _i = 0; _i < 2; ++_i) \
;         __builtin_amdgcn_global_load_lds((const unsigned*)((const char*)(gbase) + (voff)[_i]), (LAS unsigned*)(lds + (bufoff) + ldsw + _i * 8192), 16, 0, 0); } while (0)
; #define PG8_LDA(dst, b, h) do { _Pragma("unroll") for (int m = 0; m < 4; ++m) _Pragma("unroll") for (int k = 0; k < 2; ++k) dst[m][k] = *(const LAS bf16x8*)(lds + PG8_SA(b, h) + aoff + m * 2048 + k * 1024); } while (0)
; #define PG8_MMA(ai, bj, At, Bt) do { __builtin_amdgcn_s_setprio(1); _Pragma("unroll") for (int m = 0; m < 4; ++m) _Pragma("unroll") for (int n = 0; n < 2; ++n) _Pragma("unroll") for (int k = 0; k < 2; ++k) \
;         acc[ai][bj][m][n] = __builtin_amdgcn_mfma_f32_16x16x32_bf16(Bt[n][k], At[m][k], acc[ai][bj][m][n], 0, 0, 0); __builtin_amdgcn_s_setprio(0); } while (0)
; #define PG8_WAIT_V(n) asm volatile("s_waitcnt vmcnt(" #n ")" ::: "memory")
; #define PG8_WAIT_L(n) asm volatile("s_waitcnt lgkmcnt(" #n ")" ::: "memory")
; #define PG8_BAR __builtin_amdgcn_s_barrier()
; #define PG8_SCHED __builtin_amdgcn_sched_barrier(0)
; template <class Epi>
; __device__ __forceinline__ void gemm_phase(LAS unsigned char* lds, const Gemm g, const StaticOrder& S, const Epi& E) {
;     ...
;             PG8_LDA(At, 1, 1); PG8_STAGE(PG8_SA(1, 0), a3, voffA);
;             PG8_BAR; PG8_WAIT_L(0); PG8_MMA(1, 0, At, B0); PG8_BAR; PG8_SCHED;
;             PG8_STAGE(PG8_SB(1, 1), b3 + hstepB, voffB);
;             PG8_WAIT_V(6); PG8_BAR; PG8_MMA(1, 1, At, B1); PG8_BAR;
	s_waitcnt lgkmcnt(0)
	s_waitcnt lgkmcnt(0)
	v_mfma_f32_16x16x32_bf16 v[62:65], v[130:133], v[176:179], v[62:65]
	v_mfma_f32_16x16x32_bf16 v[58:61], v[138:141], v[176:179], v[58:61]
	v_mfma_f32_16x16x32_bf16 v[46:49], v[130:133], v[184:187], v[46:49]
	v_mfma_f32_16x16x32_bf16 v[42:45], v[138:141], v[184:187], v[42:45]
	v_mfma_f32_16x16x32_bf16 v[30:33], v[130:133], v[192:195], v[30:33]
	v_mfma_f32_16x16x32_bf16 v[26:29], v[138:141], v[192:195], v[26:29]
	v_mfma_f32_16x16x32_bf16 v[14:17], v[130:133], v[216:219], v[14:17]
	v_mfma_f32_16x16x32_bf16 v[10:13], v[138:141], v[216:219], v[10:13]
	v_mfma_f32_16x16x32_bf16 v[62:65], v[134:137], v[180:183], v[62:65]
	v_mfma_f32_16x16x32_bf16 v[58:61], v[142:145], v[180:183], v[58:61]
	v_mfma_f32_16x16x32_bf16 v[46:49], v[134:137], v[188:191], v[46:49]
	v_mfma_f32_16x16x32_bf16 v[42:45], v[142:145], v[188:191], v[42:45]
	v_mfma_f32_16x16x32_bf16 v[30:33], v[134:137], v[196:199], v[30:33]
	v_mfma_f32_16x16x32_bf16 v[26:29], v[142:145], v[196:199], v[26:29]
	v_mfma_f32_16x16x32_bf16 v[14:17], v[134:137], v[220:223], v[14:17]
	v_mfma_f32_16x16x32_bf16 v[10:13], v[142:145], v[220:223], v[10:13]
	s_barrier
	s_add_u32 s6, s48, 0x40080
	s_addc_u32 s7, s49, 0
	s_add_i32 s48, s52, s11
	v_lshl_add_u64 v[130:131], s[6:7], 0, v[148:149]
	s_mov_b32 m0, s48
	s_nop 0
	global_load_lds_dwordx4 v[130:131], off
	v_lshl_add_u64 v[130:131], s[6:7], 0, v[146:147]
	s_add_i32 m0, s48, 0x2000
	s_nop 0
	global_load_lds_dwordx4 v[130:131], off
	s_waitcnt vmcnt(6)
	s_barrier
	v_mfma_f32_16x16x32_bf16 v[54:57], v[224:227], v[176:179], v[54:57]
	v_mfma_f32_16x16x32_bf16 v[50:53], v[232:235], v[176:179], v[50:53]
	v_mfma_f32_16x16x32_bf16 v[38:41], v[224:227], v[184:187], v[38:41]
	v_mfma_f32_16x16x32_bf16 v[34:37], v[232:235], v[184:187], v[34:37]
	v_mfma_f32_16x16x32_bf16 v[22:25], v[224:227], v[192:195], v[22:25]
	v_mfma_f32_16x16x32_bf16 v[18:21], v[232:235], v[192:195], v[18:21]
	v_mfma_f32_16x16x32_bf16 v[6:9], v[224:227], v[216:219], v[6:9]
	v_mfma_f32_16x16x32_bf16 v[2:5], v[232:235], v[216:219], v[2:5]
	v_mfma_f32_16x16x32_bf16 v[54:57], v[228:231], v[180:183], v[54:57]
	v_mfma_f32_16x16x32_bf16 v[50:53], v[236:239], v[180:183], v[50:53]
	v_mfma_f32_16x16x32_bf16 v[38:41], v[228:231], v[188:191], v[38:41]
	v_mfma_f32_16x16x32_bf16 v[34:37], v[236:239], v[188:191], v[34:37]
	v_mfma_f32_16x16x32_bf16 v[22:25], v[228:231], v[196:199], v[22:25]
	v_mfma_f32_16x16x32_bf16 v[18:21], v[236:239], v[196:199], v[18:21]
	v_mfma_f32_16x16x32_bf16 v[6:9], v[228:231], v[220:223], v[6:9]
	v_mfma_f32_16x16x32_bf16 v[2:5], v[236:239], v[220:223], v[2:5]
	s_add_i32 s62, s62, 2
	s_add_u32 s36, s36, 0x100
	s_addc_u32 s37, s37, 0
	s_add_u32 s60, s60, 0x100
	s_addc_u32 s61, s61, 0
	s_cmp_gt_u32 s62, 13
	s_barrier
	s_cbranch_scc0 .LBB0_120
; __device__ __forceinline__ unsigned pk2(float lo, float hi) { unsigned r; asm volatile("v_cvt_pk_bf16_f32 %0, %1, %2" : "=v"(r) : "v"(lo), "v"(hi)); return r; }
;     __device__ __forceinline__ void operator()(const f32x4 (&acc)[2][2][4][2], const Unit& u, int wr, int wc, int fr, int fq) const {
;         const int rowb = u.pm * 256 + wr * 64 + fr, colb = u.pn * 256 + wc * 32 + fq * 4;
;         float* base = (u.pm * 256 < NM0) ? out : xmeta - (size_t)NM0 * 1024;
; #pragma unroll
;         for (int ai = 0; ai < 2; ++ai)
; #pragma unroll
;             for (int mh = 0; mh < 2; ++mh) {
;                 f32x4 xv[2][2][2];
; #pragma unroll
;                 for (int m2 = 0; m2 < 2; ++m2)
; #pragma unroll
;                     for (int bj = 0; bj < 2; ++bj)
; #pragma unroll
;                         for (int n = 0; n < 2; ++n) { const int rr = rowb + ai * 128 + (mh * 2 + m2) * 16; const float* lp = !xin_p ? base + (size_t)rr * 1024 : (u.pm < 256 ? xin_p + (size_t)rr * 1024 : (u.pm < 260 ? xin_s + (size_t)(rr - NS0) * 1024 : xin_m + (size_t)fr * 1024));
;                             xv[m2][bj][n] = *(const f32x4*)(lp + colb + bj * 128 + n * 16); }
; #pragma unroll
;                 for (int m2 = 0; m2 < 2; ++m2) { const int m = mh * 2 + m2, row = rowb + ai * 128 + m * 16; float* rp = base + (size_t)row * 1024 + colb; float ss = 0.f;
; #pragma unroll
;                     for (int bj = 0; bj < 2; ++bj)
; #pragma unroll
;                         for (int n = 0; n < 2; ++n) { const f32x4 v = xv[m2][bj][n] + acc[ai][bj][m][n]; *(f32x4*)(rp + bj * 128 + n * 16) = v;
;                             if (XB) { u32x2 o; o[0] = pk2(v[0], v[1]); o[1] = pk2(v[2], v[3]); *(u32x2*)(XB + (size_t)row * 1024 + colb + bj * 128 + n * 16) = o; ss += (v[0] * v[0] + v[1] * v[1]) + (v[2] * v[2] + v[3] * v[3]); } }
;                     if (XB) { ss += __shfl_xor(ss, 16); ss += __shfl_xor(ss, 32); if (fq == 0) __hip_atomic_fetch_add(ssq + row, ss, __ATOMIC_RELAXED, __HIP_MEMORY_SCOPE_AGENT); } } }
	s_cmpk_lt_i32 s46, 0x104
	s_cselect_b64 vcc, -1, 0
	s_and_b64 s[6:7], vcc, exec
	v_readlane_b32 s6, v255, 30
	v_readlane_b32 s7, v255, 31
	s_load_dwordx2 s[6:7], s[6:7], 0x8
	v_lshl_add_u32 v182, s46, 8, v1
	v_ashrrev_i32_e32 v183, 31, v182
	v_lshlrev_b64 v[198:199], 12, v[182:183]
	s_cselect_b32 s37, s21, s57
	s_waitcnt lgkmcnt(0)
	v_lshl_add_u64 v[184:185], s[6:7], 0, v[198:199]
	s_brev_b32 s6, 15
	s_mov_b32 s7, -1
	s_cselect_b32 s36, s20, s56
	s_cmpk_lt_i32 s46, 0x100
	v_lshl_add_u64 v[130:131], v[184:185], 0, s[6:7]
	v_lshl_or_b32 v176, s47, 8, v158
	s_cselect_b64 s[46:47], -1, 0
	v_lshl_add_u64 v[132:133], s[18:19], 0, v[198:199]
	v_cndmask_b32_e32 v131, v151, v131, vcc
	v_cndmask_b32_e32 v130, v150, v130, vcc
	v_ashrrev_i32_e32 v177, 31, v176
	v_lshl_add_u64 v[134:135], s[36:37], 0, v[198:199]
	v_cndmask_b32_e64 v130, v130, v132, s[46:47]
	v_cndmask_b32_e64 v131, v131, v133, s[46:47]
	v_lshlrev_b64 v[180:181], 2, v[176:177]
	v_cndmask_b32_e64 v131, v131, v135, s[42:43]
	v_cndmask_b32_e64 v130, v130, v134, s[42:43]
	v_lshl_add_u64 v[130:131], v[130:131], 0, v[180:181]
	global_load_dwordx4 v[190:193], v[130:131], off
	global_load_dwordx4 v[194:197], v[130:131], off offset:64
	global_load_dwordx4 v[216:219], v[130:131], off offset:512
	global_load_dwordx4 v[220:223], v[130:131], off offset:576
	v_or_b32_e32 v186, 16, v182
	s_mov_b32 s6, 0xf0010000
	s_mov_b32 s7, -1
	v_ashrrev_i32_e32 v187, 31, v186
	v_lshl_add_u64 v[130:131], v[184:185], 0, s[6:7]
	v_lshlrev_b64 v[188:189], 12, v[186:187]
	v_lshl_add_u64 v[132:133], s[18:19], 0, v[188:189]
	v_cndmask_b32_e32 v131, v151, v131, vcc
	v_cndmask_b32_e32 v130, v150, v130, vcc
	v_lshl_add_u64 v[134:135], s[36:37], 0, v[188:189]
	v_cndmask_b32_e64 v130, v130, v132, s[46:47]
	v_cndmask_b32_e64 v131, v131, v133, s[46:47]
	v_cndmask_b32_e64 v131, v131, v135, s[42:43]
	v_cndmask_b32_e64 v130, v130, v134, s[42:43]
	v_lshl_add_u64 v[130:131], v[130:131], 0, v[180:181]
	global_load_dwordx4 v[142:145], v[130:131], off
	global_load_dwordx4 v[138:141], v[130:131], off offset:64
	global_load_dwordx4 v[134:137], v[130:131], off offset:512
	s_nop 0
	global_load_dwordx4 v[130:133], v[130:131], off offset:576
	v_lshl_add_u64 v[178:179], s[36:37], 0, v[180:181]
	v_lshl_add_u64 v[198:199], v[178:179], 0, v[198:199]
	s_waitcnt vmcnt(0)
	v_pk_add_f32 v[128:129], v[128:129], v[192:193]
	v_pk_add_f32 v[126:127], v[126:127], v[190:191]
	global_store_dwordx4 v[198:199], v[126:129], off
	v_cvt_pk_bf16_f32 v190, v126, v127
	v_lshlrev_b64 v[192:193], 11, v[182:183]
	v_lshl_add_u64 v[192:193], s[24:25], 0, v[192:193]
	v_mul_f32_e32 v127, v127, v127
	v_fmac_f32_e32 v127, v126, v126
	v_mul_f32_e32 v126, v129, v129
	v_lshl_add_u64 v[192:193], v[176:177], 1, v[192:193]
	v_fmac_f32_e32 v126, v128, v128
	v_pk_add_f32 v[124:125], v[124:125], v[196:197]
	v_pk_add_f32 v[122:123], v[122:123], v[194:195]
	v_cvt_pk_bf16_f32 v191, v128, v129
	global_store_dwordx2 v[192:193], v[190:191], off
	v_add_f32_e32 v128, v127, v126
	global_store_dwordx4 v[198:199], v[122:125], off offset:64
	v_cvt_pk_bf16_f32 v126, v122, v123
	v_pk_add_f32 v[120:121], v[120:121], v[218:219]
	v_pk_add_f32 v[118:119], v[118:119], v[216:217]
	v_mul_f32_e32 v123, v123, v123
	v_fmac_f32_e32 v123, v122, v122
	v_mul_f32_e32 v122, v125, v125
	v_fmac_f32_e32 v122, v124, v124
	v_add_f32_e32 v122, v123, v122
	v_cvt_pk_bf16_f32 v127, v124, v125
	global_store_dwordx2 v[192:193], v[126:127], off offset:32
	v_add_f32_e32 v124, v128, v122
	global_store_dwordx4 v[198:199], v[118:121], off offset:512
	v_cvt_pk_bf16_f32 v122, v118, v119
	v_pk_add_f32 v[116:117], v[116:117], v[222:223]
	v_pk_add_f32 v[114:115], v[114:115], v[220:221]
	v_mul_f32_e32 v119, v119, v119
	v_fmac_f32_e32 v119, v118, v118
	v_mul_f32_e32 v118, v121, v121
	v_fmac_f32_e32 v118, v120, v120
	v_add_f32_e32 v118, v119, v118
	v_cvt_pk_bf16_f32 v123, v120, v121
	global_store_dwordx2 v[192:193], v[122:123], off offset:256
	v_add_f32_e32 v120, v124, v118
	global_store_dwordx4 v[198:199], v[114:117], off offset:576
	v_cvt_pk_bf16_f32 v118, v114, v115
	v_cvt_pk_bf16_f32 v119, v116, v117
	global_store_dwordx2 v[192:193], v[118:119], off offset:288
	s_nop 0
	v_mul_f32_e32 v115, v115, v115
	v_fmac_f32_e32 v115, v114, v114
	v_mul_f32_e32 v114, v117, v117
	v_fmac_f32_e32 v114, v116, v116
	v_and_b32_e32 v116, 64, v205
	v_add_f32_e32 v114, v115, v114
	v_xor_b32_e32 v115, 16, v205
	v_add_u32_e32 v117, 64, v116
	v_cmp_lt_i32_e64 s[48:49], v115, v117
	v_add_f32_e32 v114, v120, v114
	s_nop 0
	v_cndmask_b32_e64 v115, v205, v115, s[48:49]
	v_lshlrev_b32_e32 v120, 2, v115
	ds_bpermute_b32 v115, v120, v114
	s_waitcnt lgkmcnt(0)
	v_add_f32_e32 v116, v114, v115
	v_xor_b32_e32 v114, 32, v205
	v_cmp_lt_i32_e64 s[48:49], v114, v117
	s_nop 1
	v_cndmask_b32_e64 v114, v205, v114, s[48:49]
	v_lshlrev_b32_e32 v121, 2, v114
	ds_bpermute_b32 v117, v121, v116
	v_lshl_add_u64 v[114:115], v[182:183], 2, s[26:27]
	s_and_saveexec_b64 s[48:49], s[40:41]
	s_cbranch_execz .LBB0_123
	s_waitcnt lgkmcnt(0)
	v_add_f32_e32 v116, v116, v117
	global_atomic_add_f32 v[114:115], v116, off

;     __device__ bool next(int i, Unit& u) const {
;         const long L = (long)i * G + c; if (L >= nwg) return false;
;         int wgid = (int)L; { const int q = nwg / NXCD, r = nwg % NXCD, xcd = wgid % NXCD, off = wgid / NXCD; wgid = (xcd < r ? xcd * (q + 1) : r * (q + 1) + (xcd - r) * q) + off; }
;         const int nig = WGM * nN, gid = wgid / nig, fm = gid * WGM, gsz = (nM - fm) < WGM ? (nM - fm) : WGM;
;         u.pm = fm + ((wgid % nig) % gsz); u.pn = (wgid % nig) / gsz; return true;
;     }
; template <class Epi>
; __device__ __forceinline__ void gemm_phase(LAS unsigned char* lds, const Gemm g, const StaticOrder& S, const Epi& E) {
;     const int tid = ltid(), wid = __builtin_amdgcn_readfirstlane(tid >> 6), lane = tid & 63, wr = wid >> 2, wc = wid & 3, fr = lane & 15, fq = lane >> 4;
;     const int K = g.K, nt = K / BK;
;     unsigned voffA[2], voffB[2];
; #pragma unroll
;     for (int i = 0; i < 2; ++i) { int R, C; stage_rc(tid * 16 + i * 8192, R, C); voffA[i] = (unsigned)(R * g.lda + C) * 2u; voffB[i] = (unsigned)(R * g.ldb + C) * 2u; }
;     const size_t kstep = (size_t)(BK * 2);
;     const size_t hstepA = (size_t)HALF * g.lda * 2, hstepB = (size_t)HALF * g.ldb * 2;
;     const size_t tstepA = 2 * hstepA, tstepB = 2 * hstepB;
;     const unsigned ldsw = (unsigned)wid * 1024u;
;     const int aoff = lds_byte(wr * 64 + fr, fq * 8), boff = lds_byte(wc * 32 + fr, fq * 8);
;     ...
;     Unit cur, nxt; int ui = 0;
;     if (!S.next(0, cur)) return;
;     f32x4 acc[2][2][4][2];
; #pragma unroll
;     for (int a = 0; a < 2; ++a)
; #pragma unroll
;         for (int b = 0; b < 2; ++b)
; #pragma unroll
;             for (int m = 0; m < 4; ++m)
; #pragma unroll
;                 for (int n = 0; n < 2; ++n) acc[a][b][m][n] = (f32x4){0.f, 0.f, 0.f, 0.f};
;     bf16x8 At[4][2], B0[2][2], B1[2][2];
;     const char* cA = (const char*)g.A + (size_t)cur.pm * tstepA; const char* cB = (const char*)g.Bt + (size_t)cur.pn * tstepB;
;     PG8_STAGE(PG8_SB(0, 0), cB, voffB); PG8_STAGE(PG8_SA(0, 0), cA, voffA); PG8_STAGE(PG8_SB(0, 1), cB + hstepB, voffB); PG8_STAGE(PG8_SA(0, 1), cA + hstepA, voffA);
;     if (wr == 1) PG8_BAR;
; __global__ __launch_bounds__(512, 2) void mega(Params pk) {
;     ...
;                 EpiMix E; pg8::Gemm g;
;                 if (call == 0) { E = EpiMix{HB, G, XBC, 0}; g = pg8::Gemm{Z, (const bf16_t*)(ws + W_LA), NROWS, 1024, 1024, 1024, 1024}; }
.LBB0_148:
	s_and_b64 s[6:7], s[20:21], exec
	v_readlane_b32 s6, v255, 32
	v_readlane_b32 s8, v255, 36
	v_readlane_b32 s7, v255, 33
	v_readlane_b32 s9, v255, 37
	s_cselect_b32 s55, s7, s9
	s_cselect_b32 s56, s6, s8
	v_readlane_b32 s8, v255, 30
	v_readlane_b32 s9, v255, 31
	s_load_dwordx2 s[8:9], s[8:9], 0x118
	v_bfe_i32 v3, v20, 27, 1
	v_lshlrev_b32_e32 v1, 4, v20
	v_lshrrev_b32_e32 v3, 22, v3
	v_add_u32_e32 v3, v1, v3
	s_mov_b32 s6, 0x1100000
	v_and_b32_e32 v3, 0xfffffc00, v3
	s_cselect_b32 s6, s6, 0x1300000
	v_sub_u32_e32 v3, v1, v3
	s_waitcnt lgkmcnt(0)
	s_add_u32 s57, s8, s6
	v_ashrrev_i32_e32 v2, 31, v20
	v_lshrrev_b32_e32 v4, 4, v3
	s_addc_u32 s58, s9, 0
	v_lshrrev_b32_e32 v2, 26, v2
	v_bitop3_b32 v4, v4, v3, 32 bitop3:0x6c
	v_ashrrev_i32_e32 v3, 31, v3
	s_and_b64 s[6:7], s[20:21], exec
	v_add_u32_e32 v2, v20, v2
	v_lshrrev_b32_e32 v3, 26, v3
	s_movk_i32 s6, 0x200
	v_ashrrev_i32_e32 v2, 6, v2
	v_add_u32_e32 v3, v4, v3
	s_cselect_b32 s9, 0x400, s6
	s_ashr_i32 s8, s54, 6
	v_lshlrev_b32_e32 v5, 3, v2
	v_ashrrev_i32_e32 v3, 6, v3
	v_lshlrev_b32_e32 v2, 5, v2
	v_and_b32_e32 v14, 32, v2
	v_mul_i32_i24_e32 v2, 64, v3
	s_and_b64 s[6:7], s[20:21], exec
	v_and_b32_e32 v5, 0x7ffffff0, v5
	v_sub_u32_e32 v2, v4, v2
	s_cselect_b32 s6, 10, 9
	v_ashrrev_i16_sdwa v2, v201, sext(v2) dst_sel:DWORD dst_unused:UNUSED_PAD src0_sel:DWORD src1_sel:BYTE_0
	v_add_lshl_u32 v16, v3, v5, s6
	v_bfe_i32 v15, v2, 0, 16
	v_or_b32_e32 v2, v16, v14
	v_add_u32_e32 v1, 0x2000, v1
	v_add_lshl_u32 v176, v2, v15, 1
	v_ashrrev_i32_e32 v2, 31, v1
	v_lshrrev_b32_e32 v2, 22, v2
	v_add_u32_e32 v2, v1, v2
	v_ashrrev_i32_e32 v2, 10, v2
	v_mul_i32_i24_e32 v3, 0x400, v2
	v_sub_u32_e32 v1, v1, v3
	v_lshrrev_b32_e32 v3, 4, v1
	v_bitop3_b32 v1, v3, v1, 32 bitop3:0x6c
	v_ashrrev_i32_e32 v4, 31, v1
	v_lshrrev_b32_e32 v4, 26, v4
	v_lshlrev_b32_e32 v3, 3, v2
	v_add_u32_e32 v4, v1, v4
	v_and_b32_e32 v3, 0x7ffffff0, v3
	v_ashrrev_i32_e32 v5, 6, v4
	s_ashr_i32 s10, s54, 8
	s_lshl_b32 s84, s9, 8
	s_lshl_b32 s59, s8, 10
	s_ashr_i32 s37, s36, 31
	v_add_lshl_u32 v19, v5, v3, s6
	s_and_b64 s[6:7], s[20:21], exec
	s_cselect_b32 s60, 19, 18
	s_ashr_i32 s35, s34, 31
	v_lshlrev_b32_e32 v2, 5, v2
	s_lshl_b64 s[6:7], s[36:37], s60
	s_lshl_b64 s[26:27], s[34:35], s60
	v_and_b32_e32 v17, 32, v2
	v_and_b32_e32 v2, 0xc0, v4
	s_add_u32 s44, s57, s26
	v_sub_u32_e32 v1, v1, v2
	s_addc_u32 s45, s58, s27
	s_add_i32 s35, s59, 0
	v_ashrrev_i16_sdwa v1, v201, sext(v1) dst_sel:DWORD dst_unused:UNUSED_PAD src0_sel:DWORD src1_sel:BYTE_0
	s_add_i32 m0, s35, 0x10000
	v_bfe_i32 v18, v1, 0, 16
	v_or_b32_e32 v1, v19, v17
	global_load_lds_dwordx4 v176, s[44:45]
	s_add_i32 m0, s35, 0x12000
	v_add_lshl_u32 v178, v1, v18, 1
	s_add_u32 s42, s56, s6
	global_load_lds_dwordx4 v178, s[44:45]
	s_addc_u32 s43, s55, s7
	s_mov_b32 m0, s35
	s_add_i32 s37, s35, 0x2000
	global_load_lds_dwordx4 v176, s[42:43]
	s_mov_b32 m0, s37
	s_add_u32 s6, s44, s84
	global_load_lds_dwordx4 v178, s[42:43]
	s_addc_u32 s7, s45, 0
	s_add_i32 m0, s35, 0x14000
	v_mov_b32_e32 v177, v0
	v_mov_b32_e32 v179, v0
	global_load_lds_dwordx4 v176, s[6:7]
	s_add_i32 m0, s35, 0x16000
	v_lshl_add_u64 v[10:11], s[6:7], 0, v[176:177]
	v_lshl_add_u64 v[12:13], s[6:7], 0, v[178:179]
	global_load_lds_dwordx4 v178, s[6:7]
	s_add_u32 s6, s42, s84
	s_addc_u32 s7, s43, 0
	s_add_i32 s61, s35, 0x4000
	s_mov_b32 m0, s61
	s_add_i32 s62, s35, 0x6000
	global_load_lds_dwordx4 v176, s[6:7]
	s_mov_b32 m0, s62
	v_lshl_add_u64 v[2:3], s[44:45], 0, v[176:177]
	global_load_lds_dwordx4 v178, s[6:7]
	v_lshl_add_u64 v[4:5], s[44:45], 0, v[178:179]
	v_lshl_add_u64 v[6:7], s[42:43], 0, v[176:177]
	v_lshl_add_u64 v[8:9], s[42:43], 0, v[178:179]
	s_cmp_lg_u32 s10, 1
	s_cbranch_scc1 .LBB0_150
	s_barrier
	s_setprio 1

; #define PG8_STAGE(bufoff, gbase, voff) do { _Pragma("unroll") for (int _i = 0; _i < 2; ++_i) \
;         __builtin_amdgcn_global_load_lds((const unsigned*)((const char*)(gbase) + (voff)[_i]), (LAS unsigned*)(lds + (bufoff) + ldsw + _i * 8192), 16, 0, 0); } while (0)
; #define PG8_LDA(dst, b, h) do { _Pragma("unroll") for (int m = 0; m < 4; ++m) _Pragma("unroll") for (int k = 0; k < 2; ++k) dst[m][k] = *(const LAS bf16x8*)(lds + PG8_SA(b, h) + aoff + m * 2048 + k * 1024); } while (0)
; #define PG8_LDB(dst, b, h) do { _Pragma("unroll") for (int n = 0; n < 2; ++n) _Pragma("unroll") for (int k = 0; k < 2; ++k) dst[n][k] = *(const LAS bf16x8*)(lds + PG8_SB(b, h) + boff + n * 2048 + k * 1024); } while (0)
; #define PG8_MMA(ai, bj, At, Bt) do { __builtin_amdgcn_s_setprio(1); _Pragma("unroll") for (int m = 0; m < 4; ++m) _Pragma("unroll") for (int n = 0; n < 2; ++n) _Pragma("unroll") for (int k = 0; k < 2; ++k) \
;         acc[ai][bj][m][n] = __builtin_amdgcn_mfma_f32_16x16x32_bf16(Bt[n][k], At[m][k], acc[ai][bj][m][n], 0, 0, 0); __builtin_amdgcn_s_setprio(0); } while (0)
; #define PG8_WAIT_L(n) asm volatile("s_waitcnt lgkmcnt(" #n ")" ::: "memory")
; #define PG8_BAR __builtin_amdgcn_s_barrier()
; #define PG8_SCHED __builtin_amdgcn_sched_barrier(0)
; template <class Epi>
; __device__ __forceinline__ void gemm_phase(LAS unsigned char* lds, const Gemm g, const StaticOrder& S, const Epi& E) {
;     ...
;             const char* a1 = cA + (size_t)(t + 1) * kstep;
;             const char* a2 = last ? nA : cA + (size_t)(t + 2) * kstep; const char* b2 = last ? nB : cB + (size_t)(t + 2) * kstep;
;             const char* a3 = a2 + kstep; const char* b3 = b2 + kstep;
;             PG8_LDB(B0, 0, 0); PG8_SCHED; PG8_LDA(At, 0, 0); PG8_STAGE(PG8_SA(1, 1), a1 + hstepA, voffA);
;             PG8_WAIT_L(8); PG8_BAR; PG8_WAIT_L(0); PG8_MMA(0, 0, At, B0); PG8_BAR; PG8_SCHED;
;             PG8_LDB(B1, 0, 1); PG8_STAGE(PG8_SB(0, 0), b2, voffB);
;             PG8_BAR; PG8_WAIT_L(0); PG8_MMA(0, 1, At, B1); PG8_BAR;
;             PG8_LDA(At, 0, 1); PG8_STAGE(PG8_SA(0, 0), a2, voffA);
;             PG8_BAR; PG8_WAIT_L(0); PG8_MMA(1, 0, At, B0); PG8_BAR; PG8_SCHED;
.LBB0_155:
	s_add_i32 s31, s11, 2
	s_add_u32 s6, s42, 0x80
	s_addc_u32 s7, s43, 0
	s_add_i32 s33, 0, 0x10000
	v_add_u32_e32 v142, s33, v157
	ds_read_b128 v[130:133], v142
	ds_read_b128 v[134:137], v142 offset:1024
	ds_read_b128 v[138:141], v142 offset:2048
	ds_read_b128 v[142:145], v142 offset:3072
	s_cmp_eq_u32 s10, s11
	s_cselect_b32 s45, s49, s7
	s_cselect_b32 s44, s48, s6
	s_cselect_b32 s53, s51, s9
	s_cselect_b32 s52, s50, s8
	v_lshl_add_u64 v[154:155], s[42:43], 0, v[180:181]
	s_add_i32 m0, s35, 0xc000
	ds_read_b128 v[146:149], v171
	ds_read_b128 v[150:153], v171 offset:1024
	ds_read_b128 v[184:187], v171 offset:2048
	ds_read_b128 v[188:191], v171 offset:3072
	ds_read_b128 v[192:195], v171 offset:4096
	ds_read_b128 v[196:199], v171 offset:5120
	ds_read_b128 v[216:219], v171 offset:6144
	ds_read_b128 v[220:223], v171 offset:7168
	global_load_lds_dwordx4 v[154:155], off
	v_lshl_add_u64 v[154:155], s[42:43], 0, v[182:183]
	s_add_i32 m0, s35, 0xe000
	s_nop 0
	global_load_lds_dwordx4 v[154:155], off
	s_waitcnt lgkmcnt(8)
	s_barrier
	s_waitcnt lgkmcnt(0)
	s_waitcnt lgkmcnt(0)
	v_mfma_f32_16x16x32_bf16 v[126:129], v[130:133], v[146:149], v[126:129]
	v_mfma_f32_16x16x32_bf16 v[122:125], v[138:141], v[146:149], v[122:125]
	v_mfma_f32_16x16x32_bf16 v[110:113], v[130:133], v[184:187], v[110:113]
	v_mfma_f32_16x16x32_bf16 v[106:109], v[138:141], v[184:187], v[106:109]
	v_mfma_f32_16x16x32_bf16 v[94:97], v[130:133], v[192:195], v[94:97]
	v_mfma_f32_16x16x32_bf16 v[90:93], v[138:141], v[192:195], v[90:93]
	v_mfma_f32_16x16x32_bf16 v[78:81], v[130:133], v[216:219], v[78:81]
	v_mfma_f32_16x16x32_bf16 v[74:77], v[138:141], v[216:219], v[74:77]
	v_mfma_f32_16x16x32_bf16 v[126:129], v[134:137], v[150:153], v[126:129]
	v_mfma_f32_16x16x32_bf16 v[122:125], v[142:145], v[150:153], v[122:125]
	v_mfma_f32_16x16x32_bf16 v[110:113], v[134:137], v[188:191], v[110:113]
	v_mfma_f32_16x16x32_bf16 v[106:109], v[142:145], v[188:191], v[106:109]
	v_mfma_f32_16x16x32_bf16 v[94:97], v[134:137], v[196:199], v[94:97]
	v_mfma_f32_16x16x32_bf16 v[90:93], v[142:145], v[196:199], v[90:93]
	v_mfma_f32_16x16x32_bf16 v[78:81], v[134:137], v[220:223], v[78:81]
	v_mfma_f32_16x16x32_bf16 v[74:77], v[142:145], v[220:223], v[74:77]
	s_barrier
	s_add_i32 s11, 0, 0x14000
	v_add_u32_e32 v154, s11, v157
	s_add_i32 s6, s33, s59
	ds_read_b128 v[224:227], v154
	ds_read_b128 v[228:231], v154 offset:1024
	ds_read_b128 v[232:235], v154 offset:2048
	ds_read_b128 v[236:239], v154 offset:3072
	v_lshl_add_u64 v[154:155], s[52:53], 0, v[176:177]
	s_mov_b32 m0, s6
	v_lshl_add_u64 v[212:213], s[52:53], 0, v[178:179]
	global_load_lds_dwordx4 v[154:155], off
	s_add_i32 m0, s6, 0x2000
	s_nop 0
	global_load_lds_dwordx4 v[212:213], off
	s_barrier
	s_waitcnt lgkmcnt(0)
	s_waitcnt lgkmcnt(0)
	v_mfma_f32_16x16x32_bf16 v[118:121], v[224:227], v[146:149], v[118:121]
	v_mfma_f32_16x16x32_bf16 v[114:117], v[232:235], v[146:149], v[114:117]
	v_mfma_f32_16x16x32_bf16 v[102:105], v[224:227], v[184:187], v[102:105]
	v_mfma_f32_16x16x32_bf16 v[98:101], v[232:235], v[184:187], v[98:101]
	v_mfma_f32_16x16x32_bf16 v[86:89], v[224:227], v[192:195], v[86:89]
	v_mfma_f32_16x16x32_bf16 v[82:85], v[232:235], v[192:195], v[82:85]
	v_mfma_f32_16x16x32_bf16 v[70:73], v[224:227], v[216:219], v[70:73]
	v_mfma_f32_16x16x32_bf16 v[66:69], v[232:235], v[216:219], v[66:69]
	v_mfma_f32_16x16x32_bf16 v[118:121], v[228:231], v[150:153], v[118:121]
	v_mfma_f32_16x16x32_bf16 v[114:117], v[236:239], v[150:153], v[114:117]
	v_mfma_f32_16x16x32_bf16 v[102:105], v[228:231], v[188:191], v[102:105]
	v_mfma_f32_16x16x32_bf16 v[98:101], v[236:239], v[188:191], v[98:101]
	v_mfma_f32_16x16x32_bf16 v[86:89], v[228:231], v[196:199], v[86:89]
	v_mfma_f32_16x16x32_bf16 v[82:85], v[236:239], v[196:199], v[82:85]
	v_mfma_f32_16x16x32_bf16 v[70:73], v[228:231], v[220:223], v[70:73]
	v_mfma_f32_16x16x32_bf16 v[66:69], v[236:239], v[220:223], v[66:69]
	s_mov_b32 m0, s35
	v_lshl_add_u64 v[240:241], s[44:45], 0, v[176:177]
	s_barrier
	ds_read_b128 v[146:149], v171 offset:16384
	ds_read_b128 v[150:153], v171 offset:17408
	ds_read_b128 v[184:187], v171 offset:18432
	ds_read_b128 v[188:191], v171 offset:19456
	ds_read_b128 v[192:195], v171 offset:20480
	ds_read_b128 v[196:199], v171 offset:21504
	ds_read_b128 v[216:219], v171 offset:22528
	ds_read_b128 v[220:223], v171 offset:23552
	global_load_lds_dwordx4 v[240:241], off
	v_lshl_add_u64 v[242:243], s[44:45], 0, v[178:179]
	s_mov_b32 m0, s37
	s_nop 0
	global_load_lds_dwordx4 v[242:243], off
	s_barrier
	s_waitcnt lgkmcnt(0)
	s_waitcnt lgkmcnt(0)
	v_mfma_f32_16x16x32_bf16 v[62:65], v[130:133], v[146:149], v[62:65]
	v_mfma_f32_16x16x32_bf16 v[58:61], v[138:141], v[146:149], v[58:61]
	v_mfma_f32_16x16x32_bf16 v[46:49], v[130:133], v[184:187], v[46:49]
	v_mfma_f32_16x16x32_bf16 v[42:45], v[138:141], v[184:187], v[42:45]
	v_mfma_f32_16x16x32_bf16 v[30:33], v[130:133], v[192:195], v[30:33]
	v_mfma_f32_16x16x32_bf16 v[26:29], v[138:141], v[192:195], v[26:29]
	v_mfma_f32_16x16x32_bf16 v[14:17], v[130:133], v[216:219], v[14:17]
	v_mfma_f32_16x16x32_bf16 v[10:13], v[138:141], v[216:219], v[10:13]
	v_mfma_f32_16x16x32_bf16 v[62:65], v[134:137], v[150:153], v[62:65]
	v_mfma_f32_16x16x32_bf16 v[58:61], v[142:145], v[150:153], v[58:61]
	v_mfma_f32_16x16x32_bf16 v[46:49], v[134:137], v[188:191], v[46:49]
	v_mfma_f32_16x16x32_bf16 v[42:45], v[142:145], v[188:191], v[42:45]
	v_mfma_f32_16x16x32_bf16 v[30:33], v[134:137], v[196:199], v[30:33]
	v_mfma_f32_16x16x32_bf16 v[26:29], v[142:145], v[196:199], v[26:29]
	v_mfma_f32_16x16x32_bf16 v[14:17], v[134:137], v[220:223], v[14:17]
	v_mfma_f32_16x16x32_bf16 v[10:13], v[142:145], v[220:223], v[10:13]
	s_barrier
; #define PG8_STAGE(bufoff, gbase, voff) do { _Pragma("unroll") for (int _i = 0; _i < 2; ++_i) \
;         __builtin_amdgcn_global_load_lds((const unsigned*)((const char*)(gbase) + (voff)[_i]), (LAS unsigned*)(lds + (bufoff) + ldsw + _i * 8192), 16, 0, 0); } while (0)
; #define PG8_LDA(dst, b, h) do { _Pragma("unroll") for (int m = 0; m < 4; ++m) _Pragma("unroll") for (int k = 0; k < 2; ++k) dst[m][k] = *(const LAS bf16x8*)(lds + PG8_SA(b, h) + aoff + m * 2048 + k * 1024); } while (0)
; #define PG8_LDB(dst, b, h) do { _Pragma("unroll") for (int n = 0; n < 2; ++n) _Pragma("unroll") for (int k = 0; k < 2; ++k) dst[n][k] = *(const LAS bf16x8*)(lds + PG8_SB(b, h) + boff + n * 2048 + k * 1024); } while (0)
; #define PG8_MMA(ai, bj, At, Bt) do { __builtin_amdgcn_s_setprio(1); _Pragma("unroll") for (int m = 0; m < 4; ++m) _Pragma("unroll") for (int n = 0; n < 2; ++n) _Pragma("unroll") for (int k = 0; k < 2; ++k) \
;         acc[ai][bj][m][n] = __builtin_amdgcn_mfma_f32_16x16x32_bf16(Bt[n][k], At[m][k], acc[ai][bj][m][n], 0, 0, 0); __builtin_amdgcn_s_setprio(0); } while (0)
; #define PG8_WAIT_V(n) asm volatile("s_waitcnt vmcnt(" #n ")" ::: "memory")
; #define PG8_WAIT_L(n) asm volatile("s_waitcnt lgkmcnt(" #n ")" ::: "memory")
; #define PG8_BAR __builtin_amdgcn_s_barrier()
; #define PG8_SCHED __builtin_amdgcn_sched_barrier(0)
; template <class Epi>
; __device__ __forceinline__ void gemm_phase(LAS unsigned char* lds, const Gemm g, const StaticOrder& S, const Epi& E) {
;     ...
;             PG8_STAGE(PG8_SB(0, 1), b2 + hstepB, voffB);
;             PG8_WAIT_V(6); PG8_BAR; PG8_MMA(1, 1, At, B1); PG8_BAR;
;             PG8_LDB(B0, 1, 0); PG8_SCHED; PG8_LDA(At, 1, 0); PG8_STAGE(PG8_SA(0, 1), a2 + hstepA, voffA);
;             PG8_WAIT_L(8); PG8_BAR; PG8_WAIT_L(0); PG8_MMA(0, 0, At, B0); PG8_BAR; PG8_SCHED;
;             PG8_LDB(B1, 1, 1); PG8_STAGE(PG8_SB(1, 0), b3, voffB);
;             PG8_BAR; PG8_WAIT_L(0); PG8_MMA(0, 1, At, B1); PG8_BAR;
	s_add_u32 s6, s52, s84
	s_addc_u32 s7, s53, 0
	s_add_i32 s11, s11, s59
	v_lshl_add_u64 v[244:245], s[6:7], 0, v[176:177]
	s_mov_b32 m0, s11
	v_lshl_add_u64 v[246:247], s[6:7], 0, v[178:179]
	global_load_lds_dwordx4 v[244:245], off
	s_add_i32 m0, s11, 0x2000
	s_nop 0
	global_load_lds_dwordx4 v[246:247], off
	s_waitcnt vmcnt(6)
	s_barrier
	v_mfma_f32_16x16x32_bf16 v[54:57], v[224:227], v[146:149], v[54:57]
	v_mfma_f32_16x16x32_bf16 v[50:53], v[232:235], v[146:149], v[50:53]
	v_mfma_f32_16x16x32_bf16 v[38:41], v[224:227], v[184:187], v[38:41]
	v_mfma_f32_16x16x32_bf16 v[34:37], v[232:235], v[184:187], v[34:37]
	v_mfma_f32_16x16x32_bf16 v[22:25], v[224:227], v[192:195], v[22:25]
	v_mfma_f32_16x16x32_bf16 v[18:21], v[232:235], v[192:195], v[18:21]
	v_mfma_f32_16x16x32_bf16 v[6:9], v[224:227], v[216:219], v[6:9]
	v_mfma_f32_16x16x32_bf16 v[2:5], v[232:235], v[216:219], v[2:5]
	v_mfma_f32_16x16x32_bf16 v[54:57], v[228:231], v[150:153], v[54:57]
	v_mfma_f32_16x16x32_bf16 v[50:53], v[236:239], v[150:153], v[50:53]
	v_mfma_f32_16x16x32_bf16 v[38:41], v[228:231], v[188:191], v[38:41]
	v_mfma_f32_16x16x32_bf16 v[34:37], v[236:239], v[188:191], v[34:37]
	v_mfma_f32_16x16x32_bf16 v[22:25], v[228:231], v[196:199], v[22:25]
	v_mfma_f32_16x16x32_bf16 v[18:21], v[236:239], v[196:199], v[18:21]
	v_mfma_f32_16x16x32_bf16 v[6:9], v[228:231], v[220:223], v[6:9]
	v_mfma_f32_16x16x32_bf16 v[2:5], v[236:239], v[220:223], v[2:5]
	s_add_i32 s11, 0, 0x18000
	v_add_u32_e32 v142, s11, v157
	s_barrier
	ds_read_b128 v[130:133], v142
	ds_read_b128 v[134:137], v142 offset:1024
	ds_read_b128 v[138:141], v142 offset:2048
	ds_read_b128 v[142:145], v142 offset:3072
	s_add_u32 s6, s44, s84
	s_addc_u32 s7, s45, 0
	s_mov_b32 m0, s61
	v_lshl_add_u64 v[224:225], s[6:7], 0, v[176:177]
	ds_read_b128 v[146:149], v171 offset:32768
	ds_read_b128 v[150:153], v171 offset:33792
	ds_read_b128 v[184:187], v171 offset:34816
	ds_read_b128 v[188:191], v171 offset:35840
	ds_read_b128 v[192:195], v171 offset:36864
	ds_read_b128 v[196:199], v171 offset:37888
	ds_read_b128 v[216:219], v171 offset:38912
	ds_read_b128 v[220:223], v171 offset:39936
	global_load_lds_dwordx4 v[224:225], off
	v_lshl_add_u64 v[224:225], s[6:7], 0, v[178:179]
	s_mov_b32 m0, s62
	s_nop 0
	global_load_lds_dwordx4 v[224:225], off
	s_waitcnt lgkmcnt(8)
	s_barrier
	s_waitcnt lgkmcnt(0)
	s_waitcnt lgkmcnt(0)
	v_mfma_f32_16x16x32_bf16 v[126:129], v[130:133], v[146:149], v[126:129]
	v_mfma_f32_16x16x32_bf16 v[122:125], v[138:141], v[146:149], v[122:125]
	v_mfma_f32_16x16x32_bf16 v[110:113], v[130:133], v[184:187], v[110:113]
	v_mfma_f32_16x16x32_bf16 v[106:109], v[138:141], v[184:187], v[106:109]
	v_mfma_f32_16x16x32_bf16 v[94:97], v[130:133], v[192:195], v[94:97]
	v_mfma_f32_16x16x32_bf16 v[90:93], v[138:141], v[192:195], v[90:93]
	v_mfma_f32_16x16x32_bf16 v[78:81], v[130:133], v[216:219], v[78:81]
	v_mfma_f32_16x16x32_bf16 v[74:77], v[138:141], v[216:219], v[74:77]
	v_mfma_f32_16x16x32_bf16 v[126:129], v[134:137], v[150:153], v[126:129]
	v_mfma_f32_16x16x32_bf16 v[122:125], v[142:145], v[150:153], v[122:125]
	v_mfma_f32_16x16x32_bf16 v[110:113], v[134:137], v[188:191], v[110:113]
	v_mfma_f32_16x16x32_bf16 v[106:109], v[142:145], v[188:191], v[106:109]
	v_mfma_f32_16x16x32_bf16 v[94:97], v[134:137], v[196:199], v[94:97]
	v_mfma_f32_16x16x32_bf16 v[90:93], v[142:145], v[196:199], v[90:93]
	v_mfma_f32_16x16x32_bf16 v[78:81], v[134:137], v[220:223], v[78:81]
	v_mfma_f32_16x16x32_bf16 v[74:77], v[142:145], v[220:223], v[74:77]
	s_barrier
	s_add_i32 s6, 0, 0x1c000
	s_add_i32 s7, s11, s59
	v_add_u32_e32 v236, s6, v157
	v_lshl_add_u64 v[154:155], v[154:155], 0, s[88:89]
	s_mov_b32 m0, s7
	ds_read_b128 v[224:227], v236
	ds_read_b128 v[228:231], v236 offset:1024
	ds_read_b128 v[232:235], v236 offset:2048
	ds_read_b128 v[236:239], v236 offset:3072
	global_load_lds_dwordx4 v[154:155], off
	v_lshl_add_u64 v[154:155], v[212:213], 0, s[88:89]
	s_add_i32 m0, s7, 0x2000
	s_nop 0
	global_load_lds_dwordx4 v[154:155], off
	s_barrier
	s_waitcnt lgkmcnt(0)
	s_waitcnt lgkmcnt(0)
	v_mfma_f32_16x16x32_bf16 v[118:121], v[224:227], v[146:149], v[118:121]
	v_mfma_f32_16x16x32_bf16 v[114:117], v[232:235], v[146:149], v[114:117]
	v_mfma_f32_16x16x32_bf16 v[102:105], v[224:227], v[184:187], v[102:105]
	v_mfma_f32_16x16x32_bf16 v[98:101], v[232:235], v[184:187], v[98:101]
	v_mfma_f32_16x16x32_bf16 v[86:89], v[224:227], v[192:195], v[86:89]
	v_mfma_f32_16x16x32_bf16 v[82:85], v[232:235], v[192:195], v[82:85]
	v_mfma_f32_16x16x32_bf16 v[70:73], v[224:227], v[216:219], v[70:73]
	v_mfma_f32_16x16x32_bf16 v[66:69], v[232:235], v[216:219], v[66:69]
	v_mfma_f32_16x16x32_bf16 v[118:121], v[228:231], v[150:153], v[118:121]
	v_mfma_f32_16x16x32_bf16 v[114:117], v[236:239], v[150:153], v[114:117]
	v_mfma_f32_16x16x32_bf16 v[102:105], v[228:231], v[188:191], v[102:105]
	v_mfma_f32_16x16x32_bf16 v[98:101], v[236:239], v[188:191], v[98:101]
	v_mfma_f32_16x16x32_bf16 v[86:89], v[228:231], v[196:199], v[86:89]
	v_mfma_f32_16x16x32_bf16 v[82:85], v[236:239], v[196:199], v[82:85]
	v_mfma_f32_16x16x32_bf16 v[70:73], v[228:231], v[220:223], v[70:73]
	v_mfma_f32_16x16x32_bf16 v[66:69], v[236:239], v[220:223], v[66:69]
	s_mov_b32 m0, s65
	v_lshl_add_u64 v[154:155], v[240:241], 0, s[88:89]
	s_barrier
; __device__ __forceinline__ u32x2 ld_l2_u32x2(const void* ptr) { const unsigned long long v = __hip_atomic_load((const unsigned long long*)ptr, __ATOMIC_RELAXED, __HIP_MEMORY_SCOPE_AGENT); u32x2 r; r[0] = (unsigned)v; r[1] = (unsigned)(v >> 32); return r; }
; #define PG8_STAGE(bufoff, gbase, voff) do { _Pragma("unroll") for (int _i = 0; _i < 2; ++_i) \
;         __builtin_amdgcn_global_load_lds((const unsigned*)((const char*)(gbase) + (voff)[_i]), (LAS unsigned*)(lds + (bufoff) + ldsw + _i * 8192), 16, 0, 0); } while (0)
; #define PG8_LDA(dst, b, h) do { _Pragma("unroll") for (int m = 0; m < 4; ++m) _Pragma("unroll") for (int k = 0; k < 2; ++k) dst[m][k] = *(const LAS bf16x8*)(lds + PG8_SA(b, h) + aoff + m * 2048 + k * 1024); } while (0)
; #define PG8_WAIT_V(n) asm volatile("s_waitcnt vmcnt(" #n ")" ::: "memory")
; #define PG8_WAIT_L(n) asm volatile("s_waitcnt lgkmcnt(" #n ")" ::: "memory")
; #define PG8_BAR __builtin_amdgcn_s_barrier()
; #define PG8_SCHED __builtin_amdgcn_sched_barrier(0)
; template <class Epi>
; __device__ __forceinline__ void gemm_phase(LAS unsigned char* lds, const Gemm g, const StaticOrder& S, const Epi& E) {
;     ...
;             PG8_LDA(At, 1, 1); PG8_STAGE(PG8_SA(1, 0), a3, voffA);
;             PG8_BAR; PG8_WAIT_L(0); PG8_MMA(1, 0, At, B0); PG8_BAR; PG8_SCHED;
;             PG8_STAGE(PG8_SB(1, 1), b3 + hstepB, voffB);
;             PG8_WAIT_V(6); PG8_BAR; PG8_MMA(1, 1, At, B1); PG8_BAR;
;     __device__ __forceinline__ void operator()(const f32x4 (&acc)[2][2][4][2], const Unit& u, int wr, int wc, int fr, int fq) const {
;     ...
;             for (int m = 0; m < 4; ++m) { const int row = rowb + ai * 128 + m * 16;
;                 u32x4 gw[2], g1[2], ob[2]; u32x2 rw[2][2];
; #pragma unroll
;                 for (int bj = 0; bj < 2; ++bj) { const int col = colb + bj * 128;
;                     gw[bj] = *(const u32x4*)(G + (size_t)row * 3072 + col);
;                     g1[bj] = (u32x4){0u, 0u, 0u, 0u}; ob[bj] = (u32x4){0u, 0u, 0u, 0u}; rw[bj][0] = (u32x2){0u, 0u}; rw[bj][1] = (u32x2){0u, 0u};
;                     if (OB) { g1[bj] = *(const u32x4*)(G + (size_t)row * 3072 + 1024 + col); ob[bj] = *(const u32x4*)(OB + (size_t)row * 1024 + col); }
;                     if (accum) { rw[bj][0] = ld_l2_u32x2(R + (size_t)row * 1024 + col); rw[bj][1] = ld_l2_u32x2(R + (size_t)row * 1024 + col + 4); } }
	ds_read_b128 v[146:149], v171 offset:49152
	ds_read_b128 v[150:153], v171 offset:50176
	ds_read_b128 v[184:187], v171 offset:51200
	ds_read_b128 v[188:191], v171 offset:52224
	ds_read_b128 v[192:195], v171 offset:53248
	ds_read_b128 v[196:199], v171 offset:54272
	ds_read_b128 v[216:219], v171 offset:55296
	ds_read_b128 v[220:223], v171 offset:56320
	global_load_lds_dwordx4 v[154:155], off
	v_lshl_add_u64 v[154:155], v[242:243], 0, s[88:89]
	s_mov_b32 m0, s66
	s_nop 0
	global_load_lds_dwordx4 v[154:155], off
	s_barrier
	s_waitcnt lgkmcnt(0)
	s_waitcnt lgkmcnt(0)
	v_mfma_f32_16x16x32_bf16 v[62:65], v[130:133], v[146:149], v[62:65]
	v_mfma_f32_16x16x32_bf16 v[58:61], v[138:141], v[146:149], v[58:61]
	v_mfma_f32_16x16x32_bf16 v[46:49], v[130:133], v[184:187], v[46:49]
	v_mfma_f32_16x16x32_bf16 v[42:45], v[138:141], v[184:187], v[42:45]
	v_mfma_f32_16x16x32_bf16 v[30:33], v[130:133], v[192:195], v[30:33]
	v_mfma_f32_16x16x32_bf16 v[26:29], v[138:141], v[192:195], v[26:29]
	v_mfma_f32_16x16x32_bf16 v[14:17], v[130:133], v[216:219], v[14:17]
	v_mfma_f32_16x16x32_bf16 v[10:13], v[138:141], v[216:219], v[10:13]
	v_mfma_f32_16x16x32_bf16 v[62:65], v[134:137], v[150:153], v[62:65]
	v_mfma_f32_16x16x32_bf16 v[58:61], v[142:145], v[150:153], v[58:61]
	v_mfma_f32_16x16x32_bf16 v[46:49], v[134:137], v[188:191], v[46:49]
	v_mfma_f32_16x16x32_bf16 v[42:45], v[142:145], v[188:191], v[42:45]
	v_mfma_f32_16x16x32_bf16 v[30:33], v[134:137], v[196:199], v[30:33]
	v_mfma_f32_16x16x32_bf16 v[26:29], v[142:145], v[196:199], v[26:29]
	v_mfma_f32_16x16x32_bf16 v[14:17], v[134:137], v[220:223], v[14:17]
	v_mfma_f32_16x16x32_bf16 v[10:13], v[142:145], v[220:223], v[10:13]
	s_barrier
	s_add_i32 s6, s6, s59
	v_lshl_add_u64 v[130:131], v[244:245], 0, s[88:89]
	s_mov_b32 m0, s6
	s_nop 0
	global_load_lds_dwordx4 v[130:131], off
	v_lshl_add_u64 v[130:131], v[246:247], 0, s[88:89]
	s_add_i32 m0, s6, 0x2000
	s_nop 0
	global_load_lds_dwordx4 v[130:131], off
	s_waitcnt vmcnt(6)
	s_barrier
	v_mfma_f32_16x16x32_bf16 v[54:57], v[224:227], v[146:149], v[54:57]
	v_mfma_f32_16x16x32_bf16 v[50:53], v[232:235], v[146:149], v[50:53]
	v_mfma_f32_16x16x32_bf16 v[38:41], v[224:227], v[184:187], v[38:41]
	v_mfma_f32_16x16x32_bf16 v[34:37], v[232:235], v[184:187], v[34:37]
	v_mfma_f32_16x16x32_bf16 v[22:25], v[224:227], v[192:195], v[22:25]
	v_mfma_f32_16x16x32_bf16 v[18:21], v[232:235], v[192:195], v[18:21]
	v_mfma_f32_16x16x32_bf16 v[6:9], v[224:227], v[216:219], v[6:9]
	v_mfma_f32_16x16x32_bf16 v[2:5], v[232:235], v[216:219], v[2:5]
	v_mfma_f32_16x16x32_bf16 v[54:57], v[228:231], v[150:153], v[54:57]
	v_mfma_f32_16x16x32_bf16 v[50:53], v[236:239], v[150:153], v[50:53]
	v_mfma_f32_16x16x32_bf16 v[38:41], v[228:231], v[188:191], v[38:41]
	v_mfma_f32_16x16x32_bf16 v[34:37], v[236:239], v[188:191], v[34:37]
	v_mfma_f32_16x16x32_bf16 v[22:25], v[228:231], v[196:199], v[22:25]
	v_mfma_f32_16x16x32_bf16 v[18:21], v[236:239], v[196:199], v[18:21]
	v_mfma_f32_16x16x32_bf16 v[6:9], v[228:231], v[220:223], v[6:9]
	v_mfma_f32_16x16x32_bf16 v[2:5], v[236:239], v[220:223], v[2:5]
	s_add_u32 s42, s42, 0x100
	s_addc_u32 s43, s43, 0
	s_add_u32 s8, s8, 0x100
	s_addc_u32 s9, s9, 0
	s_cmp_ge_u32 s31, s64
	s_mov_b32 s11, s31
	s_barrier
	s_cbranch_scc0 .LBB0_155
	v_lshl_add_u32 v186, s36, 8, v1
	v_lshl_or_b32 v184, s34, 8, v158
	v_mov_b64_e32 v[130:131], s[26:27]
	v_ashrrev_i32_e32 v185, 31, v184
	v_mad_i64_i32 v[130:131], s[6:7], v186, s86, v[130:131]
	v_lshl_add_u64 v[130:131], v[184:185], 1, v[130:131]
	global_load_dwordx4 v[144:147], v[130:131], off
	v_ashrrev_i32_e32 v187, 31, v186
	v_lshlrev_b64 v[134:135], 11, v[186:187]
	v_lshl_add_u64 v[132:133], s[28:29], 0, v[134:135]
	v_cndmask_b32_e64 v136, 0, 1, s[20:21]
	v_mov_b32_e32 v188, 0
	v_cmp_ne_u32_e64 s[42:43], 1, v136
	s_andn2_b64 vcc, exec, s[20:21]
	v_lshl_add_u64 v[132:133], v[184:185], 1, v[132:133]
	v_mov_b32_e32 v148, 0
	v_mov_b32_e32 v149, 0
	v_mov_b32_e32 v150, 0
	v_mov_b32_e32 v151, 0
	v_mov_b32_e32 v152, 0
	v_mov_b32_e32 v153, 0
	v_mov_b32_e32 v154, 0
	v_mov_b32_e32 v155, 0
	s_cbranch_vccnz .LBB0_158
	global_load_dwordx4 v[152:155], v[130:131], off offset:2048
	global_load_dwordx4 v[148:151], v[132:133], off

; #define LAS __attribute__((address_space(3)))
; __device__ __forceinline__ int ltid() { int t = threadIdx.x; asm volatile("" : "+v"(t)); return t; }
; #define PG8_BAR __builtin_amdgcn_s_barrier()
;     __device__ bool next(int i, Unit& u) const {
;         const long L = (long)i * G + c; if (L >= nwg) return false;
;         int wgid = (int)L; { const int q = nwg / NXCD, r = nwg % NXCD, xcd = wgid % NXCD, off = wgid / NXCD; wgid = (xcd < r ? xcd * (q + 1) : r * (q + 1) + (xcd - r) * q) + off; }
;         const int nig = WGM * nN, gid = wgid / nig, fm = gid * WGM, gsz = (nM - fm) < WGM ? (nM - fm) : WGM;
;         u.pm = fm + ((wgid % nig) % gsz); u.pn = (wgid % nig) / gsz; return true;
;     }
; template <class Epi>
; __device__ __forceinline__ void gemm_phase(LAS unsigned char* lds, const Gemm g, const StaticOrder& S, const Epi& E) {
;     const int tid = ltid(), wid = __builtin_amdgcn_readfirstlane(tid >> 6), lane = tid & 63, wr = wid >> 2, wc = wid & 3, fr = lane & 15, fq = lane >> 4;
;     const int K = g.K, nt = K / BK;
;     unsigned voffA[2], voffB[2];
; #pragma unroll
;     for (int i = 0; i < 2; ++i) { int R, C; stage_rc(tid * 16 + i * 8192, R, C); voffA[i] = (unsigned)(R * g.lda + C) * 2u; voffB[i] = (unsigned)(R * g.ldb + C) * 2u; }
;     const size_t kstep = (size_t)(BK * 2);
;     const size_t hstepA = (size_t)HALF * g.lda * 2, hstepB = (size_t)HALF * g.ldb * 2;
;     const size_t tstepA = 2 * hstepA, tstepB = 2 * hstepB;
;     const unsigned ldsw = (unsigned)wid * 1024u;
;     const int aoff = lds_byte(wr * 64 + fr, fq * 8), boff = lds_byte(wc * 32 + fr, fq * 8);
;     ...
;     Unit cur, nxt; int ui = 0;
;     if (!S.next(0, cur)) return;
;     f32x4 acc[2][2][4][2];
; #pragma unroll
;     for (int a = 0; a < 2; ++a)
; #pragma unroll
;         for (int b = 0; b < 2; ++b)
; #pragma unroll
;             for (int m = 0; m < 4; ++m)
; #pragma unroll
;                 for (int n = 0; n < 2; ++n) acc[a][b][m][n] = (f32x4){0.f, 0.f, 0.f, 0.f};
;     bf16x8 At[4][2], B0[2][2], B1[2][2];
;     const char* cA = (const char*)g.A + (size_t)cur.pm * tstepA; const char* cB = (const char*)g.Bt + (size_t)cur.pn * tstepB;
;     PG8_STAGE(PG8_SB(0, 0), cB, voffB); PG8_STAGE(PG8_SA(0, 0), cA, voffA); PG8_STAGE(PG8_SB(0, 1), cB + hstepB, voffB); PG8_STAGE(PG8_SA(0, 1), cA + hstepA, voffA);
;     if (wr == 1) PG8_BAR;
.LBB0_230:
	s_waitcnt vmcnt(0)
	s_or_b64 exec, exec, s[18:19]
	s_mov_b32 s0, s68
	v_readlane_b32 s1, v254, 0
	v_mov_b32_e32 v8, v200
	s_cmpk_gt_i32 s1, 0x82f
	v_readfirstlane_b32 s8, v8
	s_cbranch_scc1 .LBB0_242
	v_lshlrev_b32_e32 v1, 4, v8
	v_add_u32_e32 v3, 0x2000, v1
	v_ashrrev_i32_e32 v2, 31, v3
	v_lshrrev_b32_e32 v2, 22, v2
	v_add_u32_e32 v2, v3, v2
	v_ashrrev_i32_e32 v2, 10, v2
	v_lshlrev_b32_e32 v4, 5, v2
	v_and_b32_e32 v5, 32, v4
	v_mul_i32_i24_e32 v4, 0x400, v2
	v_sub_u32_e32 v3, v3, v4
	v_lshrrev_b32_e32 v4, 4, v3
	v_bitop3_b32 v4, v4, v3, 32 bitop3:0x6c
	v_ashrrev_i32_e32 v3, 31, v4
	v_lshrrev_b32_e32 v3, 26, v3
	v_add_u32_e32 v6, v4, v3
	v_ashrrev_i32_e32 v3, 6, v6
	v_and_b32_e32 v6, 0xc0, v6
	v_sub_u32_e32 v4, v4, v6
	v_ashrrev_i16_sdwa v4, v201, sext(v4) dst_sel:DWORD dst_unused:UNUSED_PAD src0_sel:DWORD src1_sel:BYTE_0
	v_lshlrev_b32_e32 v6, 3, v2
	v_readlane_b32 s6, v255, 30
	v_bfe_i32 v4, v4, 0, 16
	v_and_b32_e32 v6, 0x3ffff0, v6
	v_readlane_b32 s7, v255, 31
	v_add_u32_e32 v5, v5, v4
	v_add_lshl_u32 v6, v3, v6, 10
	s_load_dwordx2 s[6:7], s[6:7], 0x118
	v_lshl_add_u32 v130, v5, 1, v6
	v_ashrrev_i32_e32 v5, 31, v8
	v_lshrrev_b32_e32 v5, 26, v5
	v_add_u32_e32 v5, v8, v5
	v_ashrrev_i32_e32 v5, 6, v5
	v_lshlrev_b32_e32 v6, 5, v5
	s_waitcnt lgkmcnt(0)
	s_add_u32 s9, s6, 0xf00000
	v_and_b32_e32 v9, 32, v6
	v_bfe_i32 v6, v8, 27, 1
	s_addc_u32 s10, s7, 0
	v_lshrrev_b32_e32 v6, 22, v6
	s_ashr_i32 s12, s1, 31
	v_add_u32_e32 v6, v1, v6
	s_lshr_b32 s6, s12, 29
	v_and_b32_e32 v6, 0xfffffc00, v6
	s_add_i32 s6, s1, s6
	s_ashr_i32 s17, s8, 6
	v_sub_u32_e32 v1, v1, v6
	s_ashr_i32 s7, s6, 3
	s_and_b32 s6, s6, -8
	s_ashr_i32 s19, s8, 8
	s_lshl_b32 s11, s17, 10
	v_lshrrev_b32_e32 v6, 4, v1
	s_sub_i32 s6, s1, s6
	v_bitop3_b32 v7, v6, v1, 32 bitop3:0x6c
	v_ashrrev_i32_e32 v1, 31, v1
	s_cmp_lt_i32 s6, 0
	s_movk_i32 s13, 0x107
	v_lshrrev_b32_e32 v1, 26, v1
	s_cselect_b32 s13, s13, 0x106
	v_add_u32_e32 v1, v7, v1
	s_mul_i32 s6, s6, s13
	v_ashrrev_i32_e32 v6, 6, v1
	s_add_i32 s6, s6, s7
	v_mul_i32_i24_e32 v1, 64, v6
	s_ashr_i32 s7, s6, 31
	v_sub_u32_e32 v1, v7, v1
	s_lshr_b32 s7, s7, 26
	v_ashrrev_i16_sdwa v1, v201, sext(v1) dst_sel:DWORD dst_unused:UNUSED_PAD src0_sel:DWORD src1_sel:BYTE_0
	s_add_i32 s7, s6, s7
	v_bfe_i32 v7, v1, 0, 16
	s_ashr_i32 s13, s7, 6
	v_add_u32_e32 v1, v9, v7
	v_lshlrev_b32_e32 v9, 3, v5
	s_lshl_b32 s13, s13, 3
	v_and_b32_e32 v9, 0x3ffff0, v9
	s_sub_i32 s14, 0x106, s13
	v_add_lshl_u32 v9, v6, v9, 10
	s_min_u32 s14, s14, 8
	s_andn2_b32 s7, s7, 63
	v_lshl_add_u32 v132, v1, 1, v9
	s_sub_i32 s15, s6, s7
	v_cvt_f32_ubyte0_e32 v9, s14
	v_cvt_f32_i32_e32 v1, s15
	v_rcp_iflag_f32_e32 v10, v9
	s_ashr_i32 s6, s15, 30
	s_or_b32 s16, s6, 1
	v_mul_f32_e32 v10, v1, v10
	v_trunc_f32_e32 v10, v10
	v_fma_f32 v1, -v10, v9, v1
	v_cvt_i32_f32_e32 v10, v10
	v_cmp_ge_f32_e64 s[6:7], |v1|, v9
	s_and_b64 s[6:7], s[6:7], exec
	s_cselect_b32 s6, s16, 0
	v_readfirstlane_b32 s7, v10
	s_add_i32 s18, s7, s6
	s_mul_i32 s6, s18, s14
	s_sub_i32 s6, s15, s6
	s_sext_i32_i8 s6, s6
	s_add_i32 s30, s13, s6
	s_ashr_i32 s31, s30, 31
	s_bfe_i64 s[14:15], s[18:19], 0x80000
	s_lshl_b64 s[6:7], s[30:31], 18
	s_lshl_b64 s[14:15], s[14:15], 18
	s_add_u32 s36, s9, s14
	s_addc_u32 s37, s10, s15
	s_add_i32 s13, s11, 0
	s_add_i32 m0, s13, 0x10000
	v_readlane_b32 s14, v255, 49
	global_load_lds_dwordx4 v132, s[36:37]
	s_add_i32 m0, s13, 0x12000
	v_readlane_b32 s15, v255, 50
	s_add_u32 s34, s14, s6
	global_load_lds_dwordx4 v130, s[36:37]
	s_addc_u32 s35, s15, s7
	s_mov_b32 m0, s13
	s_add_i32 s14, s13, 0x2000
	global_load_lds_dwordx4 v132, s[34:35]
	s_mov_b32 m0, s14
	s_add_u32 s6, s36, 0x20000
	global_load_lds_dwordx4 v130, s[34:35]
	s_addc_u32 s7, s37, 0
	s_add_i32 m0, s13, 0x14000
	s_nop 0
	global_load_lds_dwordx4 v132, s[6:7]
	s_add_i32 m0, s13, 0x16000
	s_nop 0
	global_load_lds_dwordx4 v130, s[6:7]
	s_add_u32 s6, s34, 0x20000
	s_addc_u32 s7, s35, 0
	s_add_i32 s15, s13, 0x4000
	s_mov_b32 m0, s15
	s_add_i32 s16, s13, 0x6000
	global_load_lds_dwordx4 v132, s[6:7]
	s_mov_b32 m0, s16
	s_cmp_lg_u32 s19, 1
	global_load_lds_dwordx4 v130, s[6:7]
	s_cbranch_scc1 .LBB0_233
	s_barrier
	s_setprio 1

; #define PG8_STAGE(bufoff, gbase, voff) do { _Pragma("unroll") for (int _i = 0; _i < 2; ++_i) \
;         __builtin_amdgcn_global_load_lds((const unsigned*)((const char*)(gbase) + (voff)[_i]), (LAS unsigned*)(lds + (bufoff) + ldsw + _i * 8192), 16, 0, 0); } while (0)
; #define PG8_LDA(dst, b, h) do { _Pragma("unroll") for (int m = 0; m < 4; ++m) _Pragma("unroll") for (int k = 0; k < 2; ++k) dst[m][k] = *(const LAS bf16x8*)(lds + PG8_SA(b, h) + aoff + m * 2048 + k * 1024); } while (0)
; #define PG8_LDB(dst, b, h) do { _Pragma("unroll") for (int n = 0; n < 2; ++n) _Pragma("unroll") for (int k = 0; k < 2; ++k) dst[n][k] = *(const LAS bf16x8*)(lds + PG8_SB(b, h) + boff + n * 2048 + k * 1024); } while (0)
; #define PG8_MMA(ai, bj, At, Bt) do { __builtin_amdgcn_s_setprio(1); _Pragma("unroll") for (int m = 0; m < 4; ++m) _Pragma("unroll") for (int n = 0; n < 2; ++n) _Pragma("unroll") for (int k = 0; k < 2; ++k) \
;         acc[ai][bj][m][n] = __builtin_amdgcn_mfma_f32_16x16x32_bf16(Bt[n][k], At[m][k], acc[ai][bj][m][n], 0, 0, 0); __builtin_amdgcn_s_setprio(0); } while (0)
; #define PG8_WAIT_L(n) asm volatile("s_waitcnt lgkmcnt(" #n ")" ::: "memory")
; #define PG8_BAR __builtin_amdgcn_s_barrier()
; #define PG8_SCHED __builtin_amdgcn_sched_barrier(0)
; template <class Epi>
; __device__ __forceinline__ void gemm_phase(LAS unsigned char* lds, const Gemm g, const StaticOrder& S, const Epi& E) {
;     ...
;             const char* a1 = cA + (size_t)(t + 1) * kstep;
;             const char* a2 = last ? nA : cA + (size_t)(t + 2) * kstep; const char* b2 = last ? nB : cB + (size_t)(t + 2) * kstep;
;             const char* a3 = a2 + kstep; const char* b3 = b2 + kstep;
;             PG8_LDB(B0, 0, 0); PG8_SCHED; PG8_LDA(At, 0, 0); PG8_STAGE(PG8_SA(1, 1), a1 + hstepA, voffA);
;             PG8_WAIT_L(8); PG8_BAR; PG8_WAIT_L(0); PG8_MMA(0, 0, At, B0); PG8_BAR; PG8_SCHED;
;             PG8_LDB(B1, 0, 1); PG8_STAGE(PG8_SB(0, 0), b2, voffB);
;             PG8_BAR; PG8_WAIT_L(0); PG8_MMA(0, 1, At, B1); PG8_BAR;
;             PG8_LDA(At, 0, 1); PG8_STAGE(PG8_SA(0, 0), a2, voffA);
;             PG8_BAR; PG8_WAIT_L(0); PG8_MMA(1, 0, At, B0); PG8_BAR; PG8_SCHED;
.LBB0_237:
	s_add_u32 s6, s34, 0xfffe0080
	s_addc_u32 s7, s35, -1
	s_add_i32 s49, 0, 0x10000
	v_add_u32_e32 v141, s49, v138
	ds_read_b128 v[142:145], v141
	ds_read_b128 v[146:149], v141 offset:1024
	ds_read_b128 v[150:153], v141 offset:2048
	ds_read_b128 v[176:179], v141 offset:3072
	s_cmp_eq_u32 s48, 4
	s_cselect_b32 s43, s25, s7
	s_cselect_b32 s42, s44, s6
	s_cselect_b32 s37, s19, s47
	s_cselect_b32 s36, s45, s46
	v_lshl_add_u64 v[154:155], s[34:35], 0, v[134:135]
	s_add_i32 m0, s13, 0xc000
	ds_read_b128 v[180:183], v140
	ds_read_b128 v[184:187], v140 offset:1024
	ds_read_b128 v[188:191], v140 offset:2048
	ds_read_b128 v[192:195], v140 offset:3072
	ds_read_b128 v[196:199], v140 offset:4096
	ds_read_b128 v[216:219], v140 offset:5120
	ds_read_b128 v[220:223], v140 offset:6144
	ds_read_b128 v[224:227], v140 offset:7168
	global_load_lds_dwordx4 v[154:155], off
	v_lshl_add_u64 v[154:155], s[34:35], 0, v[136:137]
	s_add_i32 m0, s13, 0xe000
	s_nop 0
	global_load_lds_dwordx4 v[154:155], off
	s_waitcnt lgkmcnt(8)
	s_barrier
	s_waitcnt lgkmcnt(0)
	s_waitcnt lgkmcnt(0)
	v_mfma_f32_16x16x32_bf16 v[126:129], v[142:145], v[180:183], v[126:129]
	v_mfma_f32_16x16x32_bf16 v[118:121], v[150:153], v[180:183], v[118:121]
	v_mfma_f32_16x16x32_bf16 v[110:113], v[142:145], v[188:191], v[110:113]
	v_mfma_f32_16x16x32_bf16 v[102:105], v[150:153], v[188:191], v[102:105]
	v_mfma_f32_16x16x32_bf16 v[94:97], v[142:145], v[196:199], v[94:97]
	v_mfma_f32_16x16x32_bf16 v[86:89], v[150:153], v[196:199], v[86:89]
	v_mfma_f32_16x16x32_bf16 v[78:81], v[142:145], v[220:223], v[78:81]
	v_mfma_f32_16x16x32_bf16 v[70:73], v[150:153], v[220:223], v[70:73]
	v_mfma_f32_16x16x32_bf16 v[126:129], v[146:149], v[184:187], v[126:129]
	v_mfma_f32_16x16x32_bf16 v[118:121], v[176:179], v[184:187], v[118:121]
	v_mfma_f32_16x16x32_bf16 v[110:113], v[146:149], v[192:195], v[110:113]
	v_mfma_f32_16x16x32_bf16 v[102:105], v[176:179], v[192:195], v[102:105]
	v_mfma_f32_16x16x32_bf16 v[94:97], v[146:149], v[216:219], v[94:97]
	v_mfma_f32_16x16x32_bf16 v[86:89], v[176:179], v[216:219], v[86:89]
	v_mfma_f32_16x16x32_bf16 v[78:81], v[146:149], v[224:227], v[78:81]
	v_mfma_f32_16x16x32_bf16 v[70:73], v[176:179], v[224:227], v[70:73]
	s_barrier
	s_add_i32 s50, 0, 0x14000
	s_add_i32 s6, s49, s11
	v_add_u32_e32 v141, s50, v138
	v_lshl_add_u64 v[154:155], s[36:37], 0, v[132:133]
	s_mov_b32 m0, s6
	ds_read_b128 v[228:231], v141
	ds_read_b128 v[232:235], v141 offset:1024
	ds_read_b128 v[236:239], v141 offset:2048
	ds_read_b128 v[240:243], v141 offset:3072
	global_load_lds_dwordx4 v[154:155], off
	v_lshl_add_u64 v[212:213], s[36:37], 0, v[130:131]
	s_add_i32 m0, s6, 0x2000
	s_nop 0
	global_load_lds_dwordx4 v[212:213], off
	s_barrier
	s_waitcnt lgkmcnt(0)
	s_waitcnt lgkmcnt(0)
	v_mfma_f32_16x16x32_bf16 v[122:125], v[228:231], v[180:183], v[122:125]
	v_mfma_f32_16x16x32_bf16 v[114:117], v[236:239], v[180:183], v[114:117]
	v_mfma_f32_16x16x32_bf16 v[106:109], v[228:231], v[188:191], v[106:109]
	v_mfma_f32_16x16x32_bf16 v[98:101], v[236:239], v[188:191], v[98:101]
	v_mfma_f32_16x16x32_bf16 v[90:93], v[228:231], v[196:199], v[90:93]
	v_mfma_f32_16x16x32_bf16 v[82:85], v[236:239], v[196:199], v[82:85]
	v_mfma_f32_16x16x32_bf16 v[74:77], v[228:231], v[220:223], v[74:77]
	v_mfma_f32_16x16x32_bf16 v[66:69], v[236:239], v[220:223], v[66:69]
	v_mfma_f32_16x16x32_bf16 v[122:125], v[232:235], v[184:187], v[122:125]
	v_mfma_f32_16x16x32_bf16 v[114:117], v[240:243], v[184:187], v[114:117]
	v_mfma_f32_16x16x32_bf16 v[106:109], v[232:235], v[192:195], v[106:109]
	v_mfma_f32_16x16x32_bf16 v[98:101], v[240:243], v[192:195], v[98:101]
	v_mfma_f32_16x16x32_bf16 v[90:93], v[232:235], v[216:219], v[90:93]
	v_mfma_f32_16x16x32_bf16 v[82:85], v[240:243], v[216:219], v[82:85]
	v_mfma_f32_16x16x32_bf16 v[74:77], v[232:235], v[224:227], v[74:77]
	v_mfma_f32_16x16x32_bf16 v[66:69], v[240:243], v[224:227], v[66:69]
	s_mov_b32 m0, s13
	v_lshl_add_u64 v[244:245], s[42:43], 0, v[132:133]
	s_barrier
	ds_read_b128 v[180:183], v140 offset:16384
	ds_read_b128 v[184:187], v140 offset:17408
	ds_read_b128 v[188:191], v140 offset:18432
	ds_read_b128 v[192:195], v140 offset:19456
	ds_read_b128 v[196:199], v140 offset:20480
	ds_read_b128 v[216:219], v140 offset:21504
	ds_read_b128 v[220:223], v140 offset:22528
	ds_read_b128 v[224:227], v140 offset:23552
	global_load_lds_dwordx4 v[244:245], off
	v_lshl_add_u64 v[246:247], s[42:43], 0, v[130:131]
	s_mov_b32 m0, s14
	s_nop 0
	global_load_lds_dwordx4 v[246:247], off
	s_barrier
	s_waitcnt lgkmcnt(0)
	s_waitcnt lgkmcnt(0)
	v_mfma_f32_16x16x32_bf16 v[62:65], v[142:145], v[180:183], v[62:65]
	v_mfma_f32_16x16x32_bf16 v[54:57], v[150:153], v[180:183], v[54:57]
	v_mfma_f32_16x16x32_bf16 v[46:49], v[142:145], v[188:191], v[46:49]
	v_mfma_f32_16x16x32_bf16 v[38:41], v[150:153], v[188:191], v[38:41]
	v_mfma_f32_16x16x32_bf16 v[30:33], v[142:145], v[196:199], v[30:33]
	v_mfma_f32_16x16x32_bf16 v[22:25], v[150:153], v[196:199], v[22:25]
	v_mfma_f32_16x16x32_bf16 v[14:17], v[142:145], v[220:223], v[14:17]
	v_mfma_f32_16x16x32_bf16 v[6:9], v[150:153], v[220:223], v[6:9]
	v_mfma_f32_16x16x32_bf16 v[62:65], v[146:149], v[184:187], v[62:65]
	v_mfma_f32_16x16x32_bf16 v[54:57], v[176:179], v[184:187], v[54:57]
	v_mfma_f32_16x16x32_bf16 v[46:49], v[146:149], v[192:195], v[46:49]
	v_mfma_f32_16x16x32_bf16 v[38:41], v[176:179], v[192:195], v[38:41]
	v_mfma_f32_16x16x32_bf16 v[30:33], v[146:149], v[216:219], v[30:33]
	v_mfma_f32_16x16x32_bf16 v[22:25], v[176:179], v[216:219], v[22:25]
	v_mfma_f32_16x16x32_bf16 v[14:17], v[146:149], v[224:227], v[14:17]
	v_mfma_f32_16x16x32_bf16 v[6:9], v[176:179], v[224:227], v[6:9]
	s_barrier
; #define PG8_STAGE(bufoff, gbase, voff) do { _Pragma("unroll") for (int _i = 0; _i < 2; ++_i) \
;         __builtin_amdgcn_global_load_lds((const unsigned*)((const char*)(gbase) + (voff)[_i]), (LAS unsigned*)(lds + (bufoff) + ldsw + _i * 8192), 16, 0, 0); } while (0)
; #define PG8_LDA(dst, b, h) do { _Pragma("unroll") for (int m = 0; m < 4; ++m) _Pragma("unroll") for (int k = 0; k < 2; ++k) dst[m][k] = *(const LAS bf16x8*)(lds + PG8_SA(b, h) + aoff + m * 2048 + k * 1024); } while (0)
; #define PG8_LDB(dst, b, h) do { _Pragma("unroll") for (int n = 0; n < 2; ++n) _Pragma("unroll") for (int k = 0; k < 2; ++k) dst[n][k] = *(const LAS bf16x8*)(lds + PG8_SB(b, h) + boff + n * 2048 + k * 1024); } while (0)
; #define PG8_MMA(ai, bj, At, Bt) do { __builtin_amdgcn_s_setprio(1); _Pragma("unroll") for (int m = 0; m < 4; ++m) _Pragma("unroll") for (int n = 0; n < 2; ++n) _Pragma("unroll") for (int k = 0; k < 2; ++k) \
;         acc[ai][bj][m][n] = __builtin_amdgcn_mfma_f32_16x16x32_bf16(Bt[n][k], At[m][k], acc[ai][bj][m][n], 0, 0, 0); __builtin_amdgcn_s_setprio(0); } while (0)
; #define PG8_WAIT_V(n) asm volatile("s_waitcnt vmcnt(" #n ")" ::: "memory")
; #define PG8_WAIT_L(n) asm volatile("s_waitcnt lgkmcnt(" #n ")" ::: "memory")
; #define PG8_BAR __builtin_amdgcn_s_barrier()
; #define PG8_SCHED __builtin_amdgcn_sched_barrier(0)
; template <class Epi>
; __device__ __forceinline__ void gemm_phase(LAS unsigned char* lds, const Gemm g, const StaticOrder& S, const Epi& E) {
;     ...
;             PG8_STAGE(PG8_SB(0, 1), b2 + hstepB, voffB);
;             PG8_WAIT_V(6); PG8_BAR; PG8_MMA(1, 1, At, B1); PG8_BAR;
;             PG8_LDB(B0, 1, 0); PG8_SCHED; PG8_LDA(At, 1, 0); PG8_STAGE(PG8_SA(0, 1), a2 + hstepA, voffA);
;             PG8_WAIT_L(8); PG8_BAR; PG8_WAIT_L(0); PG8_MMA(0, 0, At, B0); PG8_BAR; PG8_SCHED;
;             PG8_LDB(B1, 1, 1); PG8_STAGE(PG8_SB(1, 0), b3, voffB);
;             PG8_BAR; PG8_WAIT_L(0); PG8_MMA(0, 1, At, B1); PG8_BAR;
	s_add_u32 s6, s36, 0x20000
	s_addc_u32 s7, s37, 0
	s_add_i32 s49, s50, s11
	v_lshl_add_u64 v[142:143], s[6:7], 0, v[132:133]
	s_mov_b32 m0, s49
	s_nop 0
	global_load_lds_dwordx4 v[142:143], off
	v_lshl_add_u64 v[142:143], s[6:7], 0, v[130:131]
	s_add_i32 m0, s49, 0x2000
	s_nop 0
	global_load_lds_dwordx4 v[142:143], off
	s_waitcnt vmcnt(6)
	s_barrier
	v_mfma_f32_16x16x32_bf16 v[58:61], v[228:231], v[180:183], v[58:61]
	v_mfma_f32_16x16x32_bf16 v[50:53], v[236:239], v[180:183], v[50:53]
	v_mfma_f32_16x16x32_bf16 v[42:45], v[228:231], v[188:191], v[42:45]
	v_mfma_f32_16x16x32_bf16 v[34:37], v[236:239], v[188:191], v[34:37]
	v_mfma_f32_16x16x32_bf16 v[26:29], v[228:231], v[196:199], v[26:29]
	v_mfma_f32_16x16x32_bf16 v[18:21], v[236:239], v[196:199], v[18:21]
	v_mfma_f32_16x16x32_bf16 v[10:13], v[228:231], v[220:223], v[10:13]
	v_mfma_f32_16x16x32_bf16 v[2:5], v[236:239], v[220:223], v[2:5]
	v_mfma_f32_16x16x32_bf16 v[58:61], v[232:235], v[184:187], v[58:61]
	v_mfma_f32_16x16x32_bf16 v[50:53], v[240:243], v[184:187], v[50:53]
	v_mfma_f32_16x16x32_bf16 v[42:45], v[232:235], v[192:195], v[42:45]
	v_mfma_f32_16x16x32_bf16 v[34:37], v[240:243], v[192:195], v[34:37]
	v_mfma_f32_16x16x32_bf16 v[26:29], v[232:235], v[216:219], v[26:29]
	v_mfma_f32_16x16x32_bf16 v[18:21], v[240:243], v[216:219], v[18:21]
	v_mfma_f32_16x16x32_bf16 v[10:13], v[232:235], v[224:227], v[10:13]
	v_mfma_f32_16x16x32_bf16 v[2:5], v[240:243], v[224:227], v[2:5]
	s_add_i32 s49, 0, 0x18000
	v_add_u32_e32 v141, s49, v138
	s_barrier
	ds_read_b128 v[142:145], v141
	ds_read_b128 v[146:149], v141 offset:1024
	ds_read_b128 v[150:153], v141 offset:2048
	ds_read_b128 v[176:179], v141 offset:3072
	s_add_u32 s6, s42, 0x20000
	s_addc_u32 s7, s43, 0
	s_mov_b32 m0, s15
	v_lshl_add_u64 v[228:229], s[6:7], 0, v[132:133]
	ds_read_b128 v[180:183], v140 offset:32768
	ds_read_b128 v[184:187], v140 offset:33792
	ds_read_b128 v[188:191], v140 offset:34816
	ds_read_b128 v[192:195], v140 offset:35840
	ds_read_b128 v[196:199], v140 offset:36864
	ds_read_b128 v[216:219], v140 offset:37888
	ds_read_b128 v[220:223], v140 offset:38912
	ds_read_b128 v[224:227], v140 offset:39936
	global_load_lds_dwordx4 v[228:229], off
	v_lshl_add_u64 v[228:229], s[6:7], 0, v[130:131]
	s_mov_b32 m0, s16
	s_nop 0
	global_load_lds_dwordx4 v[228:229], off
	s_waitcnt lgkmcnt(8)
	s_barrier
	s_waitcnt lgkmcnt(0)
	s_waitcnt lgkmcnt(0)
	v_mfma_f32_16x16x32_bf16 v[126:129], v[142:145], v[180:183], v[126:129]
	v_mfma_f32_16x16x32_bf16 v[118:121], v[150:153], v[180:183], v[118:121]
	v_mfma_f32_16x16x32_bf16 v[110:113], v[142:145], v[188:191], v[110:113]
	v_mfma_f32_16x16x32_bf16 v[102:105], v[150:153], v[188:191], v[102:105]
	v_mfma_f32_16x16x32_bf16 v[94:97], v[142:145], v[196:199], v[94:97]
	v_mfma_f32_16x16x32_bf16 v[86:89], v[150:153], v[196:199], v[86:89]
	v_mfma_f32_16x16x32_bf16 v[78:81], v[142:145], v[220:223], v[78:81]
	v_mfma_f32_16x16x32_bf16 v[70:73], v[150:153], v[220:223], v[70:73]
	v_mfma_f32_16x16x32_bf16 v[126:129], v[146:149], v[184:187], v[126:129]
	v_mfma_f32_16x16x32_bf16 v[118:121], v[176:179], v[184:187], v[118:121]
	v_mfma_f32_16x16x32_bf16 v[110:113], v[146:149], v[192:195], v[110:113]
	v_mfma_f32_16x16x32_bf16 v[102:105], v[176:179], v[192:195], v[102:105]
	v_mfma_f32_16x16x32_bf16 v[94:97], v[146:149], v[216:219], v[94:97]
	v_mfma_f32_16x16x32_bf16 v[86:89], v[176:179], v[216:219], v[86:89]
	v_mfma_f32_16x16x32_bf16 v[78:81], v[146:149], v[224:227], v[78:81]
	v_mfma_f32_16x16x32_bf16 v[70:73], v[176:179], v[224:227], v[70:73]
	s_barrier
	s_add_i32 s42, 0, 0x1c000
	s_add_i32 s6, s49, s11
	v_add_u32_e32 v141, s42, v138
	v_lshl_add_u64 v[154:155], v[154:155], 0, s[88:89]
	s_mov_b32 m0, s6
	ds_read_b128 v[228:231], v141
	ds_read_b128 v[232:235], v141 offset:1024
	ds_read_b128 v[236:239], v141 offset:2048
	ds_read_b128 v[240:243], v141 offset:3072
	global_load_lds_dwordx4 v[154:155], off
	v_lshl_add_u64 v[154:155], v[212:213], 0, s[88:89]
	s_add_i32 m0, s6, 0x2000
	s_nop 0
	global_load_lds_dwordx4 v[154:155], off
	s_barrier
	s_waitcnt lgkmcnt(0)
	s_waitcnt lgkmcnt(0)
	v_mfma_f32_16x16x32_bf16 v[122:125], v[228:231], v[180:183], v[122:125]
	v_mfma_f32_16x16x32_bf16 v[114:117], v[236:239], v[180:183], v[114:117]
	v_mfma_f32_16x16x32_bf16 v[106:109], v[228:231], v[188:191], v[106:109]
	v_mfma_f32_16x16x32_bf16 v[98:101], v[236:239], v[188:191], v[98:101]
	v_mfma_f32_16x16x32_bf16 v[90:93], v[228:231], v[196:199], v[90:93]
	v_mfma_f32_16x16x32_bf16 v[82:85], v[236:239], v[196:199], v[82:85]
	v_mfma_f32_16x16x32_bf16 v[74:77], v[228:231], v[220:223], v[74:77]
	v_mfma_f32_16x16x32_bf16 v[66:69], v[236:239], v[220:223], v[66:69]
	v_mfma_f32_16x16x32_bf16 v[122:125], v[232:235], v[184:187], v[122:125]
	v_mfma_f32_16x16x32_bf16 v[114:117], v[240:243], v[184:187], v[114:117]
	v_mfma_f32_16x16x32_bf16 v[106:109], v[232:235], v[192:195], v[106:109]
	v_mfma_f32_16x16x32_bf16 v[98:101], v[240:243], v[192:195], v[98:101]
	v_mfma_f32_16x16x32_bf16 v[90:93], v[232:235], v[216:219], v[90:93]
	v_mfma_f32_16x16x32_bf16 v[82:85], v[240:243], v[216:219], v[82:85]
	v_mfma_f32_16x16x32_bf16 v[74:77], v[232:235], v[224:227], v[74:77]
	v_mfma_f32_16x16x32_bf16 v[66:69], v[240:243], v[224:227], v[66:69]
	s_mov_b32 m0, s17
	v_lshl_add_u64 v[154:155], v[244:245], 0, s[88:89]
	s_barrier
	ds_read_b128 v[180:183], v140 offset:49152
	ds_read_b128 v[184:187], v140 offset:50176
	ds_read_b128 v[188:191], v140 offset:51200
	ds_read_b128 v[192:195], v140 offset:52224
	ds_read_b128 v[196:199], v140 offset:53248
	ds_read_b128 v[216:219], v140 offset:54272
	ds_read_b128 v[220:223], v140 offset:55296
	ds_read_b128 v[224:227], v140 offset:56320
	global_load_lds_dwordx4 v[154:155], off
	v_lshl_add_u64 v[154:155], v[246:247], 0, s[88:89]
	s_mov_b32 m0, s20
	s_nop 0
	global_load_lds_dwordx4 v[154:155], off
	s_barrier
; __device__ __forceinline__ unsigned pk2(float lo, float hi) { unsigned r; asm volatile("v_cvt_pk_bf16_f32 %0, %1, %2" : "=v"(r) : "v"(lo), "v"(hi)); return r; }
; __device__ __forceinline__ float sigmoidf_(float v) { return __builtin_amdgcn_rcpf(1.f + __expf(-v)); }
; #define PG8_STAGE(bufoff, gbase, voff) do { _Pragma("unroll") for (int _i = 0; _i < 2; ++_i) \
;         __builtin_amdgcn_global_load_lds((const unsigned*)((const char*)(gbase) + (voff)[_i]), (LAS unsigned*)(lds + (bufoff) + ldsw + _i * 8192), 16, 0, 0); } while (0)
; #define PG8_LDA(dst, b, h) do { _Pragma("unroll") for (int m = 0; m < 4; ++m) _Pragma("unroll") for (int k = 0; k < 2; ++k) dst[m][k] = *(const LAS bf16x8*)(lds + PG8_SA(b, h) + aoff + m * 2048 + k * 1024); } while (0)
; #define PG8_WAIT_V(n) asm volatile("s_waitcnt vmcnt(" #n ")" ::: "memory")
; #define PG8_WAIT_L(n) asm volatile("s_waitcnt lgkmcnt(" #n ")" ::: "memory")
; #define PG8_BAR __builtin_amdgcn_s_barrier()
; #define PG8_SCHED __builtin_amdgcn_sched_barrier(0)
; template <class Epi>
; __device__ __forceinline__ void gemm_phase(LAS unsigned char* lds, const Gemm g, const StaticOrder& S, const Epi& E) {
;     ...
;             PG8_LDA(At, 1, 1); PG8_STAGE(PG8_SA(1, 0), a3, voffA);
;             PG8_BAR; PG8_WAIT_L(0); PG8_MMA(1, 0, At, B0); PG8_BAR; PG8_SCHED;
;             PG8_STAGE(PG8_SB(1, 1), b3 + hstepB, voffB);
;             PG8_WAIT_V(6); PG8_BAR; PG8_MMA(1, 1, At, B1); PG8_BAR;
;     __device__ __forceinline__ void operator()(const f32x4 (&acc)[2][2][4][2], const Unit& u, int wr, int wc, int fr, int fq) const {
;         const int rowb = u.pm * 256 + wr * 64 + fr, colb = u.pn * 128 + wc * 32 + fq * 8;
; #pragma unroll
;         for (int ai = 0; ai < 2; ++ai)
; #pragma unroll
;             for (int m = 0; m < 4; ++m) { bf16_t* rp = OB + (size_t)(rowb + ai * 128 + m * 16) * 1024 + colb;
;                 const f32x4 a0 = acc[ai][0][m][0], g0 = acc[ai][1][m][0], a1 = acc[ai][0][m][1], g1 = acc[ai][1][m][1];
;                 u32x4 o; o[0] = pk2(a0[0] * sigmoidf_(g0[0]), a0[1] * sigmoidf_(g0[1])); o[1] = pk2(a0[2] * sigmoidf_(g0[2]), a0[3] * sigmoidf_(g0[3]));
;                 o[2] = pk2(a1[0] * sigmoidf_(g1[0]), a1[1] * sigmoidf_(g1[1])); o[3] = pk2(a1[2] * sigmoidf_(g1[2]), a1[3] * sigmoidf_(g1[3])); *(u32x4*)rp = o; }
	s_waitcnt lgkmcnt(0)
	s_waitcnt lgkmcnt(0)
	v_mfma_f32_16x16x32_bf16 v[62:65], v[142:145], v[180:183], v[62:65]
	v_mfma_f32_16x16x32_bf16 v[54:57], v[150:153], v[180:183], v[54:57]
	v_mfma_f32_16x16x32_bf16 v[46:49], v[142:145], v[188:191], v[46:49]
	v_mfma_f32_16x16x32_bf16 v[38:41], v[150:153], v[188:191], v[38:41]
	v_mfma_f32_16x16x32_bf16 v[30:33], v[142:145], v[196:199], v[30:33]
	v_mfma_f32_16x16x32_bf16 v[22:25], v[150:153], v[196:199], v[22:25]
	v_mfma_f32_16x16x32_bf16 v[14:17], v[142:145], v[220:223], v[14:17]
	v_mfma_f32_16x16x32_bf16 v[6:9], v[150:153], v[220:223], v[6:9]
	v_mfma_f32_16x16x32_bf16 v[62:65], v[146:149], v[184:187], v[62:65]
	v_mfma_f32_16x16x32_bf16 v[54:57], v[176:179], v[184:187], v[54:57]
	v_mfma_f32_16x16x32_bf16 v[46:49], v[146:149], v[192:195], v[46:49]
	v_mfma_f32_16x16x32_bf16 v[38:41], v[176:179], v[192:195], v[38:41]
	v_mfma_f32_16x16x32_bf16 v[30:33], v[146:149], v[216:219], v[30:33]
	v_mfma_f32_16x16x32_bf16 v[22:25], v[176:179], v[216:219], v[22:25]
	v_mfma_f32_16x16x32_bf16 v[14:17], v[146:149], v[224:227], v[14:17]
	v_mfma_f32_16x16x32_bf16 v[6:9], v[176:179], v[224:227], v[6:9]
	s_barrier
	s_add_u32 s6, s36, 0x20080
	s_addc_u32 s7, s37, 0
	s_add_i32 s36, s42, s11
	v_lshl_add_u64 v[142:143], s[6:7], 0, v[132:133]
	s_mov_b32 m0, s36
	s_nop 0
	global_load_lds_dwordx4 v[142:143], off
	v_lshl_add_u64 v[142:143], s[6:7], 0, v[130:131]
	s_add_i32 m0, s36, 0x2000
	s_nop 0
	global_load_lds_dwordx4 v[142:143], off
	s_waitcnt vmcnt(6)
	s_barrier
	v_mfma_f32_16x16x32_bf16 v[58:61], v[228:231], v[180:183], v[58:61]
	v_mfma_f32_16x16x32_bf16 v[50:53], v[236:239], v[180:183], v[50:53]
	v_mfma_f32_16x16x32_bf16 v[42:45], v[228:231], v[188:191], v[42:45]
	v_mfma_f32_16x16x32_bf16 v[34:37], v[236:239], v[188:191], v[34:37]
	v_mfma_f32_16x16x32_bf16 v[26:29], v[228:231], v[196:199], v[26:29]
	v_mfma_f32_16x16x32_bf16 v[18:21], v[236:239], v[196:199], v[18:21]
	v_mfma_f32_16x16x32_bf16 v[10:13], v[228:231], v[220:223], v[10:13]
	v_mfma_f32_16x16x32_bf16 v[2:5], v[236:239], v[220:223], v[2:5]
	v_mfma_f32_16x16x32_bf16 v[58:61], v[232:235], v[184:187], v[58:61]
	v_mfma_f32_16x16x32_bf16 v[50:53], v[240:243], v[184:187], v[50:53]
	v_mfma_f32_16x16x32_bf16 v[42:45], v[232:235], v[192:195], v[42:45]
	v_mfma_f32_16x16x32_bf16 v[34:37], v[240:243], v[192:195], v[34:37]
	v_mfma_f32_16x16x32_bf16 v[26:29], v[232:235], v[216:219], v[26:29]
	v_mfma_f32_16x16x32_bf16 v[18:21], v[240:243], v[216:219], v[18:21]
	v_mfma_f32_16x16x32_bf16 v[10:13], v[232:235], v[224:227], v[10:13]
	v_mfma_f32_16x16x32_bf16 v[2:5], v[240:243], v[224:227], v[2:5]
	s_add_i32 s48, s48, 2
	s_add_u32 s34, s34, 0x100
	s_addc_u32 s35, s35, 0
	s_add_u32 s46, s46, 0x100
	s_addc_u32 s47, s47, 0
	s_cmp_gt_u32 s48, 5
	s_barrier
	s_cbranch_scc0 .LBB0_237
	v_lshl_add_u32 v142, s30, 8, v1
	v_mul_f32_e32 v122, 0xbfb8aa3b, v122
	v_ashrrev_i32_e32 v143, 31, v142
	v_exp_f32_e32 v141, v122
	v_mul_f32_e32 v122, 0xbfb8aa3b, v123
	v_lshlrev_b64 v[146:147], 11, v[142:143]
	v_exp_f32_e32 v143, v122
	v_lshl_or_b32 v144, s33, 7, v139
	v_readlane_b32 s6, v255, 34
	v_ashrrev_i32_e32 v145, 31, v144
	v_readlane_b32 s7, v255, 35
	v_add_f32_e32 v141, 1.0, v141
	v_add_f32_e32 v143, 1.0, v143
	v_lshl_add_u64 v[146:147], s[6:7], 0, v[146:147]
	v_lshlrev_b64 v[144:145], 1, v[144:145]
	v_rcp_f32_e32 v141, v141
	v_rcp_f32_e32 v143, v143
	v_mul_f32_e32 v124, 0xbfb8aa3b, v124
	v_mul_f32_e32 v125, 0xbfb8aa3b, v125
	v_mul_f32_e32 v114, 0xbfb8aa3b, v114
	v_mul_f32_e32 v115, 0xbfb8aa3b, v115
	v_mul_f32_e32 v106, 0xbfb8aa3b, v106
	v_mul_f32_e32 v107, 0xbfb8aa3b, v107
	v_lshl_add_u64 v[122:123], v[146:147], 0, v[144:145]
	v_exp_f32_e32 v146, v124
	v_exp_f32_e32 v125, v125
	v_exp_f32_e32 v114, v114
	v_exp_f32_e32 v115, v115
	v_mul_f32_e32 v116, 0xbfb8aa3b, v116
	v_mul_f32_e32 v117, 0xbfb8aa3b, v117
	v_exp_f32_e32 v106, v106
	v_exp_f32_e32 v107, v107
	v_exp_f32_e32 v116, v116
	v_exp_f32_e32 v117, v117
	v_mul_f32_e32 v124, v126, v141
	v_mul_f32_e32 v126, v127, v143
	v_cvt_pk_bf16_f32 v124, v124, v126
	v_add_f32_e32 v126, 1.0, v146
	v_add_f32_e32 v125, 1.0, v125
	v_add_f32_e32 v114, 1.0, v114
	v_add_f32_e32 v115, 1.0, v115
	v_add_f32_e32 v106, 1.0, v106
	v_add_f32_e32 v107, 1.0, v107
	v_rcp_f32_e32 v126, v126
	v_rcp_f32_e32 v125, v125
	v_rcp_f32_e32 v114, v114
	v_rcp_f32_e32 v115, v115
	v_add_f32_e32 v116, 1.0, v116
	v_add_f32_e32 v117, 1.0, v117
	v_rcp_f32_e32 v106, v106
	v_rcp_f32_e32 v107, v107
	v_mul_f32_e32 v108, 0xbfb8aa3b, v108
	v_rcp_f32_e32 v116, v116
	v_rcp_f32_e32 v117, v117
	v_exp_f32_e32 v108, v108
	v_mul_f32_e32 v126, v128, v126
	v_mul_f32_e32 v125, v129, v125
	v_mul_f32_e32 v114, v118, v114
	v_mul_f32_e32 v115, v119, v115
	v_mul_f32_e32 v106, v110, v106
	v_mul_f32_e32 v107, v111, v107
	v_cvt_pk_bf16_f32 v125, v126, v125
	v_cvt_pk_bf16_f32 v126, v114, v115
	v_mul_f32_e32 v114, v120, v116
	v_mul_f32_e32 v115, v121, v117
	v_cvt_pk_bf16_f32 v127, v114, v115
	global_store_dwordx4 v[122:123], v[124:127], off
	v_cvt_pk_bf16_f32 v106, v106, v107
	v_add_f32_e32 v107, 1.0, v108
	v_mul_f32_e32 v108, 0xbfb8aa3b, v109
	v_mul_f32_e32 v98, 0xbfb8aa3b, v98
	v_mul_f32_e32 v99, 0xbfb8aa3b, v99
	v_mul_f32_e32 v90, 0xbfb8aa3b, v90
	v_mul_f32_e32 v91, 0xbfb8aa3b, v91
	v_exp_f32_e32 v108, v108
	v_exp_f32_e32 v98, v98
	v_exp_f32_e32 v99, v99
	v_mul_f32_e32 v100, 0xbfb8aa3b, v100
	v_mul_f32_e32 v101, 0xbfb8aa3b, v101
	v_exp_f32_e32 v90, v90
	v_exp_f32_e32 v91, v91
	v_exp_f32_e32 v100, v100
	v_exp_f32_e32 v101, v101
	v_add_f32_e32 v108, 1.0, v108
	v_add_f32_e32 v98, 1.0, v98
	v_add_f32_e32 v99, 1.0, v99
	v_add_f32_e32 v90, 1.0, v90
	v_add_f32_e32 v91, 1.0, v91
	v_or_b32_e32 v114, 16, v142
	v_rcp_f32_e32 v107, v107
; __device__ __forceinline__ unsigned pk2(float lo, float hi) { unsigned r; asm volatile("v_cvt_pk_bf16_f32 %0, %1, %2" : "=v"(r) : "v"(lo), "v"(hi)); return r; }
; __device__ __forceinline__ float sigmoidf_(float v) { return __builtin_amdgcn_rcpf(1.f + __expf(-v)); }
;     __device__ __forceinline__ void operator()(const f32x4 (&acc)[2][2][4][2], const Unit& u, int wr, int wc, int fr, int fq) const {
;     ...
;             for (int m = 0; m < 4; ++m) { bf16_t* rp = OB + (size_t)(rowb + ai * 128 + m * 16) * 1024 + colb;
;                 const f32x4 a0 = acc[ai][0][m][0], g0 = acc[ai][1][m][0], a1 = acc[ai][0][m][1], g1 = acc[ai][1][m][1];
;                 u32x4 o; o[0] = pk2(a0[0] * sigmoidf_(g0[0]), a0[1] * sigmoidf_(g0[1])); o[1] = pk2(a0[2] * sigmoidf_(g0[2]), a0[3] * sigmoidf_(g0[3]));
;                 o[2] = pk2(a1[0] * sigmoidf_(g1[0]), a1[1] * sigmoidf_(g1[1])); o[3] = pk2(a1[2] * sigmoidf_(g1[2]), a1[3] * sigmoidf_(g1[3])); *(u32x4*)rp = o; }
	v_rcp_f32_e32 v108, v108
	v_rcp_f32_e32 v98, v98
	v_rcp_f32_e32 v99, v99
	v_add_f32_e32 v100, 1.0, v100
	v_add_f32_e32 v101, 1.0, v101
	v_rcp_f32_e32 v90, v90
	v_rcp_f32_e32 v91, v91
	v_mul_f32_e32 v92, 0xbfb8aa3b, v92
	v_ashrrev_i32_e32 v115, 31, v114
	v_rcp_f32_e32 v100, v100
	v_rcp_f32_e32 v101, v101
	v_exp_f32_e32 v92, v92
	v_lshlrev_b64 v[114:115], 11, v[114:115]
	v_lshl_add_u64 v[114:115], s[6:7], 0, v[114:115]
	v_lshl_add_u64 v[114:115], v[114:115], 0, v[144:145]
	v_mul_f32_e32 v107, v112, v107
	v_mul_f32_e32 v108, v113, v108
	v_mul_f32_e32 v98, v102, v98
	v_mul_f32_e32 v99, v103, v99
	v_mul_f32_e32 v90, v94, v90
	v_mul_f32_e32 v91, v95, v91
	v_cvt_pk_bf16_f32 v107, v107, v108
	v_cvt_pk_bf16_f32 v108, v98, v99
	v_mul_f32_e32 v98, v104, v100
	v_mul_f32_e32 v99, v105, v101
	v_cvt_pk_bf16_f32 v109, v98, v99
	global_store_dwordx4 v[114:115], v[106:109], off
	v_cvt_pk_bf16_f32 v90, v90, v91
	v_add_f32_e32 v91, 1.0, v92
	v_mul_f32_e32 v92, 0xbfb8aa3b, v93
	v_mul_f32_e32 v82, 0xbfb8aa3b, v82
	v_mul_f32_e32 v83, 0xbfb8aa3b, v83
	v_mul_f32_e32 v74, 0xbfb8aa3b, v74
	v_mul_f32_e32 v75, 0xbfb8aa3b, v75
	v_exp_f32_e32 v92, v92
	v_exp_f32_e32 v82, v82
	v_exp_f32_e32 v83, v83
	v_mul_f32_e32 v84, 0xbfb8aa3b, v84
	v_mul_f32_e32 v85, 0xbfb8aa3b, v85
	v_exp_f32_e32 v74, v74
	v_exp_f32_e32 v75, v75
	v_exp_f32_e32 v84, v84
	v_exp_f32_e32 v85, v85
	v_add_f32_e32 v92, 1.0, v92
	v_add_f32_e32 v82, 1.0, v82
	v_add_f32_e32 v83, 1.0, v83
	v_add_f32_e32 v74, 1.0, v74
	v_add_f32_e32 v75, 1.0, v75
	v_or_b32_e32 v98, 32, v142
	v_rcp_f32_e32 v91, v91
	v_rcp_f32_e32 v92, v92
	v_rcp_f32_e32 v82, v82
	v_rcp_f32_e32 v83, v83
	v_add_f32_e32 v84, 1.0, v84
	v_add_f32_e32 v85, 1.0, v85
	v_rcp_f32_e32 v74, v74
	v_rcp_f32_e32 v75, v75
	v_mul_f32_e32 v76, 0xbfb8aa3b, v76
	v_ashrrev_i32_e32 v99, 31, v98
	v_rcp_f32_e32 v84, v84
	v_rcp_f32_e32 v85, v85
	v_exp_f32_e32 v76, v76
	v_lshlrev_b64 v[98:99], 11, v[98:99]
	v_lshl_add_u64 v[98:99], s[6:7], 0, v[98:99]
	v_lshl_add_u64 v[98:99], v[98:99], 0, v[144:145]
	v_mul_f32_e32 v91, v96, v91
	v_mul_f32_e32 v92, v97, v92
	v_mul_f32_e32 v82, v86, v82
	v_mul_f32_e32 v83, v87, v83
	v_mul_f32_e32 v74, v78, v74
	v_mul_f32_e32 v75, v79, v75
	v_cvt_pk_bf16_f32 v91, v91, v92
	v_cvt_pk_bf16_f32 v92, v82, v83
	v_mul_f32_e32 v82, v88, v84
	v_mul_f32_e32 v83, v89, v85
	v_cvt_pk_bf16_f32 v93, v82, v83
	global_store_dwordx4 v[98:99], v[90:93], off
	v_cvt_pk_bf16_f32 v74, v74, v75
	v_add_f32_e32 v75, 1.0, v76
	v_mul_f32_e32 v76, 0xbfb8aa3b, v77
	v_mul_f32_e32 v66, 0xbfb8aa3b, v66
	v_mul_f32_e32 v67, 0xbfb8aa3b, v67
	v_mul_f32_e32 v58, 0xbfb8aa3b, v58
	v_mul_f32_e32 v59, 0xbfb8aa3b, v59
	v_exp_f32_e32 v76, v76
	v_exp_f32_e32 v66, v66
	v_exp_f32_e32 v67, v67
	v_mul_f32_e32 v68, 0xbfb8aa3b, v68
	v_mul_f32_e32 v69, 0xbfb8aa3b, v69
	v_exp_f32_e32 v58, v58
	v_exp_f32_e32 v59, v59
	v_exp_f32_e32 v68, v68
	v_exp_f32_e32 v69, v69
	v_add_f32_e32 v76, 1.0, v76
	v_add_f32_e32 v66, 1.0, v66
	v_add_f32_e32 v67, 1.0, v67
	v_add_f32_e32 v58, 1.0, v58
	v_add_f32_e32 v59, 1.0, v59
	v_or_b32_e32 v82, 48, v142
	v_rcp_f32_e32 v75, v75
	v_rcp_f32_e32 v76, v76
	v_rcp_f32_e32 v66, v66
	v_rcp_f32_e32 v67, v67
	v_add_f32_e32 v68, 1.0, v68
	v_add_f32_e32 v69, 1.0, v69
	v_rcp_f32_e32 v58, v58
	v_rcp_f32_e32 v59, v59
	v_mul_f32_e32 v60, 0xbfb8aa3b, v60
	v_ashrrev_i32_e32 v83, 31, v82
	v_rcp_f32_e32 v68, v68
	v_rcp_f32_e32 v69, v69
	v_exp_f32_e32 v60, v60
	v_lshlrev_b64 v[82:83], 11, v[82:83]
	v_lshl_add_u64 v[82:83], s[6:7], 0, v[82:83]
	v_lshl_add_u64 v[82:83], v[82:83], 0, v[144:145]
	v_mul_f32_e32 v75, v80, v75
	v_mul_f32_e32 v76, v81, v76
	v_mul_f32_e32 v66, v70, v66
	v_mul_f32_e32 v67, v71, v67
	v_mul_f32_e32 v58, v62, v58
	v_mul_f32_e32 v59, v63, v59
	v_cvt_pk_bf16_f32 v75, v75, v76
	v_cvt_pk_bf16_f32 v76, v66, v67
	v_mul_f32_e32 v66, v72, v68
	v_mul_f32_e32 v67, v73, v69
	v_cvt_pk_bf16_f32 v77, v66, v67
	global_store_dwordx4 v[82:83], v[74:77], off
	v_cvt_pk_bf16_f32 v58, v58, v59
	v_add_f32_e32 v59, 1.0, v60
	v_mul_f32_e32 v60, 0xbfb8aa3b, v61
	v_mul_f32_e32 v50, 0xbfb8aa3b, v50
	v_exp_f32_e32 v60, v60
	v_exp_f32_e32 v50, v50
	v_mul_f32_e32 v51, 0xbfb8aa3b, v51
	v_mul_f32_e32 v52, 0xbfb8aa3b, v52
	v_exp_f32_e32 v51, v51
	v_exp_f32_e32 v52, v52
	v_mul_f32_e32 v53, 0xbfb8aa3b, v53
	v_exp_f32_e32 v53, v53
	v_mul_f32_e32 v42, 0xbfb8aa3b, v42
	v_mul_f32_e32 v43, 0xbfb8aa3b, v43
	v_exp_f32_e32 v42, v42
	v_exp_f32_e32 v43, v43
	v_add_f32_e32 v60, 1.0, v60
	v_add_f32_e32 v50, 1.0, v50
	v_rcp_f32_e32 v59, v59
	v_rcp_f32_e32 v60, v60
	v_rcp_f32_e32 v50, v50
	v_add_f32_e32 v51, 1.0, v51
	v_add_f32_e32 v52, 1.0, v52
	v_rcp_f32_e32 v51, v51
	v_rcp_f32_e32 v52, v52
	v_add_f32_e32 v53, 1.0, v53
	v_rcp_f32_e32 v53, v53
	v_add_f32_e32 v42, 1.0, v42
	v_add_f32_e32 v43, 1.0, v43
; __device__ __forceinline__ unsigned pk2(float lo, float hi) { unsigned r; asm volatile("v_cvt_pk_bf16_f32 %0, %1, %2" : "=v"(r) : "v"(lo), "v"(hi)); return r; }
; __device__ __forceinline__ float sigmoidf_(float v) { return __builtin_amdgcn_rcpf(1.f + __expf(-v)); }
; #define PG8_WAIT_V(n) asm volatile("s_waitcnt vmcnt(" #n ")" ::: "memory")
; #define PG8_BAR __builtin_amdgcn_s_barrier()
; template <class Epi>
; __device__ __forceinline__ void gemm_phase(LAS unsigned char* lds, const Gemm g, const StaticOrder& S, const Epi& E) {
;     ...
;         if (!has_next) break;
; #pragma unroll
;         for (int a = 0; a < 2; ++a)
; #pragma unroll
;             for (int b = 0; b < 2; ++b)
; #pragma unroll
;                 for (int m = 0; m < 4; ++m)
; #pragma unroll
;                     for (int n = 0; n < 2; ++n) acc[a][b][m][n] = (f32x4){0.f, 0.f, 0.f, 0.f};
;         cur = nxt; cA = nA; cB = nB; ++ui;
;     }
;     PG8_WAIT_V(0);
;     if (wr == 0) PG8_BAR;
;     PG8_BAR;
;     __device__ __forceinline__ void operator()(const f32x4 (&acc)[2][2][4][2], const Unit& u, int wr, int wc, int fr, int fq) const {
;     ...
;             for (int m = 0; m < 4; ++m) { bf16_t* rp = OB + (size_t)(rowb + ai * 128 + m * 16) * 1024 + colb;
;                 const f32x4 a0 = acc[ai][0][m][0], g0 = acc[ai][1][m][0], a1 = acc[ai][0][m][1], g1 = acc[ai][1][m][1];
;                 u32x4 o; o[0] = pk2(a0[0] * sigmoidf_(g0[0]), a0[1] * sigmoidf_(g0[1])); o[1] = pk2(a0[2] * sigmoidf_(g0[2]), a0[3] * sigmoidf_(g0[3]));
;                 o[2] = pk2(a1[0] * sigmoidf_(g1[0]), a1[1] * sigmoidf_(g1[1])); o[3] = pk2(a1[2] * sigmoidf_(g1[2]), a1[3] * sigmoidf_(g1[3])); *(u32x4*)rp = o; }
	v_rcp_f32_e32 v42, v42
	v_rcp_f32_e32 v43, v43
	v_mul_f32_e32 v44, 0xbfb8aa3b, v44
	v_mul_f32_e32 v59, v64, v59
	v_mul_f32_e32 v60, v65, v60
	v_mul_f32_e32 v50, v54, v50
	v_exp_f32_e32 v44, v44
	v_cvt_pk_bf16_f32 v59, v59, v60
	v_mul_f32_e32 v51, v55, v51
	v_cvt_pk_bf16_f32 v60, v50, v51
	v_mul_f32_e32 v50, v56, v52
	s_mov_b32 s6, 0x40000
	v_mul_f32_e32 v51, v57, v53
	v_cvt_pk_bf16_f32 v61, v50, v51
	v_add_co_u32_e32 v50, vcc, s6, v122
	v_mul_f32_e32 v42, v46, v42
	s_nop 0
	v_addc_co_u32_e32 v51, vcc, 0, v123, vcc
	v_mul_f32_e32 v43, v47, v43
	global_store_dwordx4 v[50:51], v[58:61], off
	v_cvt_pk_bf16_f32 v42, v42, v43
	v_add_f32_e32 v43, 1.0, v44
	v_mul_f32_e32 v44, 0xbfb8aa3b, v45
	v_mul_f32_e32 v34, 0xbfb8aa3b, v34
	v_exp_f32_e32 v44, v44
	v_exp_f32_e32 v34, v34
	v_mul_f32_e32 v35, 0xbfb8aa3b, v35
	v_mul_f32_e32 v36, 0xbfb8aa3b, v36
	v_exp_f32_e32 v35, v35
	v_exp_f32_e32 v36, v36
	v_mul_f32_e32 v37, 0xbfb8aa3b, v37
	v_exp_f32_e32 v37, v37
	v_mul_f32_e32 v26, 0xbfb8aa3b, v26
	v_mul_f32_e32 v27, 0xbfb8aa3b, v27
	v_exp_f32_e32 v26, v26
	v_exp_f32_e32 v27, v27
	v_add_f32_e32 v44, 1.0, v44
	v_add_f32_e32 v34, 1.0, v34
	v_rcp_f32_e32 v43, v43
	v_rcp_f32_e32 v44, v44
	v_rcp_f32_e32 v34, v34
	v_add_f32_e32 v35, 1.0, v35
	v_add_f32_e32 v36, 1.0, v36
	v_rcp_f32_e32 v35, v35
	v_rcp_f32_e32 v36, v36
	v_add_f32_e32 v37, 1.0, v37
	v_rcp_f32_e32 v37, v37
	v_add_f32_e32 v26, 1.0, v26
	v_add_f32_e32 v27, 1.0, v27
	v_rcp_f32_e32 v26, v26
	v_rcp_f32_e32 v27, v27
	v_mul_f32_e32 v28, 0xbfb8aa3b, v28
	v_mul_f32_e32 v43, v48, v43
	v_mul_f32_e32 v44, v49, v44
	v_mul_f32_e32 v34, v38, v34
	v_exp_f32_e32 v28, v28
	v_cvt_pk_bf16_f32 v43, v43, v44
	v_mul_f32_e32 v35, v39, v35
	v_cvt_pk_bf16_f32 v44, v34, v35
	v_mul_f32_e32 v34, v40, v36
	s_mov_b32 s6, 0x48000
	v_mul_f32_e32 v35, v41, v37
	v_cvt_pk_bf16_f32 v45, v34, v35
	v_add_co_u32_e32 v34, vcc, s6, v122
	v_mul_f32_e32 v26, v30, v26
	s_nop 0
	v_addc_co_u32_e32 v35, vcc, 0, v123, vcc
	v_mul_f32_e32 v27, v31, v27
	global_store_dwordx4 v[34:35], v[42:45], off
	v_cvt_pk_bf16_f32 v26, v26, v27
	v_add_f32_e32 v27, 1.0, v28
	v_mul_f32_e32 v28, 0xbfb8aa3b, v29
	v_mul_f32_e32 v18, 0xbfb8aa3b, v18
	v_exp_f32_e32 v28, v28
	v_exp_f32_e32 v18, v18
	v_mul_f32_e32 v19, 0xbfb8aa3b, v19
	v_mul_f32_e32 v20, 0xbfb8aa3b, v20
	v_exp_f32_e32 v19, v19
	v_exp_f32_e32 v20, v20
	v_mul_f32_e32 v21, 0xbfb8aa3b, v21
	v_exp_f32_e32 v21, v21
	v_mul_f32_e32 v10, 0xbfb8aa3b, v10
	v_mul_f32_e32 v11, 0xbfb8aa3b, v11
	v_exp_f32_e32 v10, v10
	v_exp_f32_e32 v11, v11
	v_add_f32_e32 v28, 1.0, v28
	v_add_f32_e32 v18, 1.0, v18
	v_rcp_f32_e32 v27, v27
	v_rcp_f32_e32 v28, v28
	v_rcp_f32_e32 v18, v18
	v_add_f32_e32 v19, 1.0, v19
	v_add_f32_e32 v20, 1.0, v20
	v_rcp_f32_e32 v19, v19
	v_rcp_f32_e32 v20, v20
	v_add_f32_e32 v21, 1.0, v21
	v_rcp_f32_e32 v21, v21
	v_add_f32_e32 v10, 1.0, v10
	v_add_f32_e32 v11, 1.0, v11
	v_rcp_f32_e32 v10, v10
	v_rcp_f32_e32 v11, v11
	v_mul_f32_e32 v12, 0xbfb8aa3b, v12
	v_mul_f32_e32 v27, v32, v27
	v_mul_f32_e32 v28, v33, v28
	v_mul_f32_e32 v18, v22, v18
	v_exp_f32_e32 v12, v12
	v_cvt_pk_bf16_f32 v27, v27, v28
	v_mul_f32_e32 v19, v23, v19
	v_cvt_pk_bf16_f32 v28, v18, v19
	v_mul_f32_e32 v18, v24, v20
	s_mov_b32 s6, 0x50000
	v_mul_f32_e32 v19, v25, v21
	v_cvt_pk_bf16_f32 v29, v18, v19
	v_add_co_u32_e32 v18, vcc, s6, v122
	v_mul_f32_e32 v10, v14, v10
	s_nop 0
	v_addc_co_u32_e32 v19, vcc, 0, v123, vcc
	v_mul_f32_e32 v11, v15, v11
	global_store_dwordx4 v[18:19], v[26:29], off
	v_cvt_pk_bf16_f32 v10, v10, v11
	v_add_f32_e32 v11, 1.0, v12
	v_mul_f32_e32 v12, 0xbfb8aa3b, v13
	v_mul_f32_e32 v2, 0xbfb8aa3b, v2
	v_exp_f32_e32 v12, v12
	v_exp_f32_e32 v2, v2
	v_mul_f32_e32 v3, 0xbfb8aa3b, v3
	v_mul_f32_e32 v4, 0xbfb8aa3b, v4
	v_exp_f32_e32 v3, v3
	v_exp_f32_e32 v4, v4
	v_mul_f32_e32 v5, 0xbfb8aa3b, v5
	v_exp_f32_e32 v5, v5
	v_add_f32_e32 v12, 1.0, v12
	v_add_f32_e32 v2, 1.0, v2
	v_rcp_f32_e32 v11, v11
	v_rcp_f32_e32 v12, v12
	v_rcp_f32_e32 v2, v2
	v_add_f32_e32 v3, 1.0, v3
	v_add_f32_e32 v4, 1.0, v4
	v_rcp_f32_e32 v3, v3
	v_rcp_f32_e32 v4, v4
	v_add_f32_e32 v5, 1.0, v5
	v_rcp_f32_e32 v5, v5
	v_mul_f32_e32 v11, v16, v11
	v_mul_f32_e32 v12, v17, v12
	v_mul_f32_e32 v2, v6, v2
	v_cvt_pk_bf16_f32 v11, v11, v12
	v_mul_f32_e32 v3, v7, v3
	v_cvt_pk_bf16_f32 v12, v2, v3
	v_mul_f32_e32 v2, v8, v4
	v_mul_f32_e32 v3, v9, v5
	v_cvt_pk_bf16_f32 v13, v2, v3
	v_add_co_u32_e32 v2, vcc, 0x58000, v122
	s_mov_b32 s33, s18
	s_nop 0
	v_addc_co_u32_e32 v3, vcc, 0, v123, vcc
	s_and_b64 vcc, exec, s[40:41]
	s_mov_b32 s30, s24
	s_mov_b64 s[36:37], s[28:29]
	s_mov_b64 s[34:35], s[26:27]
	global_store_dwordx4 v[2:3], v[10:13], off
	s_cbranch_vccz .LBB0_234
	s_waitcnt vmcnt(0)
	s_cmpk_gt_u32 s8, 0xff
	s_cbranch_scc1 .LBB0_241
	s_barrier

; #define LAS __attribute__((address_space(3)))
; __device__ __forceinline__ int ltid() { int t = threadIdx.x; asm volatile("" : "+v"(t)); return t; }
; #define PG8_BAR __builtin_amdgcn_s_barrier()
;     __device__ bool next(int i, Unit& u) const {
;         const long L = (long)i * G + c; if (L >= nwg) return false;
;         int wgid = (int)L; { const int q = nwg / NXCD, r = nwg % NXCD, xcd = wgid % NXCD, off = wgid / NXCD; wgid = (xcd < r ? xcd * (q + 1) : r * (q + 1) + (xcd - r) * q) + off; }
;         const int nig = WGM * nN, gid = wgid / nig, fm = gid * WGM, gsz = (nM - fm) < WGM ? (nM - fm) : WGM;
;         u.pm = fm + ((wgid % nig) % gsz); u.pn = (wgid % nig) / gsz; return true;
;     }
; template <class Epi>
; __device__ __forceinline__ void gemm_phase(LAS unsigned char* lds, const Gemm g, const StaticOrder& S, const Epi& E) {
;     const int tid = ltid(), wid = __builtin_amdgcn_readfirstlane(tid >> 6), lane = tid & 63, wr = wid >> 2, wc = wid & 3, fr = lane & 15, fq = lane >> 4;
;     const int K = g.K, nt = K / BK;
;     unsigned voffA[2], voffB[2];
; #pragma unroll
;     for (int i = 0; i < 2; ++i) { int R, C; stage_rc(tid * 16 + i * 8192, R, C); voffA[i] = (unsigned)(R * g.lda + C) * 2u; voffB[i] = (unsigned)(R * g.ldb + C) * 2u; }
;     const size_t kstep = (size_t)(BK * 2);
;     const size_t hstepA = (size_t)HALF * g.lda * 2, hstepB = (size_t)HALF * g.ldb * 2;
;     const size_t tstepA = 2 * hstepA, tstepB = 2 * hstepB;
;     const unsigned ldsw = (unsigned)wid * 1024u;
;     const int aoff = lds_byte(wr * 64 + fr, fq * 8), boff = lds_byte(wc * 32 + fr, fq * 8);
;     ...
;     Unit cur, nxt; int ui = 0;
;     if (!S.next(0, cur)) return;
;     f32x4 acc[2][2][4][2];
; #pragma unroll
;     for (int a = 0; a < 2; ++a)
; #pragma unroll
;         for (int b = 0; b < 2; ++b)
; #pragma unroll
;             for (int m = 0; m < 4; ++m)
; #pragma unroll
;                 for (int n = 0; n < 2; ++n) acc[a][b][m][n] = (f32x4){0.f, 0.f, 0.f, 0.f};
;     bf16x8 At[4][2], B0[2][2], B1[2][2];
;     const char* cA = (const char*)g.A + (size_t)cur.pm * tstepA; const char* cB = (const char*)g.Bt + (size_t)cur.pn * tstepB;
;     PG8_STAGE(PG8_SB(0, 0), cB, voffB); PG8_STAGE(PG8_SA(0, 0), cA, voffA); PG8_STAGE(PG8_SB(0, 1), cB + hstepB, voffB); PG8_STAGE(PG8_SA(0, 1), cA + hstepA, voffA);
;     if (wr == 1) PG8_BAR;
.LBB0_888:
	v_readlane_b32 s0, v255, 30
	v_readlane_b32 s1, v255, 31
	s_load_dwordx2 s[18:19], s[0:1], 0x110
	s_load_dwordx4 s[48:51], s[0:1], 0xd0
	s_andn2_b64 vcc, exec, s[24:25]
	s_cbranch_vccnz .LBB0_8
	v_ashrrev_i32_e32 v3, 31, v1
	v_lshrrev_b32_e32 v3, 26, v3
	v_add_u32_e32 v3, v1, v3
	s_waitcnt vmcnt(0)
	v_ashrrev_i32_e32 v10, 6, v3
	v_bfe_i32 v3, v1, 27, 1
	v_lshlrev_b32_e32 v2, 4, v1
	v_lshrrev_b32_e32 v3, 22, v3
	v_add_u32_e32 v3, v2, v3
	v_and_b32_e32 v3, 0xfffffc00, v3
	v_sub_u32_e32 v3, v2, v3
	v_lshrrev_b32_e32 v4, 4, v3
	v_bitop3_b32 v4, v4, v3, 32 bitop3:0x6c
	v_ashrrev_i32_e32 v3, 31, v3
	v_lshrrev_b32_e32 v3, 26, v3
	v_add_u32_e32 v3, v4, v3
	v_ashrrev_i32_e32 v11, 6, v3
	v_mul_i32_i24_e32 v6, 64, v11
	v_sub_u32_e32 v4, v4, v6
	v_lshlrev_b32_e32 v5, 3, v10
	v_lshlrev_b32_e32 v3, 5, v10
	v_ashrrev_i16_sdwa v4, v201, sext(v4) dst_sel:DWORD dst_unused:UNUSED_PAD src0_sel:DWORD src1_sel:BYTE_0
	v_and_b32_e32 v5, 0x1ffff0, v5
	v_and_b32_e32 v3, 32, v3
	v_bfe_i32 v12, v4, 0, 16
	v_add_u32_e32 v3, v3, v12
	v_add_lshl_u32 v4, v11, v5, 11
	v_add_u32_e32 v2, 0x2000, v2
	v_lshl_add_u32 v146, v3, 1, v4
	v_ashrrev_i32_e32 v3, 31, v2
	v_lshrrev_b32_e32 v3, 22, v3
	v_add_u32_e32 v3, v2, v3
	v_ashrrev_i32_e32 v13, 10, v3
	v_mul_i32_i24_e32 v3, 0x400, v13
	v_sub_u32_e32 v2, v2, v3
	v_lshrrev_b32_e32 v3, 4, v2
	v_bitop3_b32 v2, v3, v2, 32 bitop3:0x6c
	v_ashrrev_i32_e32 v4, 31, v2
	v_lshrrev_b32_e32 v4, 26, v4
	s_ashr_i32 s0, s14, 6
	v_add_u32_e32 v4, v2, v4
	s_ashr_i32 s31, s30, 31
	s_ashr_i32 s29, s28, 31
	v_ashrrev_i32_e32 v14, 6, v4
	v_and_b32_e32 v4, 0xc0, v4
	s_ashr_i32 s1, s14, 8
	s_lshl_b32 s15, s0, 10
	s_lshl_b64 s[8:9], s[30:31], 19
	s_lshl_b64 s[10:11], s[28:29], 19
	v_readlane_b32 s6, v255, 38
	v_sub_u32_e32 v2, v2, v4
	v_readlane_b32 s7, v255, 39
	s_add_u32 s36, s6, s10
	v_lshlrev_b32_e32 v3, 3, v13
	v_lshlrev_b32_e32 v5, 5, v13
	v_ashrrev_i16_sdwa v2, v201, sext(v2) dst_sel:DWORD dst_unused:UNUSED_PAD src0_sel:DWORD src1_sel:BYTE_0
	s_addc_u32 s37, s7, s11
	s_add_i32 s20, s15, 0
	v_and_b32_e32 v3, 0x1ffff0, v3
	v_and_b32_e32 v5, 32, v5
	v_bfe_i32 v15, v2, 0, 16
	s_add_i32 m0, s20, 0x10000
	v_add_u32_e32 v2, v5, v15
	v_add_lshl_u32 v3, v14, v3, 11
	global_load_lds_dwordx4 v146, s[36:37]
	s_add_i32 m0, s20, 0x12000
	v_lshl_add_u32 v148, v2, 1, v3
	s_add_u32 s34, s2, s8
	global_load_lds_dwordx4 v148, s[36:37]
	s_addc_u32 s35, s3, s9
	s_mov_b32 m0, s20
	s_add_i32 s21, s20, 0x2000
	global_load_lds_dwordx4 v146, s[34:35]
	s_mov_b32 m0, s21
	s_add_u32 s8, s36, 0x40000
	global_load_lds_dwordx4 v148, s[34:35]
	s_addc_u32 s9, s37, 0
	s_add_i32 m0, s20, 0x14000
	v_mov_b32_e32 v147, v0
	global_load_lds_dwordx4 v146, s[8:9]
	s_add_i32 m0, s20, 0x16000
	v_mov_b32_e32 v149, v0
	global_load_lds_dwordx4 v148, s[8:9]
	s_add_u32 s8, s34, 0x40000
	s_addc_u32 s9, s35, 0
	s_add_i32 s29, s20, 0x4000
	s_mov_b32 m0, s29
	s_add_i32 s56, s20, 0x6000
	global_load_lds_dwordx4 v146, s[8:9]
	s_mov_b32 m0, s56
	v_lshl_add_u64 v[8:9], s[36:37], 0, v[146:147]
	global_load_lds_dwordx4 v148, s[8:9]
	v_lshl_add_u64 v[6:7], s[36:37], 0, v[148:149]
	v_lshl_add_u64 v[4:5], s[34:35], 0, v[146:147]
	s_cmp_lg_u32 s1, 1
	v_lshl_add_u64 v[2:3], s[34:35], 0, v[148:149]
	s_cbranch_scc1 .LBB0_891
	s_barrier
	s_setprio 1

; #define PG8_STAGE(bufoff, gbase, voff) do { _Pragma("unroll") for (int _i = 0; _i < 2; ++_i) \
;         __builtin_amdgcn_global_load_lds((const unsigned*)((const char*)(gbase) + (voff)[_i]), (LAS unsigned*)(lds + (bufoff) + ldsw + _i * 8192), 16, 0, 0); } while (0)
; #define PG8_LDA(dst, b, h) do { _Pragma("unroll") for (int m = 0; m < 4; ++m) _Pragma("unroll") for (int k = 0; k < 2; ++k) dst[m][k] = *(const LAS bf16x8*)(lds + PG8_SA(b, h) + aoff + m * 2048 + k * 1024); } while (0)
; #define PG8_LDB(dst, b, h) do { _Pragma("unroll") for (int n = 0; n < 2; ++n) _Pragma("unroll") for (int k = 0; k < 2; ++k) dst[n][k] = *(const LAS bf16x8*)(lds + PG8_SB(b, h) + boff + n * 2048 + k * 1024); } while (0)
; #define PG8_WAIT_V(n) asm volatile("s_waitcnt vmcnt(" #n ")" ::: "memory")
; #define PG8_WAIT_L(n) asm volatile("s_waitcnt lgkmcnt(" #n ")" ::: "memory")
; #define PG8_BAR __builtin_amdgcn_s_barrier()
; #define PG8_SCHED __builtin_amdgcn_sched_barrier(0)
; template <class Epi>
; __device__ __forceinline__ void gemm_phase(LAS unsigned char* lds, const Gemm g, const StaticOrder& S, const Epi& E) {
;     ...
;         const bool has_next = S.next(ui + 1, nxt);
;         const char* nA = has_next ? (const char*)g.A + (size_t)nxt.pm * tstepA : cA; const char* nB = has_next ? (const char*)g.Bt + (size_t)nxt.pn * tstepB : cB;
;         for (int t = 0; t < nt; t += 2) {
;             const bool last = (t == nt - 2);
;             const char* a1 = cA + (size_t)(t + 1) * kstep;
;             const char* a2 = last ? nA : cA + (size_t)(t + 2) * kstep; const char* b2 = last ? nB : cB + (size_t)(t + 2) * kstep;
;             const char* a3 = a2 + kstep; const char* b3 = b2 + kstep;
;             PG8_LDB(B0, 0, 0); PG8_SCHED; PG8_LDA(At, 0, 0); PG8_STAGE(PG8_SA(1, 1), a1 + hstepA, voffA);
;             PG8_WAIT_L(8); PG8_BAR; PG8_WAIT_L(0); PG8_MMA(0, 0, At, B0); PG8_BAR; PG8_SCHED;
;             PG8_LDB(B1, 0, 1); PG8_STAGE(PG8_SB(0, 0), b2, voffB);
;             PG8_BAR; PG8_WAIT_L(0); PG8_MMA(0, 1, At, B1); PG8_BAR;
;             PG8_LDA(At, 0, 1); PG8_STAGE(PG8_SA(0, 0), a2, voffA);
;             PG8_BAR; PG8_WAIT_L(0); PG8_MMA(1, 0, At, B0); PG8_BAR; PG8_SCHED;
;             PG8_STAGE(PG8_SB(0, 1), b2 + hstepB, voffB);
;             PG8_WAIT_V(6); PG8_BAR; PG8_MMA(1, 1, At, B1); PG8_BAR;
.LBB0_901:
	s_add_u32 s6, s34, 0xfffc0080
	s_addc_u32 s7, s35, -1
	s_add_i32 s33, 0, 0x10000
	s_waitcnt vmcnt(0)
	v_add_u32_e32 v142, s33, v1
	ds_read_b128 v[130:133], v142
	ds_read_b128 v[134:137], v142 offset:1024
	ds_read_b128 v[138:141], v142 offset:2048
	ds_read_b128 v[142:145], v142 offset:3072
	s_cmp_eq_u32 s31, 12
	s_cselect_b32 s43, s8, s7
	s_cselect_b32 s42, s9, s6
	s_cselect_b32 s37, s10, s27
	s_cselect_b32 s36, s11, s25
	v_lshl_add_u64 v[232:233], s[34:35], 0, v[178:179]
	s_add_i32 m0, s20, 0xc000
	ds_read_b128 v[184:187], v151
	ds_read_b128 v[188:191], v151 offset:1024
	ds_read_b128 v[192:195], v151 offset:2048
	ds_read_b128 v[196:199], v151 offset:3072
	ds_read_b128 v[216:219], v151 offset:4096
	ds_read_b128 v[220:223], v151 offset:5120
	ds_read_b128 v[224:227], v151 offset:6144
	ds_read_b128 v[228:231], v151 offset:7168
	global_load_lds_dwordx4 v[232:233], off
	v_lshl_add_u64 v[232:233], s[34:35], 0, v[180:181]
	s_add_i32 m0, s20, 0xe000
	s_nop 0
	global_load_lds_dwordx4 v[232:233], off
	s_waitcnt lgkmcnt(8)
	s_barrier
	s_waitcnt lgkmcnt(0)
	s_waitcnt lgkmcnt(0)
	v_mfma_f32_16x16x32_bf16 v[126:129], v[130:133], v[184:187], v[126:129]
	v_mfma_f32_16x16x32_bf16 v[122:125], v[138:141], v[184:187], v[122:125]
	v_mfma_f32_16x16x32_bf16 v[110:113], v[130:133], v[192:195], v[110:113]
	v_mfma_f32_16x16x32_bf16 v[106:109], v[138:141], v[192:195], v[106:109]
	v_mfma_f32_16x16x32_bf16 v[94:97], v[130:133], v[216:219], v[94:97]
	v_mfma_f32_16x16x32_bf16 v[90:93], v[138:141], v[216:219], v[90:93]
	v_mfma_f32_16x16x32_bf16 v[78:81], v[130:133], v[224:227], v[78:81]
	v_mfma_f32_16x16x32_bf16 v[74:77], v[138:141], v[224:227], v[74:77]
	v_mfma_f32_16x16x32_bf16 v[126:129], v[134:137], v[188:191], v[126:129]
	v_mfma_f32_16x16x32_bf16 v[122:125], v[142:145], v[188:191], v[122:125]
	v_mfma_f32_16x16x32_bf16 v[110:113], v[134:137], v[196:199], v[110:113]
	v_mfma_f32_16x16x32_bf16 v[106:109], v[142:145], v[196:199], v[106:109]
	v_mfma_f32_16x16x32_bf16 v[94:97], v[134:137], v[220:223], v[94:97]
	v_mfma_f32_16x16x32_bf16 v[90:93], v[142:145], v[220:223], v[90:93]
	v_mfma_f32_16x16x32_bf16 v[78:81], v[134:137], v[228:231], v[78:81]
	v_mfma_f32_16x16x32_bf16 v[74:77], v[142:145], v[228:231], v[74:77]
	s_barrier
	s_add_i32 s6, 0, 0x14000
	s_add_i32 s7, s33, s15
	v_add_u32_e32 v153, s6, v1
	v_lshl_add_u64 v[248:249], s[36:37], 0, v[146:147]
	s_mov_b32 m0, s7
	ds_read_b128 v[232:235], v153
	ds_read_b128 v[236:239], v153 offset:1024
	ds_read_b128 v[240:243], v153 offset:2048
	ds_read_b128 v[244:247], v153 offset:3072
	global_load_lds_dwordx4 v[248:249], off
	v_lshl_add_u64 v[250:251], s[36:37], 0, v[148:149]
	s_add_i32 m0, s7, 0x2000
	s_nop 0
	global_load_lds_dwordx4 v[250:251], off
	s_barrier
	s_waitcnt lgkmcnt(0)
	s_waitcnt lgkmcnt(0)
	v_mfma_f32_16x16x32_bf16 v[118:121], v[232:235], v[184:187], v[118:121]
	v_mfma_f32_16x16x32_bf16 v[114:117], v[240:243], v[184:187], v[114:117]
	v_mfma_f32_16x16x32_bf16 v[102:105], v[232:235], v[192:195], v[102:105]
	v_mfma_f32_16x16x32_bf16 v[98:101], v[240:243], v[192:195], v[98:101]
	v_mfma_f32_16x16x32_bf16 v[86:89], v[232:235], v[216:219], v[86:89]
	v_mfma_f32_16x16x32_bf16 v[82:85], v[240:243], v[216:219], v[82:85]
	v_mfma_f32_16x16x32_bf16 v[70:73], v[232:235], v[224:227], v[70:73]
	v_mfma_f32_16x16x32_bf16 v[66:69], v[240:243], v[224:227], v[66:69]
	v_mfma_f32_16x16x32_bf16 v[118:121], v[236:239], v[188:191], v[118:121]
	v_mfma_f32_16x16x32_bf16 v[114:117], v[244:247], v[188:191], v[114:117]
	v_mfma_f32_16x16x32_bf16 v[102:105], v[236:239], v[196:199], v[102:105]
	v_mfma_f32_16x16x32_bf16 v[98:101], v[244:247], v[196:199], v[98:101]
	v_mfma_f32_16x16x32_bf16 v[86:89], v[236:239], v[220:223], v[86:89]
	v_mfma_f32_16x16x32_bf16 v[82:85], v[244:247], v[220:223], v[82:85]
	v_mfma_f32_16x16x32_bf16 v[70:73], v[236:239], v[228:231], v[70:73]
	v_mfma_f32_16x16x32_bf16 v[66:69], v[244:247], v[228:231], v[66:69]
	s_mov_b32 m0, s20
	v_lshl_add_u64 v[252:253], s[42:43], 0, v[146:147]
	s_barrier
	ds_read_b128 v[184:187], v151 offset:16384
	ds_read_b128 v[188:191], v151 offset:17408
	ds_read_b128 v[192:195], v151 offset:18432
	ds_read_b128 v[196:199], v151 offset:19456
	ds_read_b128 v[216:219], v151 offset:20480
	ds_read_b128 v[220:223], v151 offset:21504
	ds_read_b128 v[224:227], v151 offset:22528
	ds_read_b128 v[228:231], v151 offset:23552
	global_load_lds_dwordx4 v[252:253], off
	v_lshl_add_u64 v[212:213], s[42:43], 0, v[148:149]
	s_mov_b32 m0, s21
	s_nop 0
	global_load_lds_dwordx4 v[212:213], off
	s_barrier
	s_waitcnt lgkmcnt(0)
	s_waitcnt lgkmcnt(0)
	v_mfma_f32_16x16x32_bf16 v[62:65], v[130:133], v[184:187], v[62:65]
	v_mfma_f32_16x16x32_bf16 v[58:61], v[138:141], v[184:187], v[58:61]
	v_mfma_f32_16x16x32_bf16 v[46:49], v[130:133], v[192:195], v[46:49]
	v_mfma_f32_16x16x32_bf16 v[42:45], v[138:141], v[192:195], v[42:45]
	v_mfma_f32_16x16x32_bf16 v[30:33], v[130:133], v[216:219], v[30:33]
	v_mfma_f32_16x16x32_bf16 v[26:29], v[138:141], v[216:219], v[26:29]
	v_mfma_f32_16x16x32_bf16 v[14:17], v[130:133], v[224:227], v[14:17]
	v_mfma_f32_16x16x32_bf16 v[10:13], v[138:141], v[224:227], v[10:13]
	v_mfma_f32_16x16x32_bf16 v[62:65], v[134:137], v[188:191], v[62:65]
	v_mfma_f32_16x16x32_bf16 v[58:61], v[142:145], v[188:191], v[58:61]
	v_mfma_f32_16x16x32_bf16 v[46:49], v[134:137], v[196:199], v[46:49]
	v_mfma_f32_16x16x32_bf16 v[42:45], v[142:145], v[196:199], v[42:45]
	v_mfma_f32_16x16x32_bf16 v[30:33], v[134:137], v[220:223], v[30:33]
	v_mfma_f32_16x16x32_bf16 v[26:29], v[142:145], v[220:223], v[26:29]
	v_mfma_f32_16x16x32_bf16 v[14:17], v[134:137], v[228:231], v[14:17]
	v_mfma_f32_16x16x32_bf16 v[10:13], v[142:145], v[228:231], v[10:13]
	s_barrier
; #define PG8_STAGE(bufoff, gbase, voff) do { _Pragma("unroll") for (int _i = 0; _i < 2; ++_i) \
;         __builtin_amdgcn_global_load_lds((const unsigned*)((const char*)(gbase) + (voff)[_i]), (LAS unsigned*)(lds + (bufoff) + ldsw + _i * 8192), 16, 0, 0); } while (0)
; #define PG8_LDA(dst, b, h) do { _Pragma("unroll") for (int m = 0; m < 4; ++m) _Pragma("unroll") for (int k = 0; k < 2; ++k) dst[m][k] = *(const LAS bf16x8*)(lds + PG8_SA(b, h) + aoff + m * 2048 + k * 1024); } while (0)
; #define PG8_LDB(dst, b, h) do { _Pragma("unroll") for (int n = 0; n < 2; ++n) _Pragma("unroll") for (int k = 0; k < 2; ++k) dst[n][k] = *(const LAS bf16x8*)(lds + PG8_SB(b, h) + boff + n * 2048 + k * 1024); } while (0)
; #define PG8_MMA(ai, bj, At, Bt) do { __builtin_amdgcn_s_setprio(1); _Pragma("unroll") for (int m = 0; m < 4; ++m) _Pragma("unroll") for (int n = 0; n < 2; ++n) _Pragma("unroll") for (int k = 0; k < 2; ++k) \
;         acc[ai][bj][m][n] = __builtin_amdgcn_mfma_f32_16x16x32_bf16(Bt[n][k], At[m][k], acc[ai][bj][m][n], 0, 0, 0); __builtin_amdgcn_s_setprio(0); } while (0)
; #define PG8_WAIT_V(n) asm volatile("s_waitcnt vmcnt(" #n ")" ::: "memory")
; #define PG8_WAIT_L(n) asm volatile("s_waitcnt lgkmcnt(" #n ")" ::: "memory")
; #define PG8_BAR __builtin_amdgcn_s_barrier()
; #define PG8_SCHED __builtin_amdgcn_sched_barrier(0)
; template <class Epi>
; __device__ __forceinline__ void gemm_phase(LAS unsigned char* lds, const Gemm g, const StaticOrder& S, const Epi& E) {
;     ...
;             PG8_STAGE(PG8_SB(0, 1), b2 + hstepB, voffB);
;             PG8_WAIT_V(6); PG8_BAR; PG8_MMA(1, 1, At, B1); PG8_BAR;
;             PG8_LDB(B0, 1, 0); PG8_SCHED; PG8_LDA(At, 1, 0); PG8_STAGE(PG8_SA(0, 1), a2 + hstepA, voffA);
;             PG8_WAIT_L(8); PG8_BAR; PG8_WAIT_L(0); PG8_MMA(0, 0, At, B0); PG8_BAR; PG8_SCHED;
;             PG8_LDB(B1, 1, 1); PG8_STAGE(PG8_SB(1, 0), b3, voffB);
;             PG8_BAR; PG8_WAIT_L(0); PG8_MMA(0, 1, At, B1); PG8_BAR;
	s_add_u32 s44, s36, 0x40000
	s_addc_u32 s45, s37, 0
	s_add_i32 s6, s6, s15
	v_lshl_add_u64 v[130:131], s[44:45], 0, v[146:147]
	s_mov_b32 m0, s6
	s_nop 0
	global_load_lds_dwordx4 v[130:131], off
	v_lshl_add_u64 v[130:131], s[44:45], 0, v[148:149]
	s_add_i32 m0, s6, 0x2000
	s_nop 0
	global_load_lds_dwordx4 v[130:131], off
	s_waitcnt vmcnt(6)
	s_barrier
	v_mfma_f32_16x16x32_bf16 v[54:57], v[232:235], v[184:187], v[54:57]
	v_mfma_f32_16x16x32_bf16 v[50:53], v[240:243], v[184:187], v[50:53]
	v_mfma_f32_16x16x32_bf16 v[38:41], v[232:235], v[192:195], v[38:41]
	v_mfma_f32_16x16x32_bf16 v[34:37], v[240:243], v[192:195], v[34:37]
	v_mfma_f32_16x16x32_bf16 v[22:25], v[232:235], v[216:219], v[22:25]
	v_mfma_f32_16x16x32_bf16 v[18:21], v[240:243], v[216:219], v[18:21]
	v_mfma_f32_16x16x32_bf16 v[6:9], v[232:235], v[224:227], v[6:9]
	v_mfma_f32_16x16x32_bf16 v[2:5], v[240:243], v[224:227], v[2:5]
	v_mfma_f32_16x16x32_bf16 v[54:57], v[236:239], v[188:191], v[54:57]
	v_mfma_f32_16x16x32_bf16 v[50:53], v[244:247], v[188:191], v[50:53]
	v_mfma_f32_16x16x32_bf16 v[38:41], v[236:239], v[196:199], v[38:41]
	v_mfma_f32_16x16x32_bf16 v[34:37], v[244:247], v[196:199], v[34:37]
	v_mfma_f32_16x16x32_bf16 v[22:25], v[236:239], v[220:223], v[22:25]
	v_mfma_f32_16x16x32_bf16 v[18:21], v[244:247], v[220:223], v[18:21]
	v_mfma_f32_16x16x32_bf16 v[6:9], v[236:239], v[228:231], v[6:9]
	v_mfma_f32_16x16x32_bf16 v[2:5], v[244:247], v[228:231], v[2:5]
	s_add_i32 s6, 0, 0x18000
	v_add_u32_e32 v142, s6, v1
	s_barrier
	ds_read_b128 v[130:133], v142
	ds_read_b128 v[134:137], v142 offset:1024
	ds_read_b128 v[138:141], v142 offset:2048
	ds_read_b128 v[142:145], v142 offset:3072
	s_add_u32 s42, s42, 0x40000
	s_addc_u32 s43, s43, 0
	s_mov_b32 m0, s29
	v_lshl_add_u64 v[232:233], s[42:43], 0, v[146:147]
	ds_read_b128 v[184:187], v151 offset:32768
	ds_read_b128 v[188:191], v151 offset:33792
	ds_read_b128 v[192:195], v151 offset:34816
	ds_read_b128 v[196:199], v151 offset:35840
	ds_read_b128 v[216:219], v151 offset:36864
	ds_read_b128 v[220:223], v151 offset:37888
	ds_read_b128 v[224:227], v151 offset:38912
	ds_read_b128 v[228:231], v151 offset:39936
	global_load_lds_dwordx4 v[232:233], off
	v_lshl_add_u64 v[232:233], s[42:43], 0, v[148:149]
	s_mov_b32 m0, s56
	s_nop 0
	global_load_lds_dwordx4 v[232:233], off
	s_waitcnt lgkmcnt(8)
	s_barrier
	s_waitcnt lgkmcnt(0)
	s_waitcnt lgkmcnt(0)
	v_mfma_f32_16x16x32_bf16 v[126:129], v[130:133], v[184:187], v[126:129]
	v_mfma_f32_16x16x32_bf16 v[122:125], v[138:141], v[184:187], v[122:125]
	v_mfma_f32_16x16x32_bf16 v[110:113], v[130:133], v[192:195], v[110:113]
	v_mfma_f32_16x16x32_bf16 v[106:109], v[138:141], v[192:195], v[106:109]
	v_mfma_f32_16x16x32_bf16 v[94:97], v[130:133], v[216:219], v[94:97]
	v_mfma_f32_16x16x32_bf16 v[90:93], v[138:141], v[216:219], v[90:93]
	v_mfma_f32_16x16x32_bf16 v[78:81], v[130:133], v[224:227], v[78:81]
	v_mfma_f32_16x16x32_bf16 v[74:77], v[138:141], v[224:227], v[74:77]
	v_mfma_f32_16x16x32_bf16 v[126:129], v[134:137], v[188:191], v[126:129]
	v_mfma_f32_16x16x32_bf16 v[122:125], v[142:145], v[188:191], v[122:125]
	v_mfma_f32_16x16x32_bf16 v[110:113], v[134:137], v[196:199], v[110:113]
	v_mfma_f32_16x16x32_bf16 v[106:109], v[142:145], v[196:199], v[106:109]
	v_mfma_f32_16x16x32_bf16 v[94:97], v[134:137], v[220:223], v[94:97]
	v_mfma_f32_16x16x32_bf16 v[90:93], v[142:145], v[220:223], v[90:93]
	v_mfma_f32_16x16x32_bf16 v[78:81], v[134:137], v[228:231], v[78:81]
	v_mfma_f32_16x16x32_bf16 v[74:77], v[142:145], v[228:231], v[74:77]
	s_barrier
	s_add_i32 s7, 0, 0x1c000
	s_add_i32 s6, s6, s15
	v_add_u32_e32 v153, s7, v1
	v_lshl_add_u64 v[248:249], v[248:249], 0, s[88:89]
	s_mov_b32 m0, s6
	ds_read_b128 v[232:235], v153
	ds_read_b128 v[236:239], v153 offset:1024
	ds_read_b128 v[240:243], v153 offset:2048
	ds_read_b128 v[244:247], v153 offset:3072
	global_load_lds_dwordx4 v[248:249], off
	v_lshl_add_u64 v[248:249], v[250:251], 0, s[88:89]
	s_add_i32 m0, s6, 0x2000
	s_nop 0
	global_load_lds_dwordx4 v[248:249], off
	s_barrier
	s_waitcnt lgkmcnt(0)
	s_waitcnt lgkmcnt(0)
	v_mfma_f32_16x16x32_bf16 v[118:121], v[232:235], v[184:187], v[118:121]
	v_mfma_f32_16x16x32_bf16 v[114:117], v[240:243], v[184:187], v[114:117]
	v_mfma_f32_16x16x32_bf16 v[102:105], v[232:235], v[192:195], v[102:105]
	v_mfma_f32_16x16x32_bf16 v[98:101], v[240:243], v[192:195], v[98:101]
	v_mfma_f32_16x16x32_bf16 v[86:89], v[232:235], v[216:219], v[86:89]
	v_mfma_f32_16x16x32_bf16 v[82:85], v[240:243], v[216:219], v[82:85]
	v_mfma_f32_16x16x32_bf16 v[70:73], v[232:235], v[224:227], v[70:73]
	v_mfma_f32_16x16x32_bf16 v[66:69], v[240:243], v[224:227], v[66:69]
	v_mfma_f32_16x16x32_bf16 v[118:121], v[236:239], v[188:191], v[118:121]
	v_mfma_f32_16x16x32_bf16 v[114:117], v[244:247], v[188:191], v[114:117]
	v_mfma_f32_16x16x32_bf16 v[102:105], v[236:239], v[196:199], v[102:105]
	v_mfma_f32_16x16x32_bf16 v[98:101], v[244:247], v[196:199], v[98:101]
	v_mfma_f32_16x16x32_bf16 v[86:89], v[236:239], v[220:223], v[86:89]
	v_mfma_f32_16x16x32_bf16 v[82:85], v[244:247], v[220:223], v[82:85]
	v_mfma_f32_16x16x32_bf16 v[70:73], v[236:239], v[228:231], v[70:73]
	v_mfma_f32_16x16x32_bf16 v[66:69], v[244:247], v[228:231], v[66:69]
	s_mov_b32 m0, s59
	v_lshl_add_u64 v[248:249], v[252:253], 0, s[88:89]
	s_barrier
; #define PG8_STAGE(bufoff, gbase, voff) do { _Pragma("unroll") for (int _i = 0; _i < 2; ++_i) \
;         __builtin_amdgcn_global_load_lds((const unsigned*)((const char*)(gbase) + (voff)[_i]), (LAS unsigned*)(lds + (bufoff) + ldsw + _i * 8192), 16, 0, 0); } while (0)
; #define PG8_LDA(dst, b, h) do { _Pragma("unroll") for (int m = 0; m < 4; ++m) _Pragma("unroll") for (int k = 0; k < 2; ++k) dst[m][k] = *(const LAS bf16x8*)(lds + PG8_SA(b, h) + aoff + m * 2048 + k * 1024); } while (0)
; #define PG8_MMA(ai, bj, At, Bt) do { __builtin_amdgcn_s_setprio(1); _Pragma("unroll") for (int m = 0; m < 4; ++m) _Pragma("unroll") for (int n = 0; n < 2; ++n) _Pragma("unroll") for (int k = 0; k < 2; ++k) \
;         acc[ai][bj][m][n] = __builtin_amdgcn_mfma_f32_16x16x32_bf16(Bt[n][k], At[m][k], acc[ai][bj][m][n], 0, 0, 0); __builtin_amdgcn_s_setprio(0); } while (0)
; #define PG8_WAIT_V(n) asm volatile("s_waitcnt vmcnt(" #n ")" ::: "memory")
; #define PG8_WAIT_L(n) asm volatile("s_waitcnt lgkmcnt(" #n ")" ::: "memory")
; #define PG8_BAR __builtin_amdgcn_s_barrier()
; #define PG8_SCHED __builtin_amdgcn_sched_barrier(0)
; template <class Epi>
; __device__ __forceinline__ void gemm_phase(LAS unsigned char* lds, const Gemm g, const StaticOrder& S, const Epi& E) {
;     ...
;             PG8_LDA(At, 1, 1); PG8_STAGE(PG8_SA(1, 0), a3, voffA);
;             PG8_BAR; PG8_WAIT_L(0); PG8_MMA(1, 0, At, B0); PG8_BAR; PG8_SCHED;
;             PG8_STAGE(PG8_SB(1, 1), b3 + hstepB, voffB);
;             PG8_WAIT_V(6); PG8_BAR; PG8_MMA(1, 1, At, B1); PG8_BAR;
;         }
;         E(acc, cur, wr, wc, fr, fq);
;         if (!has_next) break;
;     __device__ __forceinline__ void operator()(const f32x4 (&acc)[2][2][4][2], const Unit& u, int wr, int wc, int fr, int fq) const {
;     ...
;             if (wc == 0) {
; #pragma unroll
;                 for (int ai = 0; ai < 2; ++ai)
; #pragma unroll
;                     for (int m = 0; m < 4; ++m) *(f32x4*)(DT + (size_t)(rowb + ai * 128 + m * 16) * 16 + 4 * fq) = acc[ai][0][m][0];
	ds_read_b128 v[184:187], v151 offset:49152
	ds_read_b128 v[188:191], v151 offset:50176
	ds_read_b128 v[192:195], v151 offset:51200
	ds_read_b128 v[196:199], v151 offset:52224
	ds_read_b128 v[216:219], v151 offset:53248
	ds_read_b128 v[220:223], v151 offset:54272
	ds_read_b128 v[224:227], v151 offset:55296
	ds_read_b128 v[228:231], v151 offset:56320
	global_load_lds_dwordx4 v[248:249], off
	v_lshl_add_u64 v[212:213], v[212:213], 0, s[88:89]
	s_mov_b32 m0, s60
	s_nop 0
	global_load_lds_dwordx4 v[212:213], off
	s_barrier
	s_waitcnt lgkmcnt(0)
	s_waitcnt lgkmcnt(0)
	v_mfma_f32_16x16x32_bf16 v[62:65], v[130:133], v[184:187], v[62:65]
	v_mfma_f32_16x16x32_bf16 v[58:61], v[138:141], v[184:187], v[58:61]
	v_mfma_f32_16x16x32_bf16 v[46:49], v[130:133], v[192:195], v[46:49]
	v_mfma_f32_16x16x32_bf16 v[42:45], v[138:141], v[192:195], v[42:45]
	v_mfma_f32_16x16x32_bf16 v[30:33], v[130:133], v[216:219], v[30:33]
	v_mfma_f32_16x16x32_bf16 v[26:29], v[138:141], v[216:219], v[26:29]
	v_mfma_f32_16x16x32_bf16 v[14:17], v[130:133], v[224:227], v[14:17]
	v_mfma_f32_16x16x32_bf16 v[10:13], v[138:141], v[224:227], v[10:13]
	v_mfma_f32_16x16x32_bf16 v[62:65], v[134:137], v[188:191], v[62:65]
	v_mfma_f32_16x16x32_bf16 v[58:61], v[142:145], v[188:191], v[58:61]
	v_mfma_f32_16x16x32_bf16 v[46:49], v[134:137], v[196:199], v[46:49]
	v_mfma_f32_16x16x32_bf16 v[42:45], v[142:145], v[196:199], v[42:45]
	v_mfma_f32_16x16x32_bf16 v[30:33], v[134:137], v[220:223], v[30:33]
	v_mfma_f32_16x16x32_bf16 v[26:29], v[142:145], v[220:223], v[26:29]
	v_mfma_f32_16x16x32_bf16 v[14:17], v[134:137], v[228:231], v[14:17]
	v_mfma_f32_16x16x32_bf16 v[10:13], v[142:145], v[228:231], v[10:13]
	s_barrier
	s_add_u32 s36, s36, 0x40080
	s_addc_u32 s37, s37, 0
	s_add_i32 s6, s7, s15
	v_lshl_add_u64 v[130:131], s[36:37], 0, v[146:147]
	s_mov_b32 m0, s6
	s_nop 0
	global_load_lds_dwordx4 v[130:131], off
	v_lshl_add_u64 v[130:131], s[36:37], 0, v[148:149]
	s_add_i32 m0, s6, 0x2000
	s_nop 0
	global_load_lds_dwordx4 v[130:131], off
	s_waitcnt vmcnt(6)
	s_barrier
	v_mfma_f32_16x16x32_bf16 v[54:57], v[232:235], v[184:187], v[54:57]
	v_mfma_f32_16x16x32_bf16 v[50:53], v[240:243], v[184:187], v[50:53]
	v_mfma_f32_16x16x32_bf16 v[38:41], v[232:235], v[192:195], v[38:41]
	v_mfma_f32_16x16x32_bf16 v[34:37], v[240:243], v[192:195], v[34:37]
	v_mfma_f32_16x16x32_bf16 v[22:25], v[232:235], v[216:219], v[22:25]
	v_mfma_f32_16x16x32_bf16 v[18:21], v[240:243], v[216:219], v[18:21]
	v_mfma_f32_16x16x32_bf16 v[6:9], v[232:235], v[224:227], v[6:9]
	v_mfma_f32_16x16x32_bf16 v[2:5], v[240:243], v[224:227], v[2:5]
	v_mfma_f32_16x16x32_bf16 v[54:57], v[236:239], v[188:191], v[54:57]
	v_mfma_f32_16x16x32_bf16 v[50:53], v[244:247], v[188:191], v[50:53]
	v_mfma_f32_16x16x32_bf16 v[38:41], v[236:239], v[196:199], v[38:41]
	v_mfma_f32_16x16x32_bf16 v[34:37], v[244:247], v[196:199], v[34:37]
	v_mfma_f32_16x16x32_bf16 v[22:25], v[236:239], v[220:223], v[22:25]
	v_mfma_f32_16x16x32_bf16 v[18:21], v[244:247], v[220:223], v[18:21]
	v_mfma_f32_16x16x32_bf16 v[6:9], v[236:239], v[228:231], v[6:9]
	v_mfma_f32_16x16x32_bf16 v[2:5], v[244:247], v[228:231], v[2:5]
	s_add_i32 s31, s31, 2
	s_add_u32 s34, s34, 0x100
	s_addc_u32 s35, s35, 0
	s_add_u32 s25, s25, 0x100
	s_addc_u32 s27, s27, 0
	s_cmp_gt_u32 s31, 13
	s_barrier
	s_cbranch_scc0 .LBB0_901
	s_lshl_b32 s8, s30, 8
	s_add_i32 s8, s8, s58
	s_cmp_gt_i32 s28, 10
	s_cselect_b64 s[30:31], -1, 0
	s_cmp_lt_i32 s28, 11
	s_cselect_b64 s[10:11], -1, 0
	s_sub_i32 s6, s28, 17
	s_cmp_lt_u32 s6, 12
	s_cselect_b64 s[34:35], -1, 0
	s_or_b64 s[10:11], s[10:11], s[34:35]
	v_or_b32_e32 v184, s8, v150
	s_andn2_b64 vcc, exec, s[10:11]
	s_mov_b64 s[34:35], -1
	s_cbranch_vccz .LBB0_1025
	s_cmp_gt_u32 s28, 16
	s_cbranch_scc0 .LBB0_907
	s_andn2_b64 vcc, exec, s[0:1]
	s_cbranch_vccnz .LBB0_906
	v_or_b32_e32 v132, 16, v184
	v_ashrrev_i32_e32 v133, 31, v132
	v_lshlrev_b64 v[132:133], 6, v[132:133]
	v_lshl_add_u64 v[132:133], v[176:177], 0, v[132:133]
	global_store_dwordx4 v[132:133], v[110:113], off
	v_or_b32_e32 v132, 32, v184
	v_ashrrev_i32_e32 v133, 31, v132
	v_lshlrev_b64 v[132:133], 6, v[132:133]
	v_ashrrev_i32_e32 v185, 31, v184
	v_lshl_add_u64 v[132:133], v[176:177], 0, v[132:133]
	v_lshlrev_b64 v[130:131], 6, v[184:185]
	global_store_dwordx4 v[132:133], v[94:97], off
	v_or_b32_e32 v132, 48, v184
	v_lshl_add_u64 v[130:131], v[176:177], 0, v[130:131]
	v_ashrrev_i32_e32 v133, 31, v132
	global_store_dwordx4 v[130:131], v[126:129], off
	v_lshlrev_b64 v[132:133], 6, v[132:133]
	v_add_co_u32_e32 v130, vcc, 0x2000, v130
	v_lshl_add_u64 v[132:133], v[176:177], 0, v[132:133]
	s_nop 0
	v_addc_co_u32_e32 v131, vcc, 0, v131, vcc
	global_store_dwordx4 v[132:133], v[78:81], off
	global_store_dwordx4 v[130:131], v[62:65], off
	global_store_dwordx4 v[130:131], v[46:49], off offset:1024
	global_store_dwordx4 v[130:131], v[30:33], off offset:2048
	global_store_dwordx4 v[130:131], v[14:17], off offset:3072
